# GEMM loops: dropped the back-to-back s_setprio 0 / s_setprio 1 pairs between the two MFMA blocks of a super-phase
# baseline (speedup 1.0000x reference)
; #define PG8_STAGE(bufoff, gbase, voff) do { _Pragma("unroll") for (int _i = 0; _i < 2; ++_i) \
;         __builtin_amdgcn_global_load_lds((const unsigned*)((const char*)(gbase) + (voff)[_i]), (PG8_LAS unsigned*)(lds + (bufoff) + ldsw + _i * 8192), 16, 0, 0); } while (0)
; #define PG8_LDA(dst, b, h) do { _Pragma("unroll") for (int m = 0; m < 4; ++m) _Pragma("unroll") for (int k = 0; k < 2; ++k) dst[m][k] = *(const PG8_LAS bf16x8*)(lds + PG8_SA(b, h) + aoff + m * 2048 + k * 1024); } while (0)
; #define PG8_LDB(dst, b, h) do { _Pragma("unroll") for (int n = 0; n < 2; ++n) _Pragma("unroll") for (int k = 0; k < 2; ++k) dst[n][k] = *(const PG8_LAS bf16x8*)(lds + PG8_SB(b, h) + boff + n * 2048 + k * 1024); } while (0)
; #define PG8_MMA(ai, bj, At, Bt) do { __builtin_amdgcn_s_setprio(1); _Pragma("unroll") for (int m = 0; m < 4; ++m) _Pragma("unroll") for (int n = 0; n < 2; ++n) _Pragma("unroll") for (int k = 0; k < 2; ++k) \
;         acc[ai][bj][m][n] = __builtin_amdgcn_mfma_f32_16x16x32_bf16(Bt[n][k], At[m][k], acc[ai][bj][m][n], 0, 0, 0); __builtin_amdgcn_s_setprio(0); } while (0)
; #define PG8_WAIT_V(n) asm volatile("s_waitcnt vmcnt(" #n ")" ::: "memory")
; #define PG8_WAIT_L(n) asm volatile("s_waitcnt lgkmcnt(" #n ")" ::: "memory")
; #define PG8_BAR __builtin_amdgcn_s_barrier()
; #define PG8_SCHED __builtin_amdgcn_sched_barrier(0)
; template <class Epi, class Sched, bool ALIGN_EPI = false, bool SP2 = false>
; __device__ __forceinline__ void gemm_phase(PG8_LAS unsigned char* lds, const Gemm g, const Sched& S, const Epi& E) {
;     ...
;             const bool last = (t == nt - 2);
;             const char* a1 = cA + (size_t)(t + 1) * kstep;
;             const char* a2 = last ? nA : cA + (size_t)(t + 2) * kstep; const char* b2 = last ? nB : cB + (size_t)(t + 2) * kstep;
;             const char* a3 = a2 + kstep; const char* b3 = b2 + kstep;
;             if (last && has_next) S.a_ready(nxt);
;             if constexpr (SP2) {
;             PG8_LDB(B0, 0, 0); PG8_LDB(B1, 0, 1); PG8_SCHED; PG8_LDA(At, 0, 0); PG8_STAGE(PG8_SA(1, 1), a1 + hstep, voffA);
;             PG8_WAIT_V(8); PG8_WAIT_L(0); PG8_BAR; PG8_MMA(0, 0, At, B0); PG8_MMA(0, 1, At, B1); PG8_BAR; PG8_SCHED;
;             PG8_LDA(At, 0, 1); PG8_STAGE(PG8_SB(0, 0), b2, voffB); PG8_STAGE(PG8_SB(0, 1), b2 + hstep, voffB); PG8_STAGE(PG8_SA(0, 0), a2, voffA);
.LBB0_128:
	ds_read_b128 v[156:159], v148
	ds_read_b128 v[160:163], v148 offset:1024
	ds_read_b128 v[164:167], v148 offset:2048
	ds_read_b128 v[168:171], v148 offset:3072
	ds_read_b128 v[172:175], v149
	ds_read_b128 v[176:179], v149 offset:1024
	ds_read_b128 v[180:183], v149 offset:2048
	ds_read_b128 v[184:187], v149 offset:3072
	s_add_i32 s55, s28, 2
	s_add_u32 s58, s26, 0x80
	s_addc_u32 s29, s27, 0
	s_cmp_eq_u32 s45, s28
	s_cselect_b32 s28, s8, s58
	s_cselect_b32 s29, s9, s29
	s_cselect_b32 s59, s25, s1
	s_cselect_b32 s58, s24, s0
	v_lshl_add_u64 v[220:221], s[26:27], 0, v[136:137]
	s_add_i32 m0, s37, 0xc000
	ds_read_b128 v[188:191], v150
	ds_read_b128 v[192:195], v150 offset:1024
	ds_read_b128 v[196:199], v150 offset:2048
	ds_read_b128 v[200:203], v150 offset:3072
	ds_read_b128 v[204:207], v150 offset:4096
	ds_read_b128 v[208:211], v150 offset:5120
	ds_read_b128 v[212:215], v150 offset:6144
	ds_read_b128 v[216:219], v150 offset:7168
	global_load_lds_dwordx4 v[220:221], off
	v_lshl_add_u64 v[220:221], s[26:27], 0, v[138:139]
	s_add_i32 m0, s37, 0xe000
	s_nop 0
	global_load_lds_dwordx4 v[220:221], off
	s_waitcnt vmcnt(8)
	s_waitcnt lgkmcnt(0)
	s_barrier
	s_setprio 1
	s_waitcnt lgkmcnt(0)
	v_mfma_f32_16x16x32_bf16 v[124:127], v[156:159], v[188:191], v[124:127]
	v_mfma_f32_16x16x32_bf16 v[116:119], v[164:167], v[188:191], v[116:119]
	v_mfma_f32_16x16x32_bf16 v[108:111], v[156:159], v[196:199], v[108:111]
	v_mfma_f32_16x16x32_bf16 v[100:103], v[164:167], v[196:199], v[100:103]
	v_mfma_f32_16x16x32_bf16 v[92:95], v[156:159], v[204:207], v[92:95]
	v_mfma_f32_16x16x32_bf16 v[84:87], v[164:167], v[204:207], v[84:87]
	v_mfma_f32_16x16x32_bf16 v[76:79], v[156:159], v[212:215], v[76:79]
	v_mfma_f32_16x16x32_bf16 v[68:71], v[164:167], v[212:215], v[68:71]
	v_mfma_f32_16x16x32_bf16 v[124:127], v[160:163], v[192:195], v[124:127]
	v_mfma_f32_16x16x32_bf16 v[116:119], v[168:171], v[192:195], v[116:119]
	v_mfma_f32_16x16x32_bf16 v[108:111], v[160:163], v[200:203], v[108:111]
	v_mfma_f32_16x16x32_bf16 v[100:103], v[168:171], v[200:203], v[100:103]
	v_mfma_f32_16x16x32_bf16 v[92:95], v[160:163], v[208:211], v[92:95]
	v_mfma_f32_16x16x32_bf16 v[84:87], v[168:171], v[208:211], v[84:87]
	v_mfma_f32_16x16x32_bf16 v[76:79], v[160:163], v[216:219], v[76:79]
	v_mfma_f32_16x16x32_bf16 v[68:71], v[168:171], v[216:219], v[68:71]
	v_mfma_f32_16x16x32_bf16 v[120:123], v[172:175], v[188:191], v[120:123]
	v_mfma_f32_16x16x32_bf16 v[112:115], v[180:183], v[188:191], v[112:115]
	v_mfma_f32_16x16x32_bf16 v[104:107], v[172:175], v[196:199], v[104:107]
	v_mfma_f32_16x16x32_bf16 v[96:99], v[180:183], v[196:199], v[96:99]
	v_mfma_f32_16x16x32_bf16 v[88:91], v[172:175], v[204:207], v[88:91]
	v_mfma_f32_16x16x32_bf16 v[80:83], v[180:183], v[204:207], v[80:83]
	v_mfma_f32_16x16x32_bf16 v[72:75], v[172:175], v[212:215], v[72:75]
	v_mfma_f32_16x16x32_bf16 v[64:67], v[180:183], v[212:215], v[64:67]
	v_mfma_f32_16x16x32_bf16 v[120:123], v[176:179], v[192:195], v[120:123]
	v_mfma_f32_16x16x32_bf16 v[112:115], v[184:187], v[192:195], v[112:115]
	v_mfma_f32_16x16x32_bf16 v[104:107], v[176:179], v[200:203], v[104:107]
	v_mfma_f32_16x16x32_bf16 v[96:99], v[184:187], v[200:203], v[96:99]
	v_mfma_f32_16x16x32_bf16 v[88:91], v[176:179], v[208:211], v[88:91]
	v_mfma_f32_16x16x32_bf16 v[80:83], v[184:187], v[208:211], v[80:83]
	v_mfma_f32_16x16x32_bf16 v[72:75], v[176:179], v[216:219], v[72:75]
	v_mfma_f32_16x16x32_bf16 v[64:67], v[184:187], v[216:219], v[64:67]
	s_setprio 0
	s_barrier
	s_add_i32 s60, s48, s36
	v_lshl_add_u64 v[220:221], s[58:59], 0, v[130:131]
	s_mov_b32 m0, s60
	ds_read_b128 v[188:191], v150 offset:16384
	ds_read_b128 v[192:195], v150 offset:17408
	ds_read_b128 v[196:199], v150 offset:18432
	ds_read_b128 v[200:203], v150 offset:19456
	ds_read_b128 v[204:207], v150 offset:20480
	ds_read_b128 v[208:211], v150 offset:21504
	ds_read_b128 v[212:215], v150 offset:22528
	ds_read_b128 v[216:219], v150 offset:23552
	global_load_lds_dwordx4 v[220:221], off
	s_add_i32 m0, s60, 0x2000
	v_lshl_add_u64 v[222:223], s[58:59], 0, v[134:135]
	s_add_u32 s58, s58, s10
	s_addc_u32 s59, s59, s11
	s_add_i32 s60, s49, s36
	global_load_lds_dwordx4 v[222:223], off
	v_lshl_add_u64 v[224:225], s[58:59], 0, v[130:131]
	s_mov_b32 m0, s60
	v_lshl_add_u64 v[226:227], s[58:59], 0, v[134:135]
	global_load_lds_dwordx4 v[224:225], off
	s_add_i32 m0, s60, 0x2000
	v_lshl_add_u64 v[228:229], s[28:29], 0, v[128:129]
	global_load_lds_dwordx4 v[226:227], off
	s_mov_b32 m0, s37
	v_lshl_add_u64 v[230:231], s[28:29], 0, v[132:133]
	global_load_lds_dwordx4 v[228:229], off
	s_mov_b32 m0, s38
	s_nop 0
	global_load_lds_dwordx4 v[230:231], off
	s_waitcnt vmcnt(8)
	s_waitcnt lgkmcnt(0)
	s_barrier
; #define PG8_STAGE(bufoff, gbase, voff) do { _Pragma("unroll") for (int _i = 0; _i < 2; ++_i) \
;         __builtin_amdgcn_global_load_lds((const unsigned*)((const char*)(gbase) + (voff)[_i]), (PG8_LAS unsigned*)(lds + (bufoff) + ldsw + _i * 8192), 16, 0, 0); } while (0)
; #define PG8_LDA(dst, b, h) do { _Pragma("unroll") for (int m = 0; m < 4; ++m) _Pragma("unroll") for (int k = 0; k < 2; ++k) dst[m][k] = *(const PG8_LAS bf16x8*)(lds + PG8_SA(b, h) + aoff + m * 2048 + k * 1024); } while (0)
; #define PG8_LDB(dst, b, h) do { _Pragma("unroll") for (int n = 0; n < 2; ++n) _Pragma("unroll") for (int k = 0; k < 2; ++k) dst[n][k] = *(const PG8_LAS bf16x8*)(lds + PG8_SB(b, h) + boff + n * 2048 + k * 1024); } while (0)
; #define PG8_MMA(ai, bj, At, Bt) do { __builtin_amdgcn_s_setprio(1); _Pragma("unroll") for (int m = 0; m < 4; ++m) _Pragma("unroll") for (int n = 0; n < 2; ++n) _Pragma("unroll") for (int k = 0; k < 2; ++k) \
;         acc[ai][bj][m][n] = __builtin_amdgcn_mfma_f32_16x16x32_bf16(Bt[n][k], At[m][k], acc[ai][bj][m][n], 0, 0, 0); __builtin_amdgcn_s_setprio(0); } while (0)
; #define PG8_WAIT_V(n) asm volatile("s_waitcnt vmcnt(" #n ")" ::: "memory")
; #define PG8_WAIT_L(n) asm volatile("s_waitcnt lgkmcnt(" #n ")" ::: "memory")
; #define PG8_BAR __builtin_amdgcn_s_barrier()
; #define PG8_SCHED __builtin_amdgcn_sched_barrier(0)
; template <class Epi, class Sched, bool ALIGN_EPI = false, bool SP2 = false>
; __device__ __forceinline__ void gemm_phase(PG8_LAS unsigned char* lds, const Gemm g, const Sched& S, const Epi& E) {
;     ...
;             PG8_WAIT_V(8); PG8_WAIT_L(0); PG8_BAR; PG8_MMA(1, 0, At, B0); PG8_MMA(1, 1, At, B1); PG8_BAR; PG8_SCHED;
;             PG8_LDB(B0, 1, 0); PG8_LDB(B1, 1, 1); PG8_SCHED; PG8_LDA(At, 1, 0); PG8_STAGE(PG8_SA(0, 1), a2 + hstep, voffA);
;             PG8_WAIT_V(8); PG8_WAIT_L(0); PG8_BAR; PG8_MMA(0, 0, At, B0); PG8_MMA(0, 1, At, B1); PG8_BAR; PG8_SCHED;
	s_setprio 1
	s_waitcnt lgkmcnt(0)
	v_mfma_f32_16x16x32_bf16 v[60:63], v[156:159], v[188:191], v[60:63]
	v_mfma_f32_16x16x32_bf16 v[52:55], v[164:167], v[188:191], v[52:55]
	v_mfma_f32_16x16x32_bf16 v[44:47], v[156:159], v[196:199], v[44:47]
	v_mfma_f32_16x16x32_bf16 v[36:39], v[164:167], v[196:199], v[36:39]
	v_mfma_f32_16x16x32_bf16 v[28:31], v[156:159], v[204:207], v[28:31]
	v_mfma_f32_16x16x32_bf16 v[20:23], v[164:167], v[204:207], v[20:23]
	v_mfma_f32_16x16x32_bf16 v[12:15], v[156:159], v[212:215], v[12:15]
	v_mfma_f32_16x16x32_bf16 v[4:7], v[164:167], v[212:215], v[4:7]
	v_mfma_f32_16x16x32_bf16 v[60:63], v[160:163], v[192:195], v[60:63]
	v_mfma_f32_16x16x32_bf16 v[52:55], v[168:171], v[192:195], v[52:55]
	v_mfma_f32_16x16x32_bf16 v[44:47], v[160:163], v[200:203], v[44:47]
	v_mfma_f32_16x16x32_bf16 v[36:39], v[168:171], v[200:203], v[36:39]
	v_mfma_f32_16x16x32_bf16 v[28:31], v[160:163], v[208:211], v[28:31]
	v_mfma_f32_16x16x32_bf16 v[20:23], v[168:171], v[208:211], v[20:23]
	v_mfma_f32_16x16x32_bf16 v[12:15], v[160:163], v[216:219], v[12:15]
	v_mfma_f32_16x16x32_bf16 v[4:7], v[168:171], v[216:219], v[4:7]
	v_mfma_f32_16x16x32_bf16 v[56:59], v[172:175], v[188:191], v[56:59]
	v_mfma_f32_16x16x32_bf16 v[48:51], v[180:183], v[188:191], v[48:51]
	v_mfma_f32_16x16x32_bf16 v[40:43], v[172:175], v[196:199], v[40:43]
	v_mfma_f32_16x16x32_bf16 v[32:35], v[180:183], v[196:199], v[32:35]
	v_mfma_f32_16x16x32_bf16 v[24:27], v[172:175], v[204:207], v[24:27]
	v_mfma_f32_16x16x32_bf16 v[16:19], v[180:183], v[204:207], v[16:19]
	v_mfma_f32_16x16x32_bf16 v[8:11], v[172:175], v[212:215], v[8:11]
	v_mfma_f32_16x16x32_bf16 v[0:3], v[180:183], v[212:215], v[0:3]
	v_mfma_f32_16x16x32_bf16 v[56:59], v[176:179], v[192:195], v[56:59]
	v_mfma_f32_16x16x32_bf16 v[48:51], v[184:187], v[192:195], v[48:51]
	v_mfma_f32_16x16x32_bf16 v[40:43], v[176:179], v[200:203], v[40:43]
	v_mfma_f32_16x16x32_bf16 v[32:35], v[184:187], v[200:203], v[32:35]
	v_mfma_f32_16x16x32_bf16 v[24:27], v[176:179], v[208:211], v[24:27]
	v_mfma_f32_16x16x32_bf16 v[16:19], v[184:187], v[208:211], v[16:19]
	v_mfma_f32_16x16x32_bf16 v[8:11], v[176:179], v[216:219], v[8:11]
	v_mfma_f32_16x16x32_bf16 v[0:3], v[184:187], v[216:219], v[0:3]
	s_setprio 0
	s_barrier
	s_add_i32 s58, 0, 0x18000
	v_add_u32_e32 v151, s58, v146
	s_add_i32 s59, 0, 0x1c000
	ds_read_b128 v[156:159], v151
	ds_read_b128 v[160:163], v151 offset:1024
	ds_read_b128 v[164:167], v151 offset:2048
	ds_read_b128 v[168:171], v151 offset:3072
	v_add_u32_e32 v151, s59, v146
	ds_read_b128 v[172:175], v151
	ds_read_b128 v[176:179], v151 offset:1024
	ds_read_b128 v[180:183], v151 offset:2048
	ds_read_b128 v[184:187], v151 offset:3072
	s_add_u32 s28, s28, s10
	s_addc_u32 s29, s29, s11
	s_mov_b32 m0, s39
	v_lshl_add_u64 v[232:233], s[28:29], 0, v[128:129]
	ds_read_b128 v[188:191], v150 offset:32768
	ds_read_b128 v[192:195], v150 offset:33792
	ds_read_b128 v[196:199], v150 offset:34816
	ds_read_b128 v[200:203], v150 offset:35840
	ds_read_b128 v[204:207], v150 offset:36864
	ds_read_b128 v[208:211], v150 offset:37888
	ds_read_b128 v[212:215], v150 offset:38912
	ds_read_b128 v[216:219], v150 offset:39936
	global_load_lds_dwordx4 v[232:233], off
	v_lshl_add_u64 v[232:233], s[28:29], 0, v[132:133]
	s_mov_b32 m0, s40
	s_nop 0
	global_load_lds_dwordx4 v[232:233], off
	s_waitcnt vmcnt(8)
	s_waitcnt lgkmcnt(0)
	s_barrier
	s_setprio 1
	s_waitcnt lgkmcnt(0)
	v_mfma_f32_16x16x32_bf16 v[124:127], v[156:159], v[188:191], v[124:127]
	v_mfma_f32_16x16x32_bf16 v[116:119], v[164:167], v[188:191], v[116:119]
	v_mfma_f32_16x16x32_bf16 v[108:111], v[156:159], v[196:199], v[108:111]
	v_mfma_f32_16x16x32_bf16 v[100:103], v[164:167], v[196:199], v[100:103]
	v_mfma_f32_16x16x32_bf16 v[92:95], v[156:159], v[204:207], v[92:95]
	v_mfma_f32_16x16x32_bf16 v[84:87], v[164:167], v[204:207], v[84:87]
	v_mfma_f32_16x16x32_bf16 v[76:79], v[156:159], v[212:215], v[76:79]
	v_mfma_f32_16x16x32_bf16 v[68:71], v[164:167], v[212:215], v[68:71]
	v_mfma_f32_16x16x32_bf16 v[124:127], v[160:163], v[192:195], v[124:127]
	v_mfma_f32_16x16x32_bf16 v[116:119], v[168:171], v[192:195], v[116:119]
	v_mfma_f32_16x16x32_bf16 v[108:111], v[160:163], v[200:203], v[108:111]
	v_mfma_f32_16x16x32_bf16 v[100:103], v[168:171], v[200:203], v[100:103]
	v_mfma_f32_16x16x32_bf16 v[92:95], v[160:163], v[208:211], v[92:95]
	v_mfma_f32_16x16x32_bf16 v[84:87], v[168:171], v[208:211], v[84:87]
	v_mfma_f32_16x16x32_bf16 v[76:79], v[160:163], v[216:219], v[76:79]
	v_mfma_f32_16x16x32_bf16 v[68:71], v[168:171], v[216:219], v[68:71]
	v_mfma_f32_16x16x32_bf16 v[120:123], v[172:175], v[188:191], v[120:123]
	v_mfma_f32_16x16x32_bf16 v[112:115], v[180:183], v[188:191], v[112:115]
	v_mfma_f32_16x16x32_bf16 v[104:107], v[172:175], v[196:199], v[104:107]
	v_mfma_f32_16x16x32_bf16 v[96:99], v[180:183], v[196:199], v[96:99]
	v_mfma_f32_16x16x32_bf16 v[88:91], v[172:175], v[204:207], v[88:91]
	v_mfma_f32_16x16x32_bf16 v[80:83], v[180:183], v[204:207], v[80:83]
	v_mfma_f32_16x16x32_bf16 v[72:75], v[172:175], v[212:215], v[72:75]
	v_mfma_f32_16x16x32_bf16 v[64:67], v[180:183], v[212:215], v[64:67]
	v_mfma_f32_16x16x32_bf16 v[120:123], v[176:179], v[192:195], v[120:123]
	v_mfma_f32_16x16x32_bf16 v[112:115], v[184:187], v[192:195], v[112:115]
	v_mfma_f32_16x16x32_bf16 v[104:107], v[176:179], v[200:203], v[104:107]
	v_mfma_f32_16x16x32_bf16 v[96:99], v[184:187], v[200:203], v[96:99]
	v_mfma_f32_16x16x32_bf16 v[88:91], v[176:179], v[208:211], v[88:91]
	v_mfma_f32_16x16x32_bf16 v[80:83], v[184:187], v[208:211], v[80:83]
	v_mfma_f32_16x16x32_bf16 v[72:75], v[176:179], v[216:219], v[72:75]
	v_mfma_f32_16x16x32_bf16 v[64:67], v[184:187], v[216:219], v[64:67]
	s_setprio 0
	s_barrier
; #define PG8_STAGE(bufoff, gbase, voff) do { _Pragma("unroll") for (int _i = 0; _i < 2; ++_i) \
;         __builtin_amdgcn_global_load_lds((const unsigned*)((const char*)(gbase) + (voff)[_i]), (PG8_LAS unsigned*)(lds + (bufoff) + ldsw + _i * 8192), 16, 0, 0); } while (0)
; #define PG8_LDA(dst, b, h) do { _Pragma("unroll") for (int m = 0; m < 4; ++m) _Pragma("unroll") for (int k = 0; k < 2; ++k) dst[m][k] = *(const PG8_LAS bf16x8*)(lds + PG8_SA(b, h) + aoff + m * 2048 + k * 1024); } while (0)
; #define PG8_MMA(ai, bj, At, Bt) do { __builtin_amdgcn_s_setprio(1); _Pragma("unroll") for (int m = 0; m < 4; ++m) _Pragma("unroll") for (int n = 0; n < 2; ++n) _Pragma("unroll") for (int k = 0; k < 2; ++k) \
;         acc[ai][bj][m][n] = __builtin_amdgcn_mfma_f32_16x16x32_bf16(Bt[n][k], At[m][k], acc[ai][bj][m][n], 0, 0, 0); __builtin_amdgcn_s_setprio(0); } while (0)
; #define PG8_WAIT_V(n) asm volatile("s_waitcnt vmcnt(" #n ")" ::: "memory")
; #define PG8_WAIT_L(n) asm volatile("s_waitcnt lgkmcnt(" #n ")" ::: "memory")
; #define PG8_BAR __builtin_amdgcn_s_barrier()
; #define PG8_SCHED __builtin_amdgcn_sched_barrier(0)
; template <class Epi, class Sched, bool ALIGN_EPI = false, bool SP2 = false>
; __device__ __forceinline__ void gemm_phase(PG8_LAS unsigned char* lds, const Gemm g, const Sched& S, const Epi& E) {
;     ...
;         for (int t = 0; t < nt; t += 2) {
;     ...
;             PG8_LDA(At, 1, 1); PG8_STAGE(PG8_SB(1, 0), b3, voffB); PG8_STAGE(PG8_SB(1, 1), b3 + hstep, voffB); PG8_STAGE(PG8_SA(1, 0), a3, voffA);
;             PG8_WAIT_V(8); PG8_WAIT_L(0); PG8_BAR; PG8_MMA(1, 0, At, B0); PG8_MMA(1, 1, At, B1); PG8_BAR; PG8_SCHED;
	s_add_i32 s28, s58, s36
	v_lshl_add_u64 v[220:221], v[220:221], 0, s[18:19]
	s_mov_b32 m0, s28
	ds_read_b128 v[188:191], v150 offset:49152
	ds_read_b128 v[192:195], v150 offset:50176
	ds_read_b128 v[196:199], v150 offset:51200
	ds_read_b128 v[200:203], v150 offset:52224
	ds_read_b128 v[204:207], v150 offset:53248
	ds_read_b128 v[208:211], v150 offset:54272
	ds_read_b128 v[212:215], v150 offset:55296
	ds_read_b128 v[216:219], v150 offset:56320
	global_load_lds_dwordx4 v[220:221], off
	v_lshl_add_u64 v[220:221], v[222:223], 0, s[18:19]
	s_add_i32 m0, s28, 0x2000
	s_add_i32 s28, s59, s36
	global_load_lds_dwordx4 v[220:221], off
	v_lshl_add_u64 v[220:221], v[224:225], 0, s[18:19]
	s_mov_b32 m0, s28
	s_nop 0
	global_load_lds_dwordx4 v[220:221], off
	v_lshl_add_u64 v[220:221], v[226:227], 0, s[18:19]
	s_add_i32 m0, s28, 0x2000
	s_nop 0
	global_load_lds_dwordx4 v[220:221], off
	v_lshl_add_u64 v[220:221], v[228:229], 0, s[18:19]
	s_mov_b32 m0, s42
	s_nop 0
	global_load_lds_dwordx4 v[220:221], off
	v_lshl_add_u64 v[220:221], v[230:231], 0, s[18:19]
	s_mov_b32 m0, s43
	s_nop 0
	global_load_lds_dwordx4 v[220:221], off
	s_waitcnt vmcnt(8)
	s_waitcnt lgkmcnt(0)
	s_barrier
	s_setprio 1
	s_waitcnt lgkmcnt(0)
	v_mfma_f32_16x16x32_bf16 v[60:63], v[156:159], v[188:191], v[60:63]
	v_mfma_f32_16x16x32_bf16 v[52:55], v[164:167], v[188:191], v[52:55]
	v_mfma_f32_16x16x32_bf16 v[44:47], v[156:159], v[196:199], v[44:47]
	v_mfma_f32_16x16x32_bf16 v[36:39], v[164:167], v[196:199], v[36:39]
	v_mfma_f32_16x16x32_bf16 v[28:31], v[156:159], v[204:207], v[28:31]
	v_mfma_f32_16x16x32_bf16 v[20:23], v[164:167], v[204:207], v[20:23]
	v_mfma_f32_16x16x32_bf16 v[12:15], v[156:159], v[212:215], v[12:15]
	v_mfma_f32_16x16x32_bf16 v[4:7], v[164:167], v[212:215], v[4:7]
	v_mfma_f32_16x16x32_bf16 v[60:63], v[160:163], v[192:195], v[60:63]
	v_mfma_f32_16x16x32_bf16 v[52:55], v[168:171], v[192:195], v[52:55]
	v_mfma_f32_16x16x32_bf16 v[44:47], v[160:163], v[200:203], v[44:47]
	v_mfma_f32_16x16x32_bf16 v[36:39], v[168:171], v[200:203], v[36:39]
	v_mfma_f32_16x16x32_bf16 v[28:31], v[160:163], v[208:211], v[28:31]
	v_mfma_f32_16x16x32_bf16 v[20:23], v[168:171], v[208:211], v[20:23]
	v_mfma_f32_16x16x32_bf16 v[12:15], v[160:163], v[216:219], v[12:15]
	v_mfma_f32_16x16x32_bf16 v[4:7], v[168:171], v[216:219], v[4:7]
	v_mfma_f32_16x16x32_bf16 v[56:59], v[172:175], v[188:191], v[56:59]
	v_mfma_f32_16x16x32_bf16 v[48:51], v[180:183], v[188:191], v[48:51]
	v_mfma_f32_16x16x32_bf16 v[40:43], v[172:175], v[196:199], v[40:43]
	v_mfma_f32_16x16x32_bf16 v[32:35], v[180:183], v[196:199], v[32:35]
	v_mfma_f32_16x16x32_bf16 v[24:27], v[172:175], v[204:207], v[24:27]
	v_mfma_f32_16x16x32_bf16 v[16:19], v[180:183], v[204:207], v[16:19]
	v_mfma_f32_16x16x32_bf16 v[8:11], v[172:175], v[212:215], v[8:11]
	v_mfma_f32_16x16x32_bf16 v[0:3], v[180:183], v[212:215], v[0:3]
	v_mfma_f32_16x16x32_bf16 v[56:59], v[176:179], v[192:195], v[56:59]
	v_mfma_f32_16x16x32_bf16 v[48:51], v[184:187], v[192:195], v[48:51]
	v_mfma_f32_16x16x32_bf16 v[40:43], v[176:179], v[200:203], v[40:43]
	v_mfma_f32_16x16x32_bf16 v[32:35], v[184:187], v[200:203], v[32:35]
	v_mfma_f32_16x16x32_bf16 v[24:27], v[176:179], v[208:211], v[24:27]
	v_mfma_f32_16x16x32_bf16 v[16:19], v[184:187], v[208:211], v[16:19]
	v_mfma_f32_16x16x32_bf16 v[8:11], v[176:179], v[216:219], v[8:11]
	v_mfma_f32_16x16x32_bf16 v[0:3], v[184:187], v[216:219], v[0:3]
	s_setprio 0
	s_barrier
	s_add_u32 s26, s26, 0x100
	s_addc_u32 s27, s27, 0
	s_add_u32 s0, s0, 0x100
	s_addc_u32 s1, s1, 0
	s_cmp_ge_i32 s55, s44
	s_mov_b32 s28, s55
	s_cbranch_scc0 .LBB0_128

; #define PG8_STAGE(bufoff, gbase, voff) do { _Pragma("unroll") for (int _i = 0; _i < 2; ++_i) \
;         __builtin_amdgcn_global_load_lds((const unsigned*)((const char*)(gbase) + (voff)[_i]), (PG8_LAS unsigned*)(lds + (bufoff) + ldsw + _i * 8192), 16, 0, 0); } while (0)
; #define PG8_LDA(dst, b, h) do { _Pragma("unroll") for (int m = 0; m < 4; ++m) _Pragma("unroll") for (int k = 0; k < 2; ++k) dst[m][k] = *(const PG8_LAS bf16x8*)(lds + PG8_SA(b, h) + aoff + m * 2048 + k * 1024); } while (0)
; #define PG8_LDB(dst, b, h) do { _Pragma("unroll") for (int n = 0; n < 2; ++n) _Pragma("unroll") for (int k = 0; k < 2; ++k) dst[n][k] = *(const PG8_LAS bf16x8*)(lds + PG8_SB(b, h) + boff + n * 2048 + k * 1024); } while (0)
; #define PG8_MMA(ai, bj, At, Bt) do { __builtin_amdgcn_s_setprio(1); _Pragma("unroll") for (int m = 0; m < 4; ++m) _Pragma("unroll") for (int n = 0; n < 2; ++n) _Pragma("unroll") for (int k = 0; k < 2; ++k) \
;         acc[ai][bj][m][n] = __builtin_amdgcn_mfma_f32_16x16x32_bf16(Bt[n][k], At[m][k], acc[ai][bj][m][n], 0, 0, 0); __builtin_amdgcn_s_setprio(0); } while (0)
; #define PG8_WAIT_V(n) asm volatile("s_waitcnt vmcnt(" #n ")" ::: "memory")
; #define PG8_WAIT_L(n) asm volatile("s_waitcnt lgkmcnt(" #n ")" ::: "memory")
; #define PG8_BAR __builtin_amdgcn_s_barrier()
; #define PG8_SCHED __builtin_amdgcn_sched_barrier(0)
; template <class Epi, class Sched, bool ALIGN_EPI = false, bool SP2 = false>
; __device__ __forceinline__ void gemm_phase(PG8_LAS unsigned char* lds, const Gemm g, const Sched& S, const Epi& E) {
;     ...
;             const bool last = (t == nt - 2);
;             const char* a1 = cA + (size_t)(t + 1) * kstep;
;             const char* a2 = last ? nA : cA + (size_t)(t + 2) * kstep; const char* b2 = last ? nB : cB + (size_t)(t + 2) * kstep;
;             const char* a3 = a2 + kstep; const char* b3 = b2 + kstep;
;             if (last && has_next) S.a_ready(nxt);
;             if constexpr (SP2) {
;             PG8_LDB(B0, 0, 0); PG8_LDB(B1, 0, 1); PG8_SCHED; PG8_LDA(At, 0, 0); PG8_STAGE(PG8_SA(1, 1), a1 + hstep, voffA);
;             PG8_WAIT_V(8); PG8_WAIT_L(0); PG8_BAR; PG8_MMA(0, 0, At, B0); PG8_MMA(0, 1, At, B1); PG8_BAR; PG8_SCHED;
;             PG8_LDA(At, 0, 1); PG8_STAGE(PG8_SB(0, 0), b2, voffB); PG8_STAGE(PG8_SB(0, 1), b2 + hstep, voffB); PG8_STAGE(PG8_SA(0, 0), a2, voffA);
.LBB0_274:
	v_add_u32_e32 v1, s68, v149
	ds_read_b128 v[158:161], v1
	ds_read_b128 v[162:165], v1 offset:1024
	ds_read_b128 v[166:169], v1 offset:2048
	ds_read_b128 v[170:173], v1 offset:3072
	v_add_u32_e32 v1, s69, v149
	ds_read_b128 v[174:177], v1
	ds_read_b128 v[178:181], v1 offset:1024
	ds_read_b128 v[182:185], v1 offset:2048
	ds_read_b128 v[186:189], v1 offset:3072
	s_add_i32 s74, s46, 2
	s_add_u32 s75, s44, 0x80
	s_addc_u32 s47, s45, 0
	s_cmp_eq_u32 s67, s46
	s_cselect_b32 s46, s10, s75
	s_cselect_b32 s47, s11, s47
	s_cselect_b32 s77, s43, s1
	s_cselect_b32 s76, s42, s0
	v_lshl_add_u64 v[2:3], s[44:45], 0, v[140:141]
	s_add_i32 m0, s59, 0xc000
	ds_read_b128 v[190:193], v150
	ds_read_b128 v[194:197], v150 offset:1024
	ds_read_b128 v[198:201], v150 offset:2048
	ds_read_b128 v[202:205], v150 offset:3072
	ds_read_b128 v[206:209], v150 offset:4096
	ds_read_b128 v[210:213], v150 offset:5120
	ds_read_b128 v[214:217], v150 offset:6144
	ds_read_b128 v[218:221], v150 offset:7168
	global_load_lds_dwordx4 v[2:3], off
	v_lshl_add_u64 v[2:3], s[44:45], 0, v[142:143]
	s_add_i32 m0, s59, 0xe000
	s_nop 0
	global_load_lds_dwordx4 v[2:3], off
	s_waitcnt vmcnt(8)
	s_waitcnt lgkmcnt(0)
	s_barrier
	s_setprio 1
	s_waitcnt lgkmcnt(0)
	v_mfma_f32_16x16x32_bf16 v[60:63], v[158:161], v[190:193], v[60:63]
	v_mfma_f32_16x16x32_bf16 v[56:59], v[166:169], v[190:193], v[56:59]
	v_mfma_f32_16x16x32_bf16 v[76:79], v[158:161], v[198:201], v[76:79]
	v_mfma_f32_16x16x32_bf16 v[72:75], v[166:169], v[198:201], v[72:75]
	v_mfma_f32_16x16x32_bf16 v[84:87], v[158:161], v[206:209], v[84:87]
	v_mfma_f32_16x16x32_bf16 v[80:83], v[166:169], v[206:209], v[80:83]
	v_mfma_f32_16x16x32_bf16 v[92:95], v[158:161], v[214:217], v[92:95]
	v_mfma_f32_16x16x32_bf16 v[88:91], v[166:169], v[214:217], v[88:91]
	v_mfma_f32_16x16x32_bf16 v[60:63], v[162:165], v[194:197], v[60:63]
	v_mfma_f32_16x16x32_bf16 v[56:59], v[170:173], v[194:197], v[56:59]
	v_mfma_f32_16x16x32_bf16 v[76:79], v[162:165], v[202:205], v[76:79]
	v_mfma_f32_16x16x32_bf16 v[72:75], v[170:173], v[202:205], v[72:75]
	v_mfma_f32_16x16x32_bf16 v[84:87], v[162:165], v[210:213], v[84:87]
	v_mfma_f32_16x16x32_bf16 v[80:83], v[170:173], v[210:213], v[80:83]
	v_mfma_f32_16x16x32_bf16 v[92:95], v[162:165], v[218:221], v[92:95]
	v_mfma_f32_16x16x32_bf16 v[88:91], v[170:173], v[218:221], v[88:91]
	v_mfma_f32_16x16x32_bf16 v[2:5], v[174:177], v[190:193], v[4:7]
	v_mfma_f32_16x16x32_bf16 v[128:131], v[182:185], v[190:193], v[128:131]
	v_mfma_f32_16x16x32_bf16 v[12:15], v[174:177], v[198:201], v[12:15]
	v_mfma_f32_16x16x32_bf16 v[6:9], v[182:185], v[198:201], v[8:11]
	v_mfma_f32_16x16x32_bf16 v[20:23], v[174:177], v[206:209], v[20:23]
	v_mfma_f32_16x16x32_bf16 v[16:19], v[182:185], v[206:209], v[16:19]
	v_mfma_f32_16x16x32_bf16 v[28:31], v[174:177], v[214:217], v[28:31]
	v_mfma_f32_16x16x32_bf16 v[24:27], v[182:185], v[214:217], v[24:27]
	v_mfma_f32_16x16x32_bf16 v[2:5], v[178:181], v[194:197], v[2:5]
	v_mfma_f32_16x16x32_bf16 v[128:131], v[186:189], v[194:197], v[128:131]
	v_mfma_f32_16x16x32_bf16 v[12:15], v[178:181], v[202:205], v[12:15]
	v_mfma_f32_16x16x32_bf16 v[8:11], v[186:189], v[202:205], v[6:9]
	v_mfma_f32_16x16x32_bf16 v[20:23], v[178:181], v[210:213], v[20:23]
	v_mfma_f32_16x16x32_bf16 v[16:19], v[186:189], v[210:213], v[16:19]
	v_mfma_f32_16x16x32_bf16 v[28:31], v[178:181], v[218:221], v[28:31]
	v_mfma_f32_16x16x32_bf16 v[24:27], v[186:189], v[218:221], v[24:27]
	s_setprio 0
	s_barrier
	s_add_i32 s75, s68, s58
	v_lshl_add_u64 v[222:223], s[76:77], 0, v[134:135]
	s_mov_b32 m0, s75
	ds_read_b128 v[190:193], v150 offset:16384
	ds_read_b128 v[194:197], v150 offset:17408
	ds_read_b128 v[198:201], v150 offset:18432
	ds_read_b128 v[202:205], v150 offset:19456
	ds_read_b128 v[206:209], v150 offset:20480
	ds_read_b128 v[210:213], v150 offset:21504
	ds_read_b128 v[214:217], v150 offset:22528
	ds_read_b128 v[218:221], v150 offset:23552
	global_load_lds_dwordx4 v[222:223], off
	s_add_i32 m0, s75, 0x2000
	v_lshl_add_u64 v[224:225], s[76:77], 0, v[138:139]
	s_add_u32 s76, s76, s28
	s_addc_u32 s77, s77, s29
	s_add_i32 s75, s69, s58
	global_load_lds_dwordx4 v[224:225], off
	v_lshl_add_u64 v[226:227], s[76:77], 0, v[134:135]
	s_mov_b32 m0, s75
	v_lshl_add_u64 v[228:229], s[76:77], 0, v[138:139]
	global_load_lds_dwordx4 v[226:227], off
	s_add_i32 m0, s75, 0x2000
	v_lshl_add_u64 v[230:231], s[46:47], 0, v[132:133]
	global_load_lds_dwordx4 v[228:229], off
	s_mov_b32 m0, s59
	v_lshl_add_u64 v[232:233], s[46:47], 0, v[136:137]
	global_load_lds_dwordx4 v[230:231], off
	s_mov_b32 m0, s60
	s_nop 0
	global_load_lds_dwordx4 v[232:233], off
	s_waitcnt vmcnt(8)
	s_waitcnt lgkmcnt(0)
	s_barrier
; #define PG8_STAGE(bufoff, gbase, voff) do { _Pragma("unroll") for (int _i = 0; _i < 2; ++_i) \
;         __builtin_amdgcn_global_load_lds((const unsigned*)((const char*)(gbase) + (voff)[_i]), (PG8_LAS unsigned*)(lds + (bufoff) + ldsw + _i * 8192), 16, 0, 0); } while (0)
; #define PG8_LDA(dst, b, h) do { _Pragma("unroll") for (int m = 0; m < 4; ++m) _Pragma("unroll") for (int k = 0; k < 2; ++k) dst[m][k] = *(const PG8_LAS bf16x8*)(lds + PG8_SA(b, h) + aoff + m * 2048 + k * 1024); } while (0)
; #define PG8_LDB(dst, b, h) do { _Pragma("unroll") for (int n = 0; n < 2; ++n) _Pragma("unroll") for (int k = 0; k < 2; ++k) dst[n][k] = *(const PG8_LAS bf16x8*)(lds + PG8_SB(b, h) + boff + n * 2048 + k * 1024); } while (0)
; #define PG8_MMA(ai, bj, At, Bt) do { __builtin_amdgcn_s_setprio(1); _Pragma("unroll") for (int m = 0; m < 4; ++m) _Pragma("unroll") for (int n = 0; n < 2; ++n) _Pragma("unroll") for (int k = 0; k < 2; ++k) \
;         acc[ai][bj][m][n] = __builtin_amdgcn_mfma_f32_16x16x32_bf16(Bt[n][k], At[m][k], acc[ai][bj][m][n], 0, 0, 0); __builtin_amdgcn_s_setprio(0); } while (0)
; #define PG8_WAIT_V(n) asm volatile("s_waitcnt vmcnt(" #n ")" ::: "memory")
; #define PG8_WAIT_L(n) asm volatile("s_waitcnt lgkmcnt(" #n ")" ::: "memory")
; #define PG8_BAR __builtin_amdgcn_s_barrier()
; #define PG8_SCHED __builtin_amdgcn_sched_barrier(0)
; template <class Epi, class Sched, bool ALIGN_EPI = false, bool SP2 = false>
; __device__ __forceinline__ void gemm_phase(PG8_LAS unsigned char* lds, const Gemm g, const Sched& S, const Epi& E) {
;     ...
;             PG8_WAIT_V(8); PG8_WAIT_L(0); PG8_BAR; PG8_MMA(1, 0, At, B0); PG8_MMA(1, 1, At, B1); PG8_BAR; PG8_SCHED;
;             PG8_LDB(B0, 1, 0); PG8_LDB(B1, 1, 1); PG8_SCHED; PG8_LDA(At, 1, 0); PG8_STAGE(PG8_SA(0, 1), a2 + hstep, voffA);
;             PG8_WAIT_V(8); PG8_WAIT_L(0); PG8_BAR; PG8_MMA(0, 0, At, B0); PG8_MMA(0, 1, At, B1); PG8_BAR; PG8_SCHED;
	s_setprio 1
	s_waitcnt lgkmcnt(0)
	v_mfma_f32_16x16x32_bf16 v[100:103], v[158:161], v[190:193], v[100:103]
	v_mfma_f32_16x16x32_bf16 v[96:99], v[166:169], v[190:193], v[96:99]
	v_mfma_f32_16x16x32_bf16 v[108:111], v[158:161], v[198:201], v[108:111]
	v_mfma_f32_16x16x32_bf16 v[104:107], v[166:169], v[198:201], v[104:107]
	v_mfma_f32_16x16x32_bf16 v[116:119], v[158:161], v[206:209], v[116:119]
	v_mfma_f32_16x16x32_bf16 v[112:115], v[166:169], v[206:209], v[112:115]
	v_mfma_f32_16x16x32_bf16 v[124:127], v[158:161], v[214:217], v[124:127]
	v_mfma_f32_16x16x32_bf16 v[120:123], v[166:169], v[214:217], v[120:123]
	v_mfma_f32_16x16x32_bf16 v[100:103], v[162:165], v[194:197], v[100:103]
	v_mfma_f32_16x16x32_bf16 v[96:99], v[170:173], v[194:197], v[96:99]
	v_mfma_f32_16x16x32_bf16 v[108:111], v[162:165], v[202:205], v[108:111]
	v_mfma_f32_16x16x32_bf16 v[104:107], v[170:173], v[202:205], v[104:107]
	v_mfma_f32_16x16x32_bf16 v[116:119], v[162:165], v[210:213], v[116:119]
	v_mfma_f32_16x16x32_bf16 v[112:115], v[170:173], v[210:213], v[112:115]
	v_mfma_f32_16x16x32_bf16 v[124:127], v[162:165], v[218:221], v[124:127]
	v_mfma_f32_16x16x32_bf16 v[120:123], v[170:173], v[218:221], v[120:123]
	v_mfma_f32_16x16x32_bf16 v[36:39], v[174:177], v[190:193], v[36:39]
	v_mfma_f32_16x16x32_bf16 v[32:35], v[182:185], v[190:193], v[32:35]
	v_mfma_f32_16x16x32_bf16 v[44:47], v[174:177], v[198:201], v[44:47]
	v_mfma_f32_16x16x32_bf16 v[40:43], v[182:185], v[198:201], v[40:43]
	v_mfma_f32_16x16x32_bf16 v[52:55], v[174:177], v[206:209], v[52:55]
	v_mfma_f32_16x16x32_bf16 v[48:51], v[182:185], v[206:209], v[48:51]
	v_mfma_f32_16x16x32_bf16 v[68:71], v[174:177], v[214:217], v[68:71]
	v_mfma_f32_16x16x32_bf16 v[64:67], v[182:185], v[214:217], v[64:67]
	v_mfma_f32_16x16x32_bf16 v[36:39], v[178:181], v[194:197], v[36:39]
	v_mfma_f32_16x16x32_bf16 v[32:35], v[186:189], v[194:197], v[32:35]
	v_mfma_f32_16x16x32_bf16 v[44:47], v[178:181], v[202:205], v[44:47]
	v_mfma_f32_16x16x32_bf16 v[40:43], v[186:189], v[202:205], v[40:43]
	v_mfma_f32_16x16x32_bf16 v[52:55], v[178:181], v[210:213], v[52:55]
	v_mfma_f32_16x16x32_bf16 v[48:51], v[186:189], v[210:213], v[48:51]
	v_mfma_f32_16x16x32_bf16 v[68:71], v[178:181], v[218:221], v[68:71]
	v_mfma_f32_16x16x32_bf16 v[64:67], v[186:189], v[218:221], v[64:67]
	s_setprio 0
	s_barrier
	s_add_i32 s75, 0, 0x18000
	v_add_u32_e32 v1, s75, v149
	s_add_i32 s76, 0, 0x1c000
	ds_read_b128 v[158:161], v1
	ds_read_b128 v[162:165], v1 offset:1024
	ds_read_b128 v[166:169], v1 offset:2048
	ds_read_b128 v[170:173], v1 offset:3072
	v_add_u32_e32 v1, s76, v149
	ds_read_b128 v[174:177], v1
	ds_read_b128 v[178:181], v1 offset:1024
	ds_read_b128 v[182:185], v1 offset:2048
	ds_read_b128 v[186:189], v1 offset:3072
	s_add_u32 s46, s46, s28
	s_addc_u32 s47, s47, s29
	s_mov_b32 m0, s61
	v_lshl_add_u64 v[6:7], s[46:47], 0, v[132:133]
	ds_read_b128 v[190:193], v150 offset:32768
	ds_read_b128 v[194:197], v150 offset:33792
	ds_read_b128 v[198:201], v150 offset:34816
	ds_read_b128 v[202:205], v150 offset:35840
	ds_read_b128 v[206:209], v150 offset:36864
	ds_read_b128 v[210:213], v150 offset:37888
	ds_read_b128 v[214:217], v150 offset:38912
	ds_read_b128 v[218:221], v150 offset:39936
	global_load_lds_dwordx4 v[6:7], off
	v_lshl_add_u64 v[6:7], s[46:47], 0, v[136:137]
	s_mov_b32 m0, s62
	s_nop 0
	global_load_lds_dwordx4 v[6:7], off
	s_waitcnt vmcnt(8)
	s_waitcnt lgkmcnt(0)
	s_barrier
	s_setprio 1
	s_waitcnt lgkmcnt(0)
	v_mfma_f32_16x16x32_bf16 v[60:63], v[158:161], v[190:193], v[60:63]
	v_mfma_f32_16x16x32_bf16 v[56:59], v[166:169], v[190:193], v[56:59]
	v_mfma_f32_16x16x32_bf16 v[76:79], v[158:161], v[198:201], v[76:79]
	v_mfma_f32_16x16x32_bf16 v[72:75], v[166:169], v[198:201], v[72:75]
	v_mfma_f32_16x16x32_bf16 v[84:87], v[158:161], v[206:209], v[84:87]
	v_mfma_f32_16x16x32_bf16 v[80:83], v[166:169], v[206:209], v[80:83]
	v_mfma_f32_16x16x32_bf16 v[92:95], v[158:161], v[214:217], v[92:95]
	v_mfma_f32_16x16x32_bf16 v[88:91], v[166:169], v[214:217], v[88:91]
	v_mfma_f32_16x16x32_bf16 v[60:63], v[162:165], v[194:197], v[60:63]
	v_mfma_f32_16x16x32_bf16 v[56:59], v[170:173], v[194:197], v[56:59]
	v_mfma_f32_16x16x32_bf16 v[76:79], v[162:165], v[202:205], v[76:79]
	v_mfma_f32_16x16x32_bf16 v[72:75], v[170:173], v[202:205], v[72:75]
	v_mfma_f32_16x16x32_bf16 v[84:87], v[162:165], v[210:213], v[84:87]
	v_mfma_f32_16x16x32_bf16 v[80:83], v[170:173], v[210:213], v[80:83]
	v_mfma_f32_16x16x32_bf16 v[92:95], v[162:165], v[218:221], v[92:95]
	v_mfma_f32_16x16x32_bf16 v[88:91], v[170:173], v[218:221], v[88:91]
	v_mfma_f32_16x16x32_bf16 v[2:5], v[174:177], v[190:193], v[2:5]
	v_mfma_f32_16x16x32_bf16 v[128:131], v[182:185], v[190:193], v[128:131]
	v_mfma_f32_16x16x32_bf16 v[12:15], v[174:177], v[198:201], v[12:15]
	v_mfma_f32_16x16x32_bf16 v[8:11], v[182:185], v[198:201], v[8:11]
	v_mfma_f32_16x16x32_bf16 v[20:23], v[174:177], v[206:209], v[20:23]
	v_mfma_f32_16x16x32_bf16 v[16:19], v[182:185], v[206:209], v[16:19]
	v_mfma_f32_16x16x32_bf16 v[28:31], v[174:177], v[214:217], v[28:31]
	v_mfma_f32_16x16x32_bf16 v[24:27], v[182:185], v[214:217], v[24:27]
	v_mfma_f32_16x16x32_bf16 v[4:7], v[178:181], v[194:197], v[2:5]
	v_mfma_f32_16x16x32_bf16 v[128:131], v[186:189], v[194:197], v[128:131]
	v_mfma_f32_16x16x32_bf16 v[12:15], v[178:181], v[202:205], v[12:15]
	v_mfma_f32_16x16x32_bf16 v[8:11], v[186:189], v[202:205], v[8:11]
	v_mfma_f32_16x16x32_bf16 v[20:23], v[178:181], v[210:213], v[20:23]
	v_mfma_f32_16x16x32_bf16 v[16:19], v[186:189], v[210:213], v[16:19]
	v_mfma_f32_16x16x32_bf16 v[28:31], v[178:181], v[218:221], v[28:31]
	v_mfma_f32_16x16x32_bf16 v[24:27], v[186:189], v[218:221], v[24:27]
	s_setprio 0
	s_barrier
; #define PG8_STAGE(bufoff, gbase, voff) do { _Pragma("unroll") for (int _i = 0; _i < 2; ++_i) \
;         __builtin_amdgcn_global_load_lds((const unsigned*)((const char*)(gbase) + (voff)[_i]), (PG8_LAS unsigned*)(lds + (bufoff) + ldsw + _i * 8192), 16, 0, 0); } while (0)
; #define PG8_LDA(dst, b, h) do { _Pragma("unroll") for (int m = 0; m < 4; ++m) _Pragma("unroll") for (int k = 0; k < 2; ++k) dst[m][k] = *(const PG8_LAS bf16x8*)(lds + PG8_SA(b, h) + aoff + m * 2048 + k * 1024); } while (0)
; #define PG8_MMA(ai, bj, At, Bt) do { __builtin_amdgcn_s_setprio(1); _Pragma("unroll") for (int m = 0; m < 4; ++m) _Pragma("unroll") for (int n = 0; n < 2; ++n) _Pragma("unroll") for (int k = 0; k < 2; ++k) \
;         acc[ai][bj][m][n] = __builtin_amdgcn_mfma_f32_16x16x32_bf16(Bt[n][k], At[m][k], acc[ai][bj][m][n], 0, 0, 0); __builtin_amdgcn_s_setprio(0); } while (0)
; #define PG8_WAIT_V(n) asm volatile("s_waitcnt vmcnt(" #n ")" ::: "memory")
; #define PG8_WAIT_L(n) asm volatile("s_waitcnt lgkmcnt(" #n ")" ::: "memory")
; #define PG8_BAR __builtin_amdgcn_s_barrier()
; #define PG8_SCHED __builtin_amdgcn_sched_barrier(0)
; template <class Epi, class Sched, bool ALIGN_EPI = false, bool SP2 = false>
; __device__ __forceinline__ void gemm_phase(PG8_LAS unsigned char* lds, const Gemm g, const Sched& S, const Epi& E) {
;     ...
;         for (int t = 0; t < nt; t += 2) {
;     ...
;             PG8_LDA(At, 1, 1); PG8_STAGE(PG8_SB(1, 0), b3, voffB); PG8_STAGE(PG8_SB(1, 1), b3 + hstep, voffB); PG8_STAGE(PG8_SA(1, 0), a3, voffA);
;             PG8_WAIT_V(8); PG8_WAIT_L(0); PG8_BAR; PG8_MMA(1, 0, At, B0); PG8_MMA(1, 1, At, B1); PG8_BAR; PG8_SCHED;
	s_add_i32 s46, s75, s58
	v_lshl_add_u64 v[2:3], v[222:223], 0, s[38:39]
	s_mov_b32 m0, s46
	ds_read_b128 v[190:193], v150 offset:49152
	ds_read_b128 v[194:197], v150 offset:50176
	ds_read_b128 v[198:201], v150 offset:51200
	ds_read_b128 v[202:205], v150 offset:52224
	ds_read_b128 v[206:209], v150 offset:53248
	ds_read_b128 v[210:213], v150 offset:54272
	ds_read_b128 v[214:217], v150 offset:55296
	ds_read_b128 v[218:221], v150 offset:56320
	global_load_lds_dwordx4 v[2:3], off
	v_lshl_add_u64 v[2:3], v[224:225], 0, s[38:39]
	s_add_i32 m0, s46, 0x2000
	s_add_i32 s46, s76, s58
	global_load_lds_dwordx4 v[2:3], off
	v_lshl_add_u64 v[2:3], v[226:227], 0, s[38:39]
	s_mov_b32 m0, s46
	s_nop 0
	global_load_lds_dwordx4 v[2:3], off
	v_lshl_add_u64 v[2:3], v[228:229], 0, s[38:39]
	s_add_i32 m0, s46, 0x2000
	s_nop 0
	global_load_lds_dwordx4 v[2:3], off
	v_lshl_add_u64 v[2:3], v[230:231], 0, s[38:39]
	s_mov_b32 m0, s63
	s_nop 0
	global_load_lds_dwordx4 v[2:3], off
	v_lshl_add_u64 v[2:3], v[232:233], 0, s[38:39]
	s_mov_b32 m0, s64
	s_nop 0
	global_load_lds_dwordx4 v[2:3], off
	s_waitcnt vmcnt(8)
	s_waitcnt lgkmcnt(0)
	s_barrier
	s_setprio 1
	s_waitcnt lgkmcnt(0)
	v_mfma_f32_16x16x32_bf16 v[100:103], v[158:161], v[190:193], v[100:103]
	v_mfma_f32_16x16x32_bf16 v[96:99], v[166:169], v[190:193], v[96:99]
	v_mfma_f32_16x16x32_bf16 v[108:111], v[158:161], v[198:201], v[108:111]
	v_mfma_f32_16x16x32_bf16 v[104:107], v[166:169], v[198:201], v[104:107]
	v_mfma_f32_16x16x32_bf16 v[116:119], v[158:161], v[206:209], v[116:119]
	v_mfma_f32_16x16x32_bf16 v[112:115], v[166:169], v[206:209], v[112:115]
	v_mfma_f32_16x16x32_bf16 v[124:127], v[158:161], v[214:217], v[124:127]
	v_mfma_f32_16x16x32_bf16 v[120:123], v[166:169], v[214:217], v[120:123]
	v_mfma_f32_16x16x32_bf16 v[100:103], v[162:165], v[194:197], v[100:103]
	v_mfma_f32_16x16x32_bf16 v[96:99], v[170:173], v[194:197], v[96:99]
	v_mfma_f32_16x16x32_bf16 v[108:111], v[162:165], v[202:205], v[108:111]
	v_mfma_f32_16x16x32_bf16 v[104:107], v[170:173], v[202:205], v[104:107]
	v_mfma_f32_16x16x32_bf16 v[116:119], v[162:165], v[210:213], v[116:119]
	v_mfma_f32_16x16x32_bf16 v[112:115], v[170:173], v[210:213], v[112:115]
	v_mfma_f32_16x16x32_bf16 v[124:127], v[162:165], v[218:221], v[124:127]
	v_mfma_f32_16x16x32_bf16 v[120:123], v[170:173], v[218:221], v[120:123]
	v_mfma_f32_16x16x32_bf16 v[36:39], v[174:177], v[190:193], v[36:39]
	v_mfma_f32_16x16x32_bf16 v[32:35], v[182:185], v[190:193], v[32:35]
	v_mfma_f32_16x16x32_bf16 v[44:47], v[174:177], v[198:201], v[44:47]
	v_mfma_f32_16x16x32_bf16 v[40:43], v[182:185], v[198:201], v[40:43]
	v_mfma_f32_16x16x32_bf16 v[52:55], v[174:177], v[206:209], v[52:55]
	v_mfma_f32_16x16x32_bf16 v[48:51], v[182:185], v[206:209], v[48:51]
	v_mfma_f32_16x16x32_bf16 v[68:71], v[174:177], v[214:217], v[68:71]
	v_mfma_f32_16x16x32_bf16 v[64:67], v[182:185], v[214:217], v[64:67]
	v_mfma_f32_16x16x32_bf16 v[36:39], v[178:181], v[194:197], v[36:39]
	v_mfma_f32_16x16x32_bf16 v[32:35], v[186:189], v[194:197], v[32:35]
	v_mfma_f32_16x16x32_bf16 v[44:47], v[178:181], v[202:205], v[44:47]
	v_mfma_f32_16x16x32_bf16 v[40:43], v[186:189], v[202:205], v[40:43]
	v_mfma_f32_16x16x32_bf16 v[52:55], v[178:181], v[210:213], v[52:55]
	v_mfma_f32_16x16x32_bf16 v[48:51], v[186:189], v[210:213], v[48:51]
	v_mfma_f32_16x16x32_bf16 v[68:71], v[178:181], v[218:221], v[68:71]
	v_mfma_f32_16x16x32_bf16 v[64:67], v[186:189], v[218:221], v[64:67]
	s_setprio 0
	s_barrier
	s_add_u32 s44, s44, 0x100
	s_addc_u32 s45, s45, 0
	s_add_u32 s0, s0, 0x100
	s_addc_u32 s1, s1, 0
	s_cmp_ge_i32 s74, s66
	s_mov_b32 s46, s74
	s_cbranch_scc0 .LBB0_274

; #define PG8_STAGE(bufoff, gbase, voff) do { _Pragma("unroll") for (int _i = 0; _i < 2; ++_i) \
;         __builtin_amdgcn_global_load_lds((const unsigned*)((const char*)(gbase) + (voff)[_i]), (PG8_LAS unsigned*)(lds + (bufoff) + ldsw + _i * 8192), 16, 0, 0); } while (0)
; #define PG8_LDA(dst, b, h) do { _Pragma("unroll") for (int m = 0; m < 4; ++m) _Pragma("unroll") for (int k = 0; k < 2; ++k) dst[m][k] = *(const PG8_LAS bf16x8*)(lds + PG8_SA(b, h) + aoff + m * 2048 + k * 1024); } while (0)
; #define PG8_LDB(dst, b, h) do { _Pragma("unroll") for (int n = 0; n < 2; ++n) _Pragma("unroll") for (int k = 0; k < 2; ++k) dst[n][k] = *(const PG8_LAS bf16x8*)(lds + PG8_SB(b, h) + boff + n * 2048 + k * 1024); } while (0)
; #define PG8_MMA(ai, bj, At, Bt) do { __builtin_amdgcn_s_setprio(1); _Pragma("unroll") for (int m = 0; m < 4; ++m) _Pragma("unroll") for (int n = 0; n < 2; ++n) _Pragma("unroll") for (int k = 0; k < 2; ++k) \
;         acc[ai][bj][m][n] = __builtin_amdgcn_mfma_f32_16x16x32_bf16(Bt[n][k], At[m][k], acc[ai][bj][m][n], 0, 0, 0); __builtin_amdgcn_s_setprio(0); } while (0)
; #define PG8_WAIT_V(n) asm volatile("s_waitcnt vmcnt(" #n ")" ::: "memory")
; #define PG8_WAIT_L(n) asm volatile("s_waitcnt lgkmcnt(" #n ")" ::: "memory")
; #define PG8_BAR __builtin_amdgcn_s_barrier()
; #define PG8_SCHED __builtin_amdgcn_sched_barrier(0)
; template <class Epi, class Sched, bool ALIGN_EPI = false, bool SP2 = false>
; __device__ __forceinline__ void gemm_phase(PG8_LAS unsigned char* lds, const Gemm g, const Sched& S, const Epi& E) {
;     ...
;             const bool last = (t == nt - 2);
;             const char* a1 = cA + (size_t)(t + 1) * kstep;
;             const char* a2 = last ? nA : cA + (size_t)(t + 2) * kstep; const char* b2 = last ? nB : cB + (size_t)(t + 2) * kstep;
;             const char* a3 = a2 + kstep; const char* b3 = b2 + kstep;
;             if (last && has_next) S.a_ready(nxt);
;             if constexpr (SP2) {
;             PG8_LDB(B0, 0, 0); PG8_LDB(B1, 0, 1); PG8_SCHED; PG8_LDA(At, 0, 0); PG8_STAGE(PG8_SA(1, 1), a1 + hstep, voffA);
;             PG8_WAIT_V(8); PG8_WAIT_L(0); PG8_BAR; PG8_MMA(0, 0, At, B0); PG8_MMA(0, 1, At, B1); PG8_BAR; PG8_SCHED;
;             PG8_LDA(At, 0, 1); PG8_STAGE(PG8_SB(0, 0), b2, voffB); PG8_STAGE(PG8_SB(0, 1), b2 + hstep, voffB); PG8_STAGE(PG8_SA(0, 0), a2, voffA);
.LBB0_501:
	ds_read_b128 v[148:151], v157
	ds_read_b128 v[158:161], v157 offset:1024
	ds_read_b128 v[166:169], v157 offset:2048
	ds_read_b128 v[170:173], v157 offset:3072
	ds_read_b128 v[174:177], v164
	ds_read_b128 v[178:181], v164 offset:1024
	ds_read_b128 v[182:185], v164 offset:2048
	ds_read_b128 v[186:189], v164 offset:3072
	s_add_i32 s44, s12, 2
	s_add_u32 s45, s10, 0x80
	s_addc_u32 s13, s11, 0
	s_cmp_eq_u32 s69, s12
	s_cselect_b32 s12, s40, s45
	s_cselect_b32 s13, s41, s13
	s_cselect_b32 s47, s43, s1
	s_cselect_b32 s46, s42, s0
	v_lshl_add_u64 v[162:163], s[10:11], 0, v[140:141]
	s_add_i32 m0, s58, 0xc000
	ds_read_b128 v[190:193], v165
	ds_read_b128 v[194:197], v165 offset:1024
	ds_read_b128 v[198:201], v165 offset:2048
	ds_read_b128 v[202:205], v165 offset:3072
	ds_read_b128 v[206:209], v165 offset:4096
	ds_read_b128 v[210:213], v165 offset:5120
	ds_read_b128 v[214:217], v165 offset:6144
	ds_read_b128 v[218:221], v165 offset:7168
	global_load_lds_dwordx4 v[162:163], off
	v_lshl_add_u64 v[162:163], s[10:11], 0, v[142:143]
	s_add_i32 m0, s58, 0xe000
	s_nop 0
	global_load_lds_dwordx4 v[162:163], off
	s_waitcnt vmcnt(8)
	s_waitcnt lgkmcnt(0)
	s_barrier
	s_setprio 1
	s_waitcnt lgkmcnt(0)
	v_mfma_f32_16x16x32_bf16 v[124:127], v[148:151], v[190:193], v[124:127]
	v_mfma_f32_16x16x32_bf16 v[120:123], v[166:169], v[190:193], v[120:123]
	v_mfma_f32_16x16x32_bf16 v[108:111], v[148:151], v[198:201], v[108:111]
	v_mfma_f32_16x16x32_bf16 v[104:107], v[166:169], v[198:201], v[104:107]
	v_mfma_f32_16x16x32_bf16 v[92:95], v[148:151], v[206:209], v[92:95]
	v_mfma_f32_16x16x32_bf16 v[88:91], v[166:169], v[206:209], v[88:91]
	v_mfma_f32_16x16x32_bf16 v[76:79], v[148:151], v[214:217], v[76:79]
	v_mfma_f32_16x16x32_bf16 v[72:75], v[166:169], v[214:217], v[72:75]
	v_mfma_f32_16x16x32_bf16 v[124:127], v[158:161], v[194:197], v[124:127]
	v_mfma_f32_16x16x32_bf16 v[120:123], v[170:173], v[194:197], v[120:123]
	v_mfma_f32_16x16x32_bf16 v[108:111], v[158:161], v[202:205], v[108:111]
	v_mfma_f32_16x16x32_bf16 v[104:107], v[170:173], v[202:205], v[104:107]
	v_mfma_f32_16x16x32_bf16 v[92:95], v[158:161], v[210:213], v[92:95]
	v_mfma_f32_16x16x32_bf16 v[88:91], v[170:173], v[210:213], v[88:91]
	v_mfma_f32_16x16x32_bf16 v[76:79], v[158:161], v[218:221], v[76:79]
	v_mfma_f32_16x16x32_bf16 v[72:75], v[170:173], v[218:221], v[72:75]
	v_mfma_f32_16x16x32_bf16 v[116:119], v[174:177], v[190:193], v[116:119]
	v_mfma_f32_16x16x32_bf16 v[112:115], v[182:185], v[190:193], v[112:115]
	v_mfma_f32_16x16x32_bf16 v[100:103], v[174:177], v[198:201], v[100:103]
	v_mfma_f32_16x16x32_bf16 v[96:99], v[182:185], v[198:201], v[96:99]
	v_mfma_f32_16x16x32_bf16 v[84:87], v[174:177], v[206:209], v[84:87]
	v_mfma_f32_16x16x32_bf16 v[80:83], v[182:185], v[206:209], v[80:83]
	v_mfma_f32_16x16x32_bf16 v[68:71], v[174:177], v[214:217], v[68:71]
	v_mfma_f32_16x16x32_bf16 v[64:67], v[182:185], v[214:217], v[64:67]
	v_mfma_f32_16x16x32_bf16 v[116:119], v[178:181], v[194:197], v[116:119]
	v_mfma_f32_16x16x32_bf16 v[112:115], v[186:189], v[194:197], v[112:115]
	v_mfma_f32_16x16x32_bf16 v[100:103], v[178:181], v[202:205], v[100:103]
	v_mfma_f32_16x16x32_bf16 v[96:99], v[186:189], v[202:205], v[96:99]
	v_mfma_f32_16x16x32_bf16 v[84:87], v[178:181], v[210:213], v[84:87]
	v_mfma_f32_16x16x32_bf16 v[80:83], v[186:189], v[210:213], v[80:83]
	v_mfma_f32_16x16x32_bf16 v[68:71], v[178:181], v[218:221], v[68:71]
	v_mfma_f32_16x16x32_bf16 v[64:67], v[186:189], v[218:221], v[64:67]
	s_setprio 0
	s_barrier
	s_add_i32 s45, s74, s55
	v_lshl_add_u64 v[162:163], s[46:47], 0, v[130:131]
	s_mov_b32 m0, s45
	ds_read_b128 v[190:193], v165 offset:16384
	ds_read_b128 v[194:197], v165 offset:17408
	ds_read_b128 v[198:201], v165 offset:18432
	ds_read_b128 v[202:205], v165 offset:19456
	ds_read_b128 v[206:209], v165 offset:20480
	ds_read_b128 v[210:213], v165 offset:21504
	ds_read_b128 v[214:217], v165 offset:22528
	ds_read_b128 v[218:221], v165 offset:23552
	global_load_lds_dwordx4 v[162:163], off
	s_add_i32 m0, s45, 0x2000
	v_lshl_add_u64 v[222:223], s[46:47], 0, v[134:135]
	s_add_u32 s46, s46, s14
	s_addc_u32 s47, s47, s15
	s_add_i32 s45, s75, s55
	global_load_lds_dwordx4 v[222:223], off
	v_lshl_add_u64 v[224:225], s[46:47], 0, v[130:131]
	s_mov_b32 m0, s45
	v_lshl_add_u64 v[226:227], s[46:47], 0, v[134:135]
	global_load_lds_dwordx4 v[224:225], off
	s_add_i32 m0, s45, 0x2000
	v_lshl_add_u64 v[228:229], s[12:13], 0, v[128:129]
	global_load_lds_dwordx4 v[226:227], off
	s_mov_b32 m0, s58
	v_lshl_add_u64 v[230:231], s[12:13], 0, v[132:133]
	global_load_lds_dwordx4 v[228:229], off
	s_mov_b32 m0, s59
	s_nop 0
	global_load_lds_dwordx4 v[230:231], off
	s_waitcnt vmcnt(8)
	s_waitcnt lgkmcnt(0)
	s_barrier
; #define PG8_STAGE(bufoff, gbase, voff) do { _Pragma("unroll") for (int _i = 0; _i < 2; ++_i) \
;         __builtin_amdgcn_global_load_lds((const unsigned*)((const char*)(gbase) + (voff)[_i]), (PG8_LAS unsigned*)(lds + (bufoff) + ldsw + _i * 8192), 16, 0, 0); } while (0)
; #define PG8_LDA(dst, b, h) do { _Pragma("unroll") for (int m = 0; m < 4; ++m) _Pragma("unroll") for (int k = 0; k < 2; ++k) dst[m][k] = *(const PG8_LAS bf16x8*)(lds + PG8_SA(b, h) + aoff + m * 2048 + k * 1024); } while (0)
; #define PG8_LDB(dst, b, h) do { _Pragma("unroll") for (int n = 0; n < 2; ++n) _Pragma("unroll") for (int k = 0; k < 2; ++k) dst[n][k] = *(const PG8_LAS bf16x8*)(lds + PG8_SB(b, h) + boff + n * 2048 + k * 1024); } while (0)
; #define PG8_MMA(ai, bj, At, Bt) do { __builtin_amdgcn_s_setprio(1); _Pragma("unroll") for (int m = 0; m < 4; ++m) _Pragma("unroll") for (int n = 0; n < 2; ++n) _Pragma("unroll") for (int k = 0; k < 2; ++k) \
;         acc[ai][bj][m][n] = __builtin_amdgcn_mfma_f32_16x16x32_bf16(Bt[n][k], At[m][k], acc[ai][bj][m][n], 0, 0, 0); __builtin_amdgcn_s_setprio(0); } while (0)
; #define PG8_WAIT_V(n) asm volatile("s_waitcnt vmcnt(" #n ")" ::: "memory")
; #define PG8_WAIT_L(n) asm volatile("s_waitcnt lgkmcnt(" #n ")" ::: "memory")
; #define PG8_BAR __builtin_amdgcn_s_barrier()
; #define PG8_SCHED __builtin_amdgcn_sched_barrier(0)
; template <class Epi, class Sched, bool ALIGN_EPI = false, bool SP2 = false>
; __device__ __forceinline__ void gemm_phase(PG8_LAS unsigned char* lds, const Gemm g, const Sched& S, const Epi& E) {
;     ...
;             PG8_WAIT_V(8); PG8_WAIT_L(0); PG8_BAR; PG8_MMA(1, 0, At, B0); PG8_MMA(1, 1, At, B1); PG8_BAR; PG8_SCHED;
;             PG8_LDB(B0, 1, 0); PG8_LDB(B1, 1, 1); PG8_SCHED; PG8_LDA(At, 1, 0); PG8_STAGE(PG8_SA(0, 1), a2 + hstep, voffA);
;             PG8_WAIT_V(8); PG8_WAIT_L(0); PG8_BAR; PG8_MMA(0, 0, At, B0); PG8_MMA(0, 1, At, B1); PG8_BAR; PG8_SCHED;
	s_setprio 1
	s_waitcnt lgkmcnt(0)
	v_mfma_f32_16x16x32_bf16 v[60:63], v[148:151], v[190:193], v[60:63]
	v_mfma_f32_16x16x32_bf16 v[56:59], v[166:169], v[190:193], v[56:59]
	v_mfma_f32_16x16x32_bf16 v[44:47], v[148:151], v[198:201], v[44:47]
	v_mfma_f32_16x16x32_bf16 v[40:43], v[166:169], v[198:201], v[40:43]
	v_mfma_f32_16x16x32_bf16 v[28:31], v[148:151], v[206:209], v[28:31]
	v_mfma_f32_16x16x32_bf16 v[24:27], v[166:169], v[206:209], v[24:27]
	v_mfma_f32_16x16x32_bf16 v[12:15], v[148:151], v[214:217], v[12:15]
	v_mfma_f32_16x16x32_bf16 v[8:11], v[166:169], v[214:217], v[8:11]
	v_mfma_f32_16x16x32_bf16 v[60:63], v[158:161], v[194:197], v[60:63]
	v_mfma_f32_16x16x32_bf16 v[56:59], v[170:173], v[194:197], v[56:59]
	v_mfma_f32_16x16x32_bf16 v[44:47], v[158:161], v[202:205], v[44:47]
	v_mfma_f32_16x16x32_bf16 v[40:43], v[170:173], v[202:205], v[40:43]
	v_mfma_f32_16x16x32_bf16 v[28:31], v[158:161], v[210:213], v[28:31]
	v_mfma_f32_16x16x32_bf16 v[24:27], v[170:173], v[210:213], v[24:27]
	v_mfma_f32_16x16x32_bf16 v[12:15], v[158:161], v[218:221], v[12:15]
	v_mfma_f32_16x16x32_bf16 v[8:11], v[170:173], v[218:221], v[8:11]
	v_mfma_f32_16x16x32_bf16 v[52:55], v[174:177], v[190:193], v[52:55]
	v_mfma_f32_16x16x32_bf16 v[48:51], v[182:185], v[190:193], v[48:51]
	v_mfma_f32_16x16x32_bf16 v[36:39], v[174:177], v[198:201], v[36:39]
	v_mfma_f32_16x16x32_bf16 v[32:35], v[182:185], v[198:201], v[32:35]
	v_mfma_f32_16x16x32_bf16 v[20:23], v[174:177], v[206:209], v[20:23]
	v_mfma_f32_16x16x32_bf16 v[16:19], v[182:185], v[206:209], v[16:19]
	v_mfma_f32_16x16x32_bf16 v[4:7], v[174:177], v[214:217], v[4:7]
	v_mfma_f32_16x16x32_bf16 v[0:3], v[182:185], v[214:217], v[0:3]
	v_mfma_f32_16x16x32_bf16 v[52:55], v[178:181], v[194:197], v[52:55]
	v_mfma_f32_16x16x32_bf16 v[48:51], v[186:189], v[194:197], v[48:51]
	v_mfma_f32_16x16x32_bf16 v[36:39], v[178:181], v[202:205], v[36:39]
	v_mfma_f32_16x16x32_bf16 v[32:35], v[186:189], v[202:205], v[32:35]
	v_mfma_f32_16x16x32_bf16 v[20:23], v[178:181], v[210:213], v[20:23]
	v_mfma_f32_16x16x32_bf16 v[16:19], v[186:189], v[210:213], v[16:19]
	v_mfma_f32_16x16x32_bf16 v[4:7], v[178:181], v[218:221], v[4:7]
	v_mfma_f32_16x16x32_bf16 v[0:3], v[186:189], v[218:221], v[0:3]
	s_setprio 0
	s_barrier
	s_add_i32 s45, 0, 0x18000
	v_add_u32_e32 v136, s45, v153
	s_add_i32 s46, 0, 0x1c000
	ds_read_b128 v[148:151], v136
	ds_read_b128 v[158:161], v136 offset:1024
	ds_read_b128 v[166:169], v136 offset:2048
	ds_read_b128 v[170:173], v136 offset:3072
	v_add_u32_e32 v136, s46, v153
	ds_read_b128 v[174:177], v136
	ds_read_b128 v[178:181], v136 offset:1024
	ds_read_b128 v[182:185], v136 offset:2048
	ds_read_b128 v[186:189], v136 offset:3072
	s_add_u32 s12, s12, s14
	s_addc_u32 s13, s13, s15
	s_mov_b32 m0, s60
	v_lshl_add_u64 v[232:233], s[12:13], 0, v[128:129]
	ds_read_b128 v[190:193], v165 offset:32768
	ds_read_b128 v[194:197], v165 offset:33792
	ds_read_b128 v[198:201], v165 offset:34816
	ds_read_b128 v[202:205], v165 offset:35840
	ds_read_b128 v[206:209], v165 offset:36864
	ds_read_b128 v[210:213], v165 offset:37888
	ds_read_b128 v[214:217], v165 offset:38912
	ds_read_b128 v[218:221], v165 offset:39936
	global_load_lds_dwordx4 v[232:233], off
	v_lshl_add_u64 v[232:233], s[12:13], 0, v[132:133]
	s_mov_b32 m0, s61
	s_nop 0
	global_load_lds_dwordx4 v[232:233], off
	s_waitcnt vmcnt(8)
	s_waitcnt lgkmcnt(0)
	s_barrier
	s_setprio 1
	s_waitcnt lgkmcnt(0)
	v_mfma_f32_16x16x32_bf16 v[124:127], v[148:151], v[190:193], v[124:127]
	v_mfma_f32_16x16x32_bf16 v[120:123], v[166:169], v[190:193], v[120:123]
	v_mfma_f32_16x16x32_bf16 v[108:111], v[148:151], v[198:201], v[108:111]
	v_mfma_f32_16x16x32_bf16 v[104:107], v[166:169], v[198:201], v[104:107]
	v_mfma_f32_16x16x32_bf16 v[92:95], v[148:151], v[206:209], v[92:95]
	v_mfma_f32_16x16x32_bf16 v[88:91], v[166:169], v[206:209], v[88:91]
	v_mfma_f32_16x16x32_bf16 v[76:79], v[148:151], v[214:217], v[76:79]
	v_mfma_f32_16x16x32_bf16 v[72:75], v[166:169], v[214:217], v[72:75]
	v_mfma_f32_16x16x32_bf16 v[124:127], v[158:161], v[194:197], v[124:127]
	v_mfma_f32_16x16x32_bf16 v[120:123], v[170:173], v[194:197], v[120:123]
	v_mfma_f32_16x16x32_bf16 v[108:111], v[158:161], v[202:205], v[108:111]
	v_mfma_f32_16x16x32_bf16 v[104:107], v[170:173], v[202:205], v[104:107]
	v_mfma_f32_16x16x32_bf16 v[92:95], v[158:161], v[210:213], v[92:95]
	v_mfma_f32_16x16x32_bf16 v[88:91], v[170:173], v[210:213], v[88:91]
	v_mfma_f32_16x16x32_bf16 v[76:79], v[158:161], v[218:221], v[76:79]
	v_mfma_f32_16x16x32_bf16 v[72:75], v[170:173], v[218:221], v[72:75]
	v_mfma_f32_16x16x32_bf16 v[116:119], v[174:177], v[190:193], v[116:119]
	v_mfma_f32_16x16x32_bf16 v[112:115], v[182:185], v[190:193], v[112:115]
	v_mfma_f32_16x16x32_bf16 v[100:103], v[174:177], v[198:201], v[100:103]
	v_mfma_f32_16x16x32_bf16 v[96:99], v[182:185], v[198:201], v[96:99]
	v_mfma_f32_16x16x32_bf16 v[84:87], v[174:177], v[206:209], v[84:87]
	v_mfma_f32_16x16x32_bf16 v[80:83], v[182:185], v[206:209], v[80:83]
	v_mfma_f32_16x16x32_bf16 v[68:71], v[174:177], v[214:217], v[68:71]
	v_mfma_f32_16x16x32_bf16 v[64:67], v[182:185], v[214:217], v[64:67]
	v_mfma_f32_16x16x32_bf16 v[116:119], v[178:181], v[194:197], v[116:119]
	v_mfma_f32_16x16x32_bf16 v[112:115], v[186:189], v[194:197], v[112:115]
	v_mfma_f32_16x16x32_bf16 v[100:103], v[178:181], v[202:205], v[100:103]
	v_mfma_f32_16x16x32_bf16 v[96:99], v[186:189], v[202:205], v[96:99]
	v_mfma_f32_16x16x32_bf16 v[84:87], v[178:181], v[210:213], v[84:87]
	v_mfma_f32_16x16x32_bf16 v[80:83], v[186:189], v[210:213], v[80:83]
	v_mfma_f32_16x16x32_bf16 v[68:71], v[178:181], v[218:221], v[68:71]
	v_mfma_f32_16x16x32_bf16 v[64:67], v[186:189], v[218:221], v[64:67]
	s_setprio 0
	s_barrier
; #define PG8_STAGE(bufoff, gbase, voff) do { _Pragma("unroll") for (int _i = 0; _i < 2; ++_i) \
;         __builtin_amdgcn_global_load_lds((const unsigned*)((const char*)(gbase) + (voff)[_i]), (PG8_LAS unsigned*)(lds + (bufoff) + ldsw + _i * 8192), 16, 0, 0); } while (0)
; #define PG8_LDA(dst, b, h) do { _Pragma("unroll") for (int m = 0; m < 4; ++m) _Pragma("unroll") for (int k = 0; k < 2; ++k) dst[m][k] = *(const PG8_LAS bf16x8*)(lds + PG8_SA(b, h) + aoff + m * 2048 + k * 1024); } while (0)
; #define PG8_MMA(ai, bj, At, Bt) do { __builtin_amdgcn_s_setprio(1); _Pragma("unroll") for (int m = 0; m < 4; ++m) _Pragma("unroll") for (int n = 0; n < 2; ++n) _Pragma("unroll") for (int k = 0; k < 2; ++k) \
;         acc[ai][bj][m][n] = __builtin_amdgcn_mfma_f32_16x16x32_bf16(Bt[n][k], At[m][k], acc[ai][bj][m][n], 0, 0, 0); __builtin_amdgcn_s_setprio(0); } while (0)
; #define PG8_WAIT_V(n) asm volatile("s_waitcnt vmcnt(" #n ")" ::: "memory")
; #define PG8_WAIT_L(n) asm volatile("s_waitcnt lgkmcnt(" #n ")" ::: "memory")
; #define PG8_BAR __builtin_amdgcn_s_barrier()
; #define PG8_SCHED __builtin_amdgcn_sched_barrier(0)
; template <class Epi, class Sched, bool ALIGN_EPI = false, bool SP2 = false>
; __device__ __forceinline__ void gemm_phase(PG8_LAS unsigned char* lds, const Gemm g, const Sched& S, const Epi& E) {
;     ...
;         for (int t = 0; t < nt; t += 2) {
;     ...
;             PG8_LDA(At, 1, 1); PG8_STAGE(PG8_SB(1, 0), b3, voffB); PG8_STAGE(PG8_SB(1, 1), b3 + hstep, voffB); PG8_STAGE(PG8_SA(1, 0), a3, voffA);
;             PG8_WAIT_V(8); PG8_WAIT_L(0); PG8_BAR; PG8_MMA(1, 0, At, B0); PG8_MMA(1, 1, At, B1); PG8_BAR; PG8_SCHED;
	s_add_i32 s12, s45, s55
	v_lshl_add_u64 v[162:163], v[162:163], 0, s[26:27]
	s_mov_b32 m0, s12
	ds_read_b128 v[190:193], v165 offset:49152
	ds_read_b128 v[194:197], v165 offset:50176
	ds_read_b128 v[198:201], v165 offset:51200
	ds_read_b128 v[202:205], v165 offset:52224
	ds_read_b128 v[206:209], v165 offset:53248
	ds_read_b128 v[210:213], v165 offset:54272
	ds_read_b128 v[214:217], v165 offset:55296
	ds_read_b128 v[218:221], v165 offset:56320
	global_load_lds_dwordx4 v[162:163], off
	v_lshl_add_u64 v[162:163], v[222:223], 0, s[26:27]
	s_add_i32 m0, s12, 0x2000
	s_add_i32 s12, s46, s55
	global_load_lds_dwordx4 v[162:163], off
	v_lshl_add_u64 v[162:163], v[224:225], 0, s[26:27]
	s_mov_b32 m0, s12
	s_nop 0
	global_load_lds_dwordx4 v[162:163], off
	v_lshl_add_u64 v[162:163], v[226:227], 0, s[26:27]
	s_add_i32 m0, s12, 0x2000
	s_nop 0
	global_load_lds_dwordx4 v[162:163], off
	v_lshl_add_u64 v[162:163], v[228:229], 0, s[26:27]
	s_mov_b32 m0, s67
	s_nop 0
	global_load_lds_dwordx4 v[162:163], off
	v_lshl_add_u64 v[162:163], v[230:231], 0, s[26:27]
	s_mov_b32 m0, s68
	s_nop 0
	global_load_lds_dwordx4 v[162:163], off
	s_waitcnt vmcnt(8)
	s_waitcnt lgkmcnt(0)
	s_barrier
	s_setprio 1
	s_waitcnt lgkmcnt(0)
	v_mfma_f32_16x16x32_bf16 v[60:63], v[148:151], v[190:193], v[60:63]
	v_mfma_f32_16x16x32_bf16 v[56:59], v[166:169], v[190:193], v[56:59]
	v_mfma_f32_16x16x32_bf16 v[44:47], v[148:151], v[198:201], v[44:47]
	v_mfma_f32_16x16x32_bf16 v[40:43], v[166:169], v[198:201], v[40:43]
	v_mfma_f32_16x16x32_bf16 v[28:31], v[148:151], v[206:209], v[28:31]
	v_mfma_f32_16x16x32_bf16 v[24:27], v[166:169], v[206:209], v[24:27]
	v_mfma_f32_16x16x32_bf16 v[12:15], v[148:151], v[214:217], v[12:15]
	v_mfma_f32_16x16x32_bf16 v[8:11], v[166:169], v[214:217], v[8:11]
	v_mfma_f32_16x16x32_bf16 v[60:63], v[158:161], v[194:197], v[60:63]
	v_mfma_f32_16x16x32_bf16 v[56:59], v[170:173], v[194:197], v[56:59]
	v_mfma_f32_16x16x32_bf16 v[44:47], v[158:161], v[202:205], v[44:47]
	v_mfma_f32_16x16x32_bf16 v[40:43], v[170:173], v[202:205], v[40:43]
	v_mfma_f32_16x16x32_bf16 v[28:31], v[158:161], v[210:213], v[28:31]
	v_mfma_f32_16x16x32_bf16 v[24:27], v[170:173], v[210:213], v[24:27]
	v_mfma_f32_16x16x32_bf16 v[12:15], v[158:161], v[218:221], v[12:15]
	v_mfma_f32_16x16x32_bf16 v[8:11], v[170:173], v[218:221], v[8:11]
	v_mfma_f32_16x16x32_bf16 v[52:55], v[174:177], v[190:193], v[52:55]
	v_mfma_f32_16x16x32_bf16 v[48:51], v[182:185], v[190:193], v[48:51]
	v_mfma_f32_16x16x32_bf16 v[36:39], v[174:177], v[198:201], v[36:39]
	v_mfma_f32_16x16x32_bf16 v[32:35], v[182:185], v[198:201], v[32:35]
	v_mfma_f32_16x16x32_bf16 v[20:23], v[174:177], v[206:209], v[20:23]
	v_mfma_f32_16x16x32_bf16 v[16:19], v[182:185], v[206:209], v[16:19]
	v_mfma_f32_16x16x32_bf16 v[4:7], v[174:177], v[214:217], v[4:7]
	v_mfma_f32_16x16x32_bf16 v[0:3], v[182:185], v[214:217], v[0:3]
	v_mfma_f32_16x16x32_bf16 v[52:55], v[178:181], v[194:197], v[52:55]
	v_mfma_f32_16x16x32_bf16 v[48:51], v[186:189], v[194:197], v[48:51]
	v_mfma_f32_16x16x32_bf16 v[36:39], v[178:181], v[202:205], v[36:39]
	v_mfma_f32_16x16x32_bf16 v[32:35], v[186:189], v[202:205], v[32:35]
	v_mfma_f32_16x16x32_bf16 v[20:23], v[178:181], v[210:213], v[20:23]
	v_mfma_f32_16x16x32_bf16 v[16:19], v[186:189], v[210:213], v[16:19]
	v_mfma_f32_16x16x32_bf16 v[4:7], v[178:181], v[218:221], v[4:7]
	v_mfma_f32_16x16x32_bf16 v[0:3], v[186:189], v[218:221], v[0:3]
	s_setprio 0
	s_barrier
	s_add_u32 s10, s10, 0x100
	s_addc_u32 s11, s11, 0
	s_add_u32 s0, s0, 0x100
	s_addc_u32 s1, s1, 0
	s_cmp_ge_i32 s44, s63
	s_mov_b32 s12, s44
	s_cbranch_scc0 .LBB0_501

; #define PG8_STAGE(bufoff, gbase, voff) do { _Pragma("unroll") for (int _i = 0; _i < 2; ++_i) \
;         __builtin_amdgcn_global_load_lds((const unsigned*)((const char*)(gbase) + (voff)[_i]), (PG8_LAS unsigned*)(lds + (bufoff) + ldsw + _i * 8192), 16, 0, 0); } while (0)
; #define PG8_LDA(dst, b, h) do { _Pragma("unroll") for (int m = 0; m < 4; ++m) _Pragma("unroll") for (int k = 0; k < 2; ++k) dst[m][k] = *(const PG8_LAS bf16x8*)(lds + PG8_SA(b, h) + aoff + m * 2048 + k * 1024); } while (0)
; #define PG8_LDB(dst, b, h) do { _Pragma("unroll") for (int n = 0; n < 2; ++n) _Pragma("unroll") for (int k = 0; k < 2; ++k) dst[n][k] = *(const PG8_LAS bf16x8*)(lds + PG8_SB(b, h) + boff + n * 2048 + k * 1024); } while (0)
; #define PG8_MMA(ai, bj, At, Bt) do { __builtin_amdgcn_s_setprio(1); _Pragma("unroll") for (int m = 0; m < 4; ++m) _Pragma("unroll") for (int n = 0; n < 2; ++n) _Pragma("unroll") for (int k = 0; k < 2; ++k) \
;         acc[ai][bj][m][n] = __builtin_amdgcn_mfma_f32_16x16x32_bf16(Bt[n][k], At[m][k], acc[ai][bj][m][n], 0, 0, 0); __builtin_amdgcn_s_setprio(0); } while (0)
; #define PG8_WAIT_V(n) asm volatile("s_waitcnt vmcnt(" #n ")" ::: "memory")
; #define PG8_WAIT_L(n) asm volatile("s_waitcnt lgkmcnt(" #n ")" ::: "memory")
; #define PG8_BAR __builtin_amdgcn_s_barrier()
; #define PG8_SCHED __builtin_amdgcn_sched_barrier(0)
; template <class Epi, class Sched, bool ALIGN_EPI = false, bool SP2 = false>
; __device__ __forceinline__ void gemm_phase(PG8_LAS unsigned char* lds, const Gemm g, const Sched& S, const Epi& E) {
;     ...
;             const bool last = (t == nt - 2);
;             const char* a1 = cA + (size_t)(t + 1) * kstep;
;             const char* a2 = last ? nA : cA + (size_t)(t + 2) * kstep; const char* b2 = last ? nB : cB + (size_t)(t + 2) * kstep;
;             const char* a3 = a2 + kstep; const char* b3 = b2 + kstep;
;             if (last && has_next) S.a_ready(nxt);
;             if constexpr (SP2) {
;             PG8_LDB(B0, 0, 0); PG8_LDB(B1, 0, 1); PG8_SCHED; PG8_LDA(At, 0, 0); PG8_STAGE(PG8_SA(1, 1), a1 + hstep, voffA);
;             PG8_WAIT_V(8); PG8_WAIT_L(0); PG8_BAR; PG8_MMA(0, 0, At, B0); PG8_MMA(0, 1, At, B1); PG8_BAR; PG8_SCHED;
;             PG8_LDA(At, 0, 1); PG8_STAGE(PG8_SB(0, 0), b2, voffB); PG8_STAGE(PG8_SB(0, 1), b2 + hstep, voffB); PG8_STAGE(PG8_SA(0, 0), a2, voffA);
.LBB0_985:
	ds_read_b128 v[128:131], v171
	ds_read_b128 v[132:135], v171 offset:1024
	ds_read_b128 v[162:165], v171 offset:2048
	ds_read_b128 v[166:169], v171 offset:3072
	ds_read_b128 v[176:179], v172
	ds_read_b128 v[180:183], v172 offset:1024
	ds_read_b128 v[184:187], v172 offset:2048
	ds_read_b128 v[188:191], v172 offset:3072
	s_add_i32 s52, s50, 2
	s_add_u32 s53, s8, 0x80
	s_addc_u32 s51, s9, 0
	s_cmp_eq_u32 s69, s50
	s_cselect_b32 s50, s46, s53
	s_cselect_b32 s51, s47, s51
	s_cselect_b32 s91, s49, s1
	s_cselect_b32 s90, s48, s0
	v_lshl_add_u64 v[224:225], s[8:9], 0, v[148:149]
	s_add_i32 m0, s60, 0xc000
	ds_read_b128 v[192:195], v173
	ds_read_b128 v[196:199], v173 offset:1024
	ds_read_b128 v[200:203], v173 offset:2048
	ds_read_b128 v[204:207], v173 offset:3072
	ds_read_b128 v[208:211], v173 offset:4096
	ds_read_b128 v[212:215], v173 offset:5120
	ds_read_b128 v[216:219], v173 offset:6144
	ds_read_b128 v[220:223], v173 offset:7168
	global_load_lds_dwordx4 v[224:225], off
	v_lshl_add_u64 v[224:225], s[8:9], 0, v[150:151]
	s_add_i32 m0, s60, 0xe000
	s_nop 0
	global_load_lds_dwordx4 v[224:225], off
	s_waitcnt vmcnt(8)
	s_waitcnt lgkmcnt(0)
	s_barrier
	s_setprio 1
	s_waitcnt lgkmcnt(0)
	v_mfma_f32_16x16x32_bf16 v[120:123], v[128:131], v[192:195], v[120:123]
	v_mfma_f32_16x16x32_bf16 v[124:127], v[162:165], v[192:195], v[124:127]
	v_mfma_f32_16x16x32_bf16 v[108:111], v[128:131], v[200:203], v[108:111]
	v_mfma_f32_16x16x32_bf16 v[104:107], v[162:165], v[200:203], v[104:107]
	v_mfma_f32_16x16x32_bf16 v[92:95], v[128:131], v[208:211], v[92:95]
	v_mfma_f32_16x16x32_bf16 v[88:91], v[162:165], v[208:211], v[88:91]
	v_mfma_f32_16x16x32_bf16 v[76:79], v[128:131], v[216:219], v[76:79]
	v_mfma_f32_16x16x32_bf16 v[72:75], v[162:165], v[216:219], v[72:75]
	v_mfma_f32_16x16x32_bf16 v[120:123], v[132:135], v[196:199], v[120:123]
	v_mfma_f32_16x16x32_bf16 v[124:127], v[166:169], v[196:199], v[124:127]
	v_mfma_f32_16x16x32_bf16 v[108:111], v[132:135], v[204:207], v[108:111]
	v_mfma_f32_16x16x32_bf16 v[104:107], v[166:169], v[204:207], v[104:107]
	v_mfma_f32_16x16x32_bf16 v[92:95], v[132:135], v[212:215], v[92:95]
	v_mfma_f32_16x16x32_bf16 v[88:91], v[166:169], v[212:215], v[88:91]
	v_mfma_f32_16x16x32_bf16 v[76:79], v[132:135], v[220:223], v[76:79]
	v_mfma_f32_16x16x32_bf16 v[72:75], v[166:169], v[220:223], v[72:75]
	v_mfma_f32_16x16x32_bf16 v[116:119], v[176:179], v[192:195], v[116:119]
	v_mfma_f32_16x16x32_bf16 v[112:115], v[184:187], v[192:195], v[112:115]
	v_mfma_f32_16x16x32_bf16 v[100:103], v[176:179], v[200:203], v[100:103]
	v_mfma_f32_16x16x32_bf16 v[96:99], v[184:187], v[200:203], v[96:99]
	v_mfma_f32_16x16x32_bf16 v[84:87], v[176:179], v[208:211], v[84:87]
	v_mfma_f32_16x16x32_bf16 v[80:83], v[184:187], v[208:211], v[80:83]
	v_mfma_f32_16x16x32_bf16 v[68:71], v[176:179], v[216:219], v[68:71]
	v_mfma_f32_16x16x32_bf16 v[64:67], v[184:187], v[216:219], v[64:67]
	v_mfma_f32_16x16x32_bf16 v[116:119], v[180:183], v[196:199], v[116:119]
	v_mfma_f32_16x16x32_bf16 v[112:115], v[188:191], v[196:199], v[112:115]
	v_mfma_f32_16x16x32_bf16 v[100:103], v[180:183], v[204:207], v[100:103]
	v_mfma_f32_16x16x32_bf16 v[96:99], v[188:191], v[204:207], v[96:99]
	v_mfma_f32_16x16x32_bf16 v[84:87], v[180:183], v[212:215], v[84:87]
	v_mfma_f32_16x16x32_bf16 v[80:83], v[188:191], v[212:215], v[80:83]
	v_mfma_f32_16x16x32_bf16 v[68:71], v[180:183], v[220:223], v[68:71]
	v_mfma_f32_16x16x32_bf16 v[64:67], v[188:191], v[220:223], v[64:67]
	s_setprio 0
	s_barrier
	s_add_i32 s53, s74, s59
	v_lshl_add_u64 v[224:225], s[90:91], 0, v[138:139]
	s_mov_b32 m0, s53
	ds_read_b128 v[192:195], v173 offset:16384
	ds_read_b128 v[196:199], v173 offset:17408
	ds_read_b128 v[200:203], v173 offset:18432
	ds_read_b128 v[204:207], v173 offset:19456
	ds_read_b128 v[208:211], v173 offset:20480
	ds_read_b128 v[212:215], v173 offset:21504
	ds_read_b128 v[216:219], v173 offset:22528
	ds_read_b128 v[220:223], v173 offset:23552
	global_load_lds_dwordx4 v[224:225], off
	s_add_i32 m0, s53, 0x2000
	v_lshl_add_u64 v[226:227], s[90:91], 0, v[142:143]
	s_add_u32 s90, s90, s10
	s_addc_u32 s91, s91, s11
	s_add_i32 s53, s75, s59
	global_load_lds_dwordx4 v[226:227], off
	v_lshl_add_u64 v[228:229], s[90:91], 0, v[138:139]
	s_mov_b32 m0, s53
	v_lshl_add_u64 v[230:231], s[90:91], 0, v[142:143]
	global_load_lds_dwordx4 v[228:229], off
	s_add_i32 m0, s53, 0x2000
	v_lshl_add_u64 v[232:233], s[50:51], 0, v[136:137]
	global_load_lds_dwordx4 v[230:231], off
	s_mov_b32 m0, s60
	v_lshl_add_u64 v[234:235], s[50:51], 0, v[140:141]
	global_load_lds_dwordx4 v[232:233], off
	s_mov_b32 m0, s61
	s_nop 0
	global_load_lds_dwordx4 v[234:235], off
	s_waitcnt vmcnt(8)
	s_waitcnt lgkmcnt(0)
	s_barrier
; #define PG8_STAGE(bufoff, gbase, voff) do { _Pragma("unroll") for (int _i = 0; _i < 2; ++_i) \
;         __builtin_amdgcn_global_load_lds((const unsigned*)((const char*)(gbase) + (voff)[_i]), (PG8_LAS unsigned*)(lds + (bufoff) + ldsw + _i * 8192), 16, 0, 0); } while (0)
; #define PG8_LDA(dst, b, h) do { _Pragma("unroll") for (int m = 0; m < 4; ++m) _Pragma("unroll") for (int k = 0; k < 2; ++k) dst[m][k] = *(const PG8_LAS bf16x8*)(lds + PG8_SA(b, h) + aoff + m * 2048 + k * 1024); } while (0)
; #define PG8_LDB(dst, b, h) do { _Pragma("unroll") for (int n = 0; n < 2; ++n) _Pragma("unroll") for (int k = 0; k < 2; ++k) dst[n][k] = *(const PG8_LAS bf16x8*)(lds + PG8_SB(b, h) + boff + n * 2048 + k * 1024); } while (0)
; #define PG8_MMA(ai, bj, At, Bt) do { __builtin_amdgcn_s_setprio(1); _Pragma("unroll") for (int m = 0; m < 4; ++m) _Pragma("unroll") for (int n = 0; n < 2; ++n) _Pragma("unroll") for (int k = 0; k < 2; ++k) \
;         acc[ai][bj][m][n] = __builtin_amdgcn_mfma_f32_16x16x32_bf16(Bt[n][k], At[m][k], acc[ai][bj][m][n], 0, 0, 0); __builtin_amdgcn_s_setprio(0); } while (0)
; #define PG8_WAIT_V(n) asm volatile("s_waitcnt vmcnt(" #n ")" ::: "memory")
; #define PG8_WAIT_L(n) asm volatile("s_waitcnt lgkmcnt(" #n ")" ::: "memory")
; #define PG8_BAR __builtin_amdgcn_s_barrier()
; #define PG8_SCHED __builtin_amdgcn_sched_barrier(0)
; template <class Epi, class Sched, bool ALIGN_EPI = false, bool SP2 = false>
; __device__ __forceinline__ void gemm_phase(PG8_LAS unsigned char* lds, const Gemm g, const Sched& S, const Epi& E) {
;     ...
;             PG8_WAIT_V(8); PG8_WAIT_L(0); PG8_BAR; PG8_MMA(1, 0, At, B0); PG8_MMA(1, 1, At, B1); PG8_BAR; PG8_SCHED;
;             PG8_LDB(B0, 1, 0); PG8_LDB(B1, 1, 1); PG8_SCHED; PG8_LDA(At, 1, 0); PG8_STAGE(PG8_SA(0, 1), a2 + hstep, voffA);
;             PG8_WAIT_V(8); PG8_WAIT_L(0); PG8_BAR; PG8_MMA(0, 0, At, B0); PG8_MMA(0, 1, At, B1); PG8_BAR; PG8_SCHED;
	s_setprio 1
	s_waitcnt lgkmcnt(0)
	v_mfma_f32_16x16x32_bf16 v[60:63], v[128:131], v[192:195], v[60:63]
	v_mfma_f32_16x16x32_bf16 v[56:59], v[162:165], v[192:195], v[56:59]
	v_mfma_f32_16x16x32_bf16 v[44:47], v[128:131], v[200:203], v[44:47]
	v_mfma_f32_16x16x32_bf16 v[40:43], v[162:165], v[200:203], v[40:43]
	v_mfma_f32_16x16x32_bf16 v[28:31], v[128:131], v[208:211], v[28:31]
	v_mfma_f32_16x16x32_bf16 v[24:27], v[162:165], v[208:211], v[24:27]
	v_mfma_f32_16x16x32_bf16 v[12:15], v[128:131], v[216:219], v[12:15]
	v_mfma_f32_16x16x32_bf16 v[8:11], v[162:165], v[216:219], v[8:11]
	v_mfma_f32_16x16x32_bf16 v[60:63], v[132:135], v[196:199], v[60:63]
	v_mfma_f32_16x16x32_bf16 v[56:59], v[166:169], v[196:199], v[56:59]
	v_mfma_f32_16x16x32_bf16 v[44:47], v[132:135], v[204:207], v[44:47]
	v_mfma_f32_16x16x32_bf16 v[40:43], v[166:169], v[204:207], v[40:43]
	v_mfma_f32_16x16x32_bf16 v[28:31], v[132:135], v[212:215], v[28:31]
	v_mfma_f32_16x16x32_bf16 v[24:27], v[166:169], v[212:215], v[24:27]
	v_mfma_f32_16x16x32_bf16 v[12:15], v[132:135], v[220:223], v[12:15]
	v_mfma_f32_16x16x32_bf16 v[8:11], v[166:169], v[220:223], v[8:11]
	v_mfma_f32_16x16x32_bf16 v[52:55], v[176:179], v[192:195], v[52:55]
	v_mfma_f32_16x16x32_bf16 v[48:51], v[184:187], v[192:195], v[48:51]
	v_mfma_f32_16x16x32_bf16 v[36:39], v[176:179], v[200:203], v[36:39]
	v_mfma_f32_16x16x32_bf16 v[32:35], v[184:187], v[200:203], v[32:35]
	v_mfma_f32_16x16x32_bf16 v[20:23], v[176:179], v[208:211], v[20:23]
	v_mfma_f32_16x16x32_bf16 v[16:19], v[184:187], v[208:211], v[16:19]
	v_mfma_f32_16x16x32_bf16 v[4:7], v[176:179], v[216:219], v[4:7]
	v_mfma_f32_16x16x32_bf16 v[0:3], v[184:187], v[216:219], v[0:3]
	v_mfma_f32_16x16x32_bf16 v[52:55], v[180:183], v[196:199], v[52:55]
	v_mfma_f32_16x16x32_bf16 v[48:51], v[188:191], v[196:199], v[48:51]
	v_mfma_f32_16x16x32_bf16 v[36:39], v[180:183], v[204:207], v[36:39]
	v_mfma_f32_16x16x32_bf16 v[32:35], v[188:191], v[204:207], v[32:35]
	v_mfma_f32_16x16x32_bf16 v[20:23], v[180:183], v[212:215], v[20:23]
	v_mfma_f32_16x16x32_bf16 v[16:19], v[188:191], v[212:215], v[16:19]
	v_mfma_f32_16x16x32_bf16 v[4:7], v[180:183], v[220:223], v[4:7]
	v_mfma_f32_16x16x32_bf16 v[0:3], v[188:191], v[220:223], v[0:3]
	s_setprio 0
	s_barrier
	s_add_i32 s53, 0, 0x18000
	v_add_u32_e32 v144, s53, v155
	s_add_i32 s85, 0, 0x1c000
	ds_read_b128 v[128:131], v144
	ds_read_b128 v[132:135], v144 offset:1024
	ds_read_b128 v[162:165], v144 offset:2048
	ds_read_b128 v[166:169], v144 offset:3072
	v_add_u32_e32 v144, s85, v155
	ds_read_b128 v[176:179], v144
	ds_read_b128 v[180:183], v144 offset:1024
	ds_read_b128 v[184:187], v144 offset:2048
	ds_read_b128 v[188:191], v144 offset:3072
	s_add_u32 s50, s50, s10
	s_addc_u32 s51, s51, s11
	s_mov_b32 m0, s62
	v_lshl_add_u64 v[236:237], s[50:51], 0, v[136:137]
	ds_read_b128 v[192:195], v173 offset:32768
	ds_read_b128 v[196:199], v173 offset:33792
	ds_read_b128 v[200:203], v173 offset:34816
	ds_read_b128 v[204:207], v173 offset:35840
	ds_read_b128 v[208:211], v173 offset:36864
	ds_read_b128 v[212:215], v173 offset:37888
	ds_read_b128 v[216:219], v173 offset:38912
	ds_read_b128 v[220:223], v173 offset:39936
	global_load_lds_dwordx4 v[236:237], off
	v_lshl_add_u64 v[236:237], s[50:51], 0, v[140:141]
	s_mov_b32 m0, s63
	s_nop 0
	global_load_lds_dwordx4 v[236:237], off
	s_waitcnt vmcnt(8)
	s_waitcnt lgkmcnt(0)
	s_barrier
	s_setprio 1
	s_waitcnt lgkmcnt(0)
	v_mfma_f32_16x16x32_bf16 v[120:123], v[128:131], v[192:195], v[120:123]
	v_mfma_f32_16x16x32_bf16 v[124:127], v[162:165], v[192:195], v[124:127]
	v_mfma_f32_16x16x32_bf16 v[108:111], v[128:131], v[200:203], v[108:111]
	v_mfma_f32_16x16x32_bf16 v[104:107], v[162:165], v[200:203], v[104:107]
	v_mfma_f32_16x16x32_bf16 v[92:95], v[128:131], v[208:211], v[92:95]
	v_mfma_f32_16x16x32_bf16 v[88:91], v[162:165], v[208:211], v[88:91]
	v_mfma_f32_16x16x32_bf16 v[76:79], v[128:131], v[216:219], v[76:79]
	v_mfma_f32_16x16x32_bf16 v[72:75], v[162:165], v[216:219], v[72:75]
	v_mfma_f32_16x16x32_bf16 v[120:123], v[132:135], v[196:199], v[120:123]
	v_mfma_f32_16x16x32_bf16 v[124:127], v[166:169], v[196:199], v[124:127]
	v_mfma_f32_16x16x32_bf16 v[108:111], v[132:135], v[204:207], v[108:111]
	v_mfma_f32_16x16x32_bf16 v[104:107], v[166:169], v[204:207], v[104:107]
	v_mfma_f32_16x16x32_bf16 v[92:95], v[132:135], v[212:215], v[92:95]
	v_mfma_f32_16x16x32_bf16 v[88:91], v[166:169], v[212:215], v[88:91]
	v_mfma_f32_16x16x32_bf16 v[76:79], v[132:135], v[220:223], v[76:79]
	v_mfma_f32_16x16x32_bf16 v[72:75], v[166:169], v[220:223], v[72:75]
	v_mfma_f32_16x16x32_bf16 v[116:119], v[176:179], v[192:195], v[116:119]
	v_mfma_f32_16x16x32_bf16 v[112:115], v[184:187], v[192:195], v[112:115]
	v_mfma_f32_16x16x32_bf16 v[100:103], v[176:179], v[200:203], v[100:103]
	v_mfma_f32_16x16x32_bf16 v[96:99], v[184:187], v[200:203], v[96:99]
	v_mfma_f32_16x16x32_bf16 v[84:87], v[176:179], v[208:211], v[84:87]
	v_mfma_f32_16x16x32_bf16 v[80:83], v[184:187], v[208:211], v[80:83]
	v_mfma_f32_16x16x32_bf16 v[68:71], v[176:179], v[216:219], v[68:71]
	v_mfma_f32_16x16x32_bf16 v[64:67], v[184:187], v[216:219], v[64:67]
	v_mfma_f32_16x16x32_bf16 v[116:119], v[180:183], v[196:199], v[116:119]
	v_mfma_f32_16x16x32_bf16 v[112:115], v[188:191], v[196:199], v[112:115]
	v_mfma_f32_16x16x32_bf16 v[100:103], v[180:183], v[204:207], v[100:103]
	v_mfma_f32_16x16x32_bf16 v[96:99], v[188:191], v[204:207], v[96:99]
	v_mfma_f32_16x16x32_bf16 v[84:87], v[180:183], v[212:215], v[84:87]
	v_mfma_f32_16x16x32_bf16 v[80:83], v[188:191], v[212:215], v[80:83]
	v_mfma_f32_16x16x32_bf16 v[68:71], v[180:183], v[220:223], v[68:71]
	v_mfma_f32_16x16x32_bf16 v[64:67], v[188:191], v[220:223], v[64:67]
	s_setprio 0
	s_barrier
; #define PG8_STAGE(bufoff, gbase, voff) do { _Pragma("unroll") for (int _i = 0; _i < 2; ++_i) \
;         __builtin_amdgcn_global_load_lds((const unsigned*)((const char*)(gbase) + (voff)[_i]), (PG8_LAS unsigned*)(lds + (bufoff) + ldsw + _i * 8192), 16, 0, 0); } while (0)
; #define PG8_LDA(dst, b, h) do { _Pragma("unroll") for (int m = 0; m < 4; ++m) _Pragma("unroll") for (int k = 0; k < 2; ++k) dst[m][k] = *(const PG8_LAS bf16x8*)(lds + PG8_SA(b, h) + aoff + m * 2048 + k * 1024); } while (0)
; #define PG8_MMA(ai, bj, At, Bt) do { __builtin_amdgcn_s_setprio(1); _Pragma("unroll") for (int m = 0; m < 4; ++m) _Pragma("unroll") for (int n = 0; n < 2; ++n) _Pragma("unroll") for (int k = 0; k < 2; ++k) \
;         acc[ai][bj][m][n] = __builtin_amdgcn_mfma_f32_16x16x32_bf16(Bt[n][k], At[m][k], acc[ai][bj][m][n], 0, 0, 0); __builtin_amdgcn_s_setprio(0); } while (0)
; #define PG8_WAIT_V(n) asm volatile("s_waitcnt vmcnt(" #n ")" ::: "memory")
; #define PG8_WAIT_L(n) asm volatile("s_waitcnt lgkmcnt(" #n ")" ::: "memory")
; #define PG8_BAR __builtin_amdgcn_s_barrier()
; #define PG8_SCHED __builtin_amdgcn_sched_barrier(0)
; template <class Epi, class Sched, bool ALIGN_EPI = false, bool SP2 = false>
; __device__ __forceinline__ void gemm_phase(PG8_LAS unsigned char* lds, const Gemm g, const Sched& S, const Epi& E) {
;     ...
;         for (int t = 0; t < nt; t += 2) {
;     ...
;             PG8_LDA(At, 1, 1); PG8_STAGE(PG8_SB(1, 0), b3, voffB); PG8_STAGE(PG8_SB(1, 1), b3 + hstep, voffB); PG8_STAGE(PG8_SA(1, 0), a3, voffA);
;             PG8_WAIT_V(8); PG8_WAIT_L(0); PG8_BAR; PG8_MMA(1, 0, At, B0); PG8_MMA(1, 1, At, B1); PG8_BAR; PG8_SCHED;
	s_add_i32 s50, s53, s59
	v_lshl_add_u64 v[224:225], v[224:225], 0, s[24:25]
	s_mov_b32 m0, s50
	ds_read_b128 v[192:195], v173 offset:49152
	ds_read_b128 v[196:199], v173 offset:50176
	ds_read_b128 v[200:203], v173 offset:51200
	ds_read_b128 v[204:207], v173 offset:52224
	ds_read_b128 v[208:211], v173 offset:53248
	ds_read_b128 v[212:215], v173 offset:54272
	ds_read_b128 v[216:219], v173 offset:55296
	ds_read_b128 v[220:223], v173 offset:56320
	global_load_lds_dwordx4 v[224:225], off
	v_lshl_add_u64 v[224:225], v[226:227], 0, s[24:25]
	s_add_i32 m0, s50, 0x2000
	s_add_i32 s50, s85, s59
	global_load_lds_dwordx4 v[224:225], off
	v_lshl_add_u64 v[224:225], v[228:229], 0, s[24:25]
	s_mov_b32 m0, s50
	s_nop 0
	global_load_lds_dwordx4 v[224:225], off
	v_lshl_add_u64 v[224:225], v[230:231], 0, s[24:25]
	s_add_i32 m0, s50, 0x2000
	s_nop 0
	global_load_lds_dwordx4 v[224:225], off
	v_lshl_add_u64 v[224:225], v[232:233], 0, s[24:25]
	s_mov_b32 m0, s67
	s_nop 0
	global_load_lds_dwordx4 v[224:225], off
	v_lshl_add_u64 v[224:225], v[234:235], 0, s[24:25]
	s_mov_b32 m0, s68
	s_nop 0
	global_load_lds_dwordx4 v[224:225], off
	s_waitcnt vmcnt(8)
	s_waitcnt lgkmcnt(0)
	s_barrier
	s_setprio 1
	s_waitcnt lgkmcnt(0)
	v_mfma_f32_16x16x32_bf16 v[60:63], v[128:131], v[192:195], v[60:63]
	v_mfma_f32_16x16x32_bf16 v[56:59], v[162:165], v[192:195], v[56:59]
	v_mfma_f32_16x16x32_bf16 v[44:47], v[128:131], v[200:203], v[44:47]
	v_mfma_f32_16x16x32_bf16 v[40:43], v[162:165], v[200:203], v[40:43]
	v_mfma_f32_16x16x32_bf16 v[28:31], v[128:131], v[208:211], v[28:31]
	v_mfma_f32_16x16x32_bf16 v[24:27], v[162:165], v[208:211], v[24:27]
	v_mfma_f32_16x16x32_bf16 v[12:15], v[128:131], v[216:219], v[12:15]
	v_mfma_f32_16x16x32_bf16 v[8:11], v[162:165], v[216:219], v[8:11]
	v_mfma_f32_16x16x32_bf16 v[60:63], v[132:135], v[196:199], v[60:63]
	v_mfma_f32_16x16x32_bf16 v[56:59], v[166:169], v[196:199], v[56:59]
	v_mfma_f32_16x16x32_bf16 v[44:47], v[132:135], v[204:207], v[44:47]
	v_mfma_f32_16x16x32_bf16 v[40:43], v[166:169], v[204:207], v[40:43]
	v_mfma_f32_16x16x32_bf16 v[28:31], v[132:135], v[212:215], v[28:31]
	v_mfma_f32_16x16x32_bf16 v[24:27], v[166:169], v[212:215], v[24:27]
	v_mfma_f32_16x16x32_bf16 v[12:15], v[132:135], v[220:223], v[12:15]
	v_mfma_f32_16x16x32_bf16 v[8:11], v[166:169], v[220:223], v[8:11]
	v_mfma_f32_16x16x32_bf16 v[52:55], v[176:179], v[192:195], v[52:55]
	v_mfma_f32_16x16x32_bf16 v[48:51], v[184:187], v[192:195], v[48:51]
	v_mfma_f32_16x16x32_bf16 v[36:39], v[176:179], v[200:203], v[36:39]
	v_mfma_f32_16x16x32_bf16 v[32:35], v[184:187], v[200:203], v[32:35]
	v_mfma_f32_16x16x32_bf16 v[20:23], v[176:179], v[208:211], v[20:23]
	v_mfma_f32_16x16x32_bf16 v[16:19], v[184:187], v[208:211], v[16:19]
	v_mfma_f32_16x16x32_bf16 v[4:7], v[176:179], v[216:219], v[4:7]
	v_mfma_f32_16x16x32_bf16 v[0:3], v[184:187], v[216:219], v[0:3]
	v_mfma_f32_16x16x32_bf16 v[52:55], v[180:183], v[196:199], v[52:55]
	v_mfma_f32_16x16x32_bf16 v[48:51], v[188:191], v[196:199], v[48:51]
	v_mfma_f32_16x16x32_bf16 v[36:39], v[180:183], v[204:207], v[36:39]
	v_mfma_f32_16x16x32_bf16 v[32:35], v[188:191], v[204:207], v[32:35]
	v_mfma_f32_16x16x32_bf16 v[20:23], v[180:183], v[212:215], v[20:23]
	v_mfma_f32_16x16x32_bf16 v[16:19], v[188:191], v[212:215], v[16:19]
	v_mfma_f32_16x16x32_bf16 v[4:7], v[180:183], v[220:223], v[4:7]
	v_mfma_f32_16x16x32_bf16 v[0:3], v[188:191], v[220:223], v[0:3]
	s_setprio 0
	s_barrier
	s_add_u32 s8, s8, 0x100
	s_addc_u32 s9, s9, 0
	s_add_u32 s0, s0, 0x100
	s_addc_u32 s1, s1, 0
	s_cmp_ge_i32 s52, s65
	s_mov_b32 s50, s52
	s_cbranch_scc0 .LBB0_985

; #define PG8_STAGE(bufoff, gbase, voff) do { _Pragma("unroll") for (int _i = 0; _i < 2; ++_i) \
;         __builtin_amdgcn_global_load_lds((const unsigned*)((const char*)(gbase) + (voff)[_i]), (PG8_LAS unsigned*)(lds + (bufoff) + ldsw + _i * 8192), 16, 0, 0); } while (0)
; #define PG8_LDA(dst, b, h) do { _Pragma("unroll") for (int m = 0; m < 4; ++m) _Pragma("unroll") for (int k = 0; k < 2; ++k) dst[m][k] = *(const PG8_LAS bf16x8*)(lds + PG8_SA(b, h) + aoff + m * 2048 + k * 1024); } while (0)
; #define PG8_LDB(dst, b, h) do { _Pragma("unroll") for (int n = 0; n < 2; ++n) _Pragma("unroll") for (int k = 0; k < 2; ++k) dst[n][k] = *(const PG8_LAS bf16x8*)(lds + PG8_SB(b, h) + boff + n * 2048 + k * 1024); } while (0)
; #define PG8_MMA(ai, bj, At, Bt) do { __builtin_amdgcn_s_setprio(1); _Pragma("unroll") for (int m = 0; m < 4; ++m) _Pragma("unroll") for (int n = 0; n < 2; ++n) _Pragma("unroll") for (int k = 0; k < 2; ++k) \
;         acc[ai][bj][m][n] = __builtin_amdgcn_mfma_f32_16x16x32_bf16(Bt[n][k], At[m][k], acc[ai][bj][m][n], 0, 0, 0); __builtin_amdgcn_s_setprio(0); } while (0)
; #define PG8_WAIT_V(n) asm volatile("s_waitcnt vmcnt(" #n ")" ::: "memory")
; #define PG8_WAIT_L(n) asm volatile("s_waitcnt lgkmcnt(" #n ")" ::: "memory")
; #define PG8_BAR __builtin_amdgcn_s_barrier()
; #define PG8_SCHED __builtin_amdgcn_sched_barrier(0)
; template <class Epi, class Sched, bool ALIGN_EPI = false, bool SP2 = false>
; __device__ __forceinline__ void gemm_phase(PG8_LAS unsigned char* lds, const Gemm g, const Sched& S, const Epi& E) {
;     ...
;             const bool last = (t == nt - 2);
;             const char* a1 = cA + (size_t)(t + 1) * kstep;
;             const char* a2 = last ? nA : cA + (size_t)(t + 2) * kstep; const char* b2 = last ? nB : cB + (size_t)(t + 2) * kstep;
;             const char* a3 = a2 + kstep; const char* b3 = b2 + kstep;
;             if (last && has_next) S.a_ready(nxt);
;             if constexpr (SP2) {
;             PG8_LDB(B0, 0, 0); PG8_LDB(B1, 0, 1); PG8_SCHED; PG8_LDA(At, 0, 0); PG8_STAGE(PG8_SA(1, 1), a1 + hstep, voffA);
;             PG8_WAIT_V(8); PG8_WAIT_L(0); PG8_BAR; PG8_MMA(0, 0, At, B0); PG8_MMA(0, 1, At, B1); PG8_BAR; PG8_SCHED;
;             PG8_LDA(At, 0, 1); PG8_STAGE(PG8_SB(0, 0), b2, voffB); PG8_STAGE(PG8_SB(0, 1), b2 + hstep, voffB); PG8_STAGE(PG8_SA(0, 0), a2, voffA);
.LBB0_1172:
	ds_read_b128 v[128:131], v174
	ds_read_b128 v[132:135], v174 offset:1024
	ds_read_b128 v[136:139], v174 offset:2048
	ds_read_b128 v[140:143], v174 offset:3072
	ds_read_b128 v[166:169], v175
	ds_read_b128 v[170:173], v175 offset:1024
	ds_read_b128 v[178:181], v175 offset:2048
	ds_read_b128 v[182:185], v175 offset:3072
	s_add_i32 s68, s38, 2
	s_add_u32 s69, s36, 0x80
	s_addc_u32 s39, s37, 0
	s_cmp_eq_u32 s53, s38
	s_cselect_b32 s38, s8, s69
	s_cselect_b32 s39, s9, s39
	s_cselect_b32 s71, s35, s1
	s_cselect_b32 s70, s34, s0
	v_lshl_add_u64 v[218:219], s[36:37], 0, v[158:159]
	s_add_i32 m0, s45, 0xc000
	ds_read_b128 v[186:189], v176
	ds_read_b128 v[190:193], v176 offset:1024
	ds_read_b128 v[194:197], v176 offset:2048
	ds_read_b128 v[198:201], v176 offset:3072
	ds_read_b128 v[202:205], v176 offset:4096
	ds_read_b128 v[206:209], v176 offset:5120
	ds_read_b128 v[210:213], v176 offset:6144
	ds_read_b128 v[214:217], v176 offset:7168
	global_load_lds_dwordx4 v[218:219], off
	v_lshl_add_u64 v[218:219], s[36:37], 0, v[160:161]
	s_add_i32 m0, s45, 0xe000
	s_nop 0
	global_load_lds_dwordx4 v[218:219], off
	s_waitcnt vmcnt(8)
	s_waitcnt lgkmcnt(0)
	s_barrier
	s_setprio 1
	s_waitcnt lgkmcnt(0)
	v_mfma_f32_16x16x32_bf16 v[120:123], v[128:131], v[186:189], v[120:123]
	v_mfma_f32_16x16x32_bf16 v[124:127], v[136:139], v[186:189], v[124:127]
	v_mfma_f32_16x16x32_bf16 v[108:111], v[128:131], v[194:197], v[108:111]
	v_mfma_f32_16x16x32_bf16 v[104:107], v[136:139], v[194:197], v[104:107]
	v_mfma_f32_16x16x32_bf16 v[92:95], v[128:131], v[202:205], v[92:95]
	v_mfma_f32_16x16x32_bf16 v[88:91], v[136:139], v[202:205], v[88:91]
	v_mfma_f32_16x16x32_bf16 v[76:79], v[128:131], v[210:213], v[76:79]
	v_mfma_f32_16x16x32_bf16 v[72:75], v[136:139], v[210:213], v[72:75]
	v_mfma_f32_16x16x32_bf16 v[120:123], v[132:135], v[190:193], v[120:123]
	v_mfma_f32_16x16x32_bf16 v[124:127], v[140:143], v[190:193], v[124:127]
	v_mfma_f32_16x16x32_bf16 v[108:111], v[132:135], v[198:201], v[108:111]
	v_mfma_f32_16x16x32_bf16 v[104:107], v[140:143], v[198:201], v[104:107]
	v_mfma_f32_16x16x32_bf16 v[92:95], v[132:135], v[206:209], v[92:95]
	v_mfma_f32_16x16x32_bf16 v[88:91], v[140:143], v[206:209], v[88:91]
	v_mfma_f32_16x16x32_bf16 v[76:79], v[132:135], v[214:217], v[76:79]
	v_mfma_f32_16x16x32_bf16 v[72:75], v[140:143], v[214:217], v[72:75]
	v_mfma_f32_16x16x32_bf16 v[116:119], v[166:169], v[186:189], v[116:119]
	v_mfma_f32_16x16x32_bf16 v[112:115], v[178:181], v[186:189], v[112:115]
	v_mfma_f32_16x16x32_bf16 v[100:103], v[166:169], v[194:197], v[100:103]
	v_mfma_f32_16x16x32_bf16 v[96:99], v[178:181], v[194:197], v[96:99]
	v_mfma_f32_16x16x32_bf16 v[84:87], v[166:169], v[202:205], v[84:87]
	v_mfma_f32_16x16x32_bf16 v[80:83], v[178:181], v[202:205], v[80:83]
	v_mfma_f32_16x16x32_bf16 v[68:71], v[166:169], v[210:213], v[68:71]
	v_mfma_f32_16x16x32_bf16 v[64:67], v[178:181], v[210:213], v[64:67]
	v_mfma_f32_16x16x32_bf16 v[116:119], v[170:173], v[190:193], v[116:119]
	v_mfma_f32_16x16x32_bf16 v[112:115], v[182:185], v[190:193], v[112:115]
	v_mfma_f32_16x16x32_bf16 v[100:103], v[170:173], v[198:201], v[100:103]
	v_mfma_f32_16x16x32_bf16 v[96:99], v[182:185], v[198:201], v[96:99]
	v_mfma_f32_16x16x32_bf16 v[84:87], v[170:173], v[206:209], v[84:87]
	v_mfma_f32_16x16x32_bf16 v[80:83], v[182:185], v[206:209], v[80:83]
	v_mfma_f32_16x16x32_bf16 v[68:71], v[170:173], v[214:217], v[68:71]
	v_mfma_f32_16x16x32_bf16 v[64:67], v[182:185], v[214:217], v[64:67]
	s_setprio 0
	s_barrier
	s_add_i32 s69, s58, s44
	v_lshl_add_u64 v[218:219], s[70:71], 0, v[146:147]
	s_mov_b32 m0, s69
	ds_read_b128 v[186:189], v176 offset:16384
	ds_read_b128 v[190:193], v176 offset:17408
	ds_read_b128 v[194:197], v176 offset:18432
	ds_read_b128 v[198:201], v176 offset:19456
	ds_read_b128 v[202:205], v176 offset:20480
	ds_read_b128 v[206:209], v176 offset:21504
	ds_read_b128 v[210:213], v176 offset:22528
	ds_read_b128 v[214:217], v176 offset:23552
	global_load_lds_dwordx4 v[218:219], off
	s_add_i32 m0, s69, 0x2000
	v_lshl_add_u64 v[220:221], s[70:71], 0, v[150:151]
	s_add_u32 s70, s70, s10
	s_addc_u32 s71, s71, s11
	s_add_i32 s69, s59, s44
	global_load_lds_dwordx4 v[220:221], off
	v_lshl_add_u64 v[222:223], s[70:71], 0, v[146:147]
	s_mov_b32 m0, s69
	v_lshl_add_u64 v[224:225], s[70:71], 0, v[150:151]
	global_load_lds_dwordx4 v[222:223], off
	s_add_i32 m0, s69, 0x2000
	v_lshl_add_u64 v[226:227], s[38:39], 0, v[144:145]
	global_load_lds_dwordx4 v[224:225], off
	s_mov_b32 m0, s45
	v_lshl_add_u64 v[228:229], s[38:39], 0, v[148:149]
	global_load_lds_dwordx4 v[226:227], off
	s_mov_b32 m0, s46
	s_nop 0
	global_load_lds_dwordx4 v[228:229], off
	s_waitcnt vmcnt(8)
	s_waitcnt lgkmcnt(0)
	s_barrier
; #define PG8_STAGE(bufoff, gbase, voff) do { _Pragma("unroll") for (int _i = 0; _i < 2; ++_i) \
;         __builtin_amdgcn_global_load_lds((const unsigned*)((const char*)(gbase) + (voff)[_i]), (PG8_LAS unsigned*)(lds + (bufoff) + ldsw + _i * 8192), 16, 0, 0); } while (0)
; #define PG8_LDA(dst, b, h) do { _Pragma("unroll") for (int m = 0; m < 4; ++m) _Pragma("unroll") for (int k = 0; k < 2; ++k) dst[m][k] = *(const PG8_LAS bf16x8*)(lds + PG8_SA(b, h) + aoff + m * 2048 + k * 1024); } while (0)
; #define PG8_LDB(dst, b, h) do { _Pragma("unroll") for (int n = 0; n < 2; ++n) _Pragma("unroll") for (int k = 0; k < 2; ++k) dst[n][k] = *(const PG8_LAS bf16x8*)(lds + PG8_SB(b, h) + boff + n * 2048 + k * 1024); } while (0)
; #define PG8_MMA(ai, bj, At, Bt) do { __builtin_amdgcn_s_setprio(1); _Pragma("unroll") for (int m = 0; m < 4; ++m) _Pragma("unroll") for (int n = 0; n < 2; ++n) _Pragma("unroll") for (int k = 0; k < 2; ++k) \
;         acc[ai][bj][m][n] = __builtin_amdgcn_mfma_f32_16x16x32_bf16(Bt[n][k], At[m][k], acc[ai][bj][m][n], 0, 0, 0); __builtin_amdgcn_s_setprio(0); } while (0)
; #define PG8_WAIT_V(n) asm volatile("s_waitcnt vmcnt(" #n ")" ::: "memory")
; #define PG8_WAIT_L(n) asm volatile("s_waitcnt lgkmcnt(" #n ")" ::: "memory")
; #define PG8_BAR __builtin_amdgcn_s_barrier()
; #define PG8_SCHED __builtin_amdgcn_sched_barrier(0)
; template <class Epi, class Sched, bool ALIGN_EPI = false, bool SP2 = false>
; __device__ __forceinline__ void gemm_phase(PG8_LAS unsigned char* lds, const Gemm g, const Sched& S, const Epi& E) {
;     ...
;             PG8_WAIT_V(8); PG8_WAIT_L(0); PG8_BAR; PG8_MMA(1, 0, At, B0); PG8_MMA(1, 1, At, B1); PG8_BAR; PG8_SCHED;
;             PG8_LDB(B0, 1, 0); PG8_LDB(B1, 1, 1); PG8_SCHED; PG8_LDA(At, 1, 0); PG8_STAGE(PG8_SA(0, 1), a2 + hstep, voffA);
;             PG8_WAIT_V(8); PG8_WAIT_L(0); PG8_BAR; PG8_MMA(0, 0, At, B0); PG8_MMA(0, 1, At, B1); PG8_BAR; PG8_SCHED;
	s_setprio 1
	s_waitcnt lgkmcnt(0)
	v_mfma_f32_16x16x32_bf16 v[60:63], v[128:131], v[186:189], v[60:63]
	v_mfma_f32_16x16x32_bf16 v[56:59], v[136:139], v[186:189], v[56:59]
	v_mfma_f32_16x16x32_bf16 v[44:47], v[128:131], v[194:197], v[44:47]
	v_mfma_f32_16x16x32_bf16 v[40:43], v[136:139], v[194:197], v[40:43]
	v_mfma_f32_16x16x32_bf16 v[28:31], v[128:131], v[202:205], v[28:31]
	v_mfma_f32_16x16x32_bf16 v[24:27], v[136:139], v[202:205], v[24:27]
	v_mfma_f32_16x16x32_bf16 v[12:15], v[128:131], v[210:213], v[12:15]
	v_mfma_f32_16x16x32_bf16 v[8:11], v[136:139], v[210:213], v[8:11]
	v_mfma_f32_16x16x32_bf16 v[60:63], v[132:135], v[190:193], v[60:63]
	v_mfma_f32_16x16x32_bf16 v[56:59], v[140:143], v[190:193], v[56:59]
	v_mfma_f32_16x16x32_bf16 v[44:47], v[132:135], v[198:201], v[44:47]
	v_mfma_f32_16x16x32_bf16 v[40:43], v[140:143], v[198:201], v[40:43]
	v_mfma_f32_16x16x32_bf16 v[28:31], v[132:135], v[206:209], v[28:31]
	v_mfma_f32_16x16x32_bf16 v[24:27], v[140:143], v[206:209], v[24:27]
	v_mfma_f32_16x16x32_bf16 v[12:15], v[132:135], v[214:217], v[12:15]
	v_mfma_f32_16x16x32_bf16 v[8:11], v[140:143], v[214:217], v[8:11]
	v_mfma_f32_16x16x32_bf16 v[52:55], v[166:169], v[186:189], v[52:55]
	v_mfma_f32_16x16x32_bf16 v[48:51], v[178:181], v[186:189], v[48:51]
	v_mfma_f32_16x16x32_bf16 v[36:39], v[166:169], v[194:197], v[36:39]
	v_mfma_f32_16x16x32_bf16 v[32:35], v[178:181], v[194:197], v[32:35]
	v_mfma_f32_16x16x32_bf16 v[20:23], v[166:169], v[202:205], v[20:23]
	v_mfma_f32_16x16x32_bf16 v[16:19], v[178:181], v[202:205], v[16:19]
	v_mfma_f32_16x16x32_bf16 v[4:7], v[166:169], v[210:213], v[4:7]
	v_mfma_f32_16x16x32_bf16 v[0:3], v[178:181], v[210:213], v[0:3]
	v_mfma_f32_16x16x32_bf16 v[52:55], v[170:173], v[190:193], v[52:55]
	v_mfma_f32_16x16x32_bf16 v[48:51], v[182:185], v[190:193], v[48:51]
	v_mfma_f32_16x16x32_bf16 v[36:39], v[170:173], v[198:201], v[36:39]
	v_mfma_f32_16x16x32_bf16 v[32:35], v[182:185], v[198:201], v[32:35]
	v_mfma_f32_16x16x32_bf16 v[20:23], v[170:173], v[206:209], v[20:23]
	v_mfma_f32_16x16x32_bf16 v[16:19], v[182:185], v[206:209], v[16:19]
	v_mfma_f32_16x16x32_bf16 v[4:7], v[170:173], v[214:217], v[4:7]
	v_mfma_f32_16x16x32_bf16 v[0:3], v[182:185], v[214:217], v[0:3]
	s_setprio 0
	s_barrier
	s_add_i32 s69, 0, 0x18000
	s_add_i32 s70, 0, 0x1c000
	v_add_u32_e32 v140, s69, v155
	v_add_u32_e32 v177, s70, v155
	ds_read_b128 v[128:131], v140
	ds_read_b128 v[132:135], v140 offset:1024
	ds_read_b128 v[136:139], v140 offset:2048
	ds_read_b128 v[140:143], v140 offset:3072
	ds_read_b128 v[166:169], v177
	ds_read_b128 v[170:173], v177 offset:1024
	ds_read_b128 v[178:181], v177 offset:2048
	ds_read_b128 v[182:185], v177 offset:3072
	s_add_u32 s38, s38, s10
	s_addc_u32 s39, s39, s11
	s_mov_b32 m0, s47
	v_lshl_add_u64 v[230:231], s[38:39], 0, v[144:145]
	ds_read_b128 v[186:189], v176 offset:32768
	ds_read_b128 v[190:193], v176 offset:33792
	ds_read_b128 v[194:197], v176 offset:34816
	ds_read_b128 v[198:201], v176 offset:35840
	ds_read_b128 v[202:205], v176 offset:36864
	ds_read_b128 v[206:209], v176 offset:37888
	ds_read_b128 v[210:213], v176 offset:38912
	ds_read_b128 v[214:217], v176 offset:39936
	global_load_lds_dwordx4 v[230:231], off
	v_lshl_add_u64 v[230:231], s[38:39], 0, v[148:149]
	s_mov_b32 m0, s48
	s_nop 0
	global_load_lds_dwordx4 v[230:231], off
	s_waitcnt vmcnt(8)
	s_waitcnt lgkmcnt(0)
	s_barrier
	s_setprio 1
	s_waitcnt lgkmcnt(0)
	v_mfma_f32_16x16x32_bf16 v[120:123], v[128:131], v[186:189], v[120:123]
	v_mfma_f32_16x16x32_bf16 v[124:127], v[136:139], v[186:189], v[124:127]
	v_mfma_f32_16x16x32_bf16 v[108:111], v[128:131], v[194:197], v[108:111]
	v_mfma_f32_16x16x32_bf16 v[104:107], v[136:139], v[194:197], v[104:107]
	v_mfma_f32_16x16x32_bf16 v[92:95], v[128:131], v[202:205], v[92:95]
	v_mfma_f32_16x16x32_bf16 v[88:91], v[136:139], v[202:205], v[88:91]
	v_mfma_f32_16x16x32_bf16 v[76:79], v[128:131], v[210:213], v[76:79]
	v_mfma_f32_16x16x32_bf16 v[72:75], v[136:139], v[210:213], v[72:75]
	v_mfma_f32_16x16x32_bf16 v[120:123], v[132:135], v[190:193], v[120:123]
	v_mfma_f32_16x16x32_bf16 v[124:127], v[140:143], v[190:193], v[124:127]
	v_mfma_f32_16x16x32_bf16 v[108:111], v[132:135], v[198:201], v[108:111]
	v_mfma_f32_16x16x32_bf16 v[104:107], v[140:143], v[198:201], v[104:107]
	v_mfma_f32_16x16x32_bf16 v[92:95], v[132:135], v[206:209], v[92:95]
	v_mfma_f32_16x16x32_bf16 v[88:91], v[140:143], v[206:209], v[88:91]
	v_mfma_f32_16x16x32_bf16 v[76:79], v[132:135], v[214:217], v[76:79]
	v_mfma_f32_16x16x32_bf16 v[72:75], v[140:143], v[214:217], v[72:75]
	v_mfma_f32_16x16x32_bf16 v[116:119], v[166:169], v[186:189], v[116:119]
	v_mfma_f32_16x16x32_bf16 v[112:115], v[178:181], v[186:189], v[112:115]
	v_mfma_f32_16x16x32_bf16 v[100:103], v[166:169], v[194:197], v[100:103]
	v_mfma_f32_16x16x32_bf16 v[96:99], v[178:181], v[194:197], v[96:99]
	v_mfma_f32_16x16x32_bf16 v[84:87], v[166:169], v[202:205], v[84:87]
	v_mfma_f32_16x16x32_bf16 v[80:83], v[178:181], v[202:205], v[80:83]
	v_mfma_f32_16x16x32_bf16 v[68:71], v[166:169], v[210:213], v[68:71]
	v_mfma_f32_16x16x32_bf16 v[64:67], v[178:181], v[210:213], v[64:67]
	v_mfma_f32_16x16x32_bf16 v[116:119], v[170:173], v[190:193], v[116:119]
	v_mfma_f32_16x16x32_bf16 v[112:115], v[182:185], v[190:193], v[112:115]
	v_mfma_f32_16x16x32_bf16 v[100:103], v[170:173], v[198:201], v[100:103]
	v_mfma_f32_16x16x32_bf16 v[96:99], v[182:185], v[198:201], v[96:99]
	v_mfma_f32_16x16x32_bf16 v[84:87], v[170:173], v[206:209], v[84:87]
	v_mfma_f32_16x16x32_bf16 v[80:83], v[182:185], v[206:209], v[80:83]
	v_mfma_f32_16x16x32_bf16 v[68:71], v[170:173], v[214:217], v[68:71]
	v_mfma_f32_16x16x32_bf16 v[64:67], v[182:185], v[214:217], v[64:67]
	s_setprio 0
	s_barrier
; #define PG8_STAGE(bufoff, gbase, voff) do { _Pragma("unroll") for (int _i = 0; _i < 2; ++_i) \
;         __builtin_amdgcn_global_load_lds((const unsigned*)((const char*)(gbase) + (voff)[_i]), (PG8_LAS unsigned*)(lds + (bufoff) + ldsw + _i * 8192), 16, 0, 0); } while (0)
; #define PG8_LDA(dst, b, h) do { _Pragma("unroll") for (int m = 0; m < 4; ++m) _Pragma("unroll") for (int k = 0; k < 2; ++k) dst[m][k] = *(const PG8_LAS bf16x8*)(lds + PG8_SA(b, h) + aoff + m * 2048 + k * 1024); } while (0)
; #define PG8_MMA(ai, bj, At, Bt) do { __builtin_amdgcn_s_setprio(1); _Pragma("unroll") for (int m = 0; m < 4; ++m) _Pragma("unroll") for (int n = 0; n < 2; ++n) _Pragma("unroll") for (int k = 0; k < 2; ++k) \
;         acc[ai][bj][m][n] = __builtin_amdgcn_mfma_f32_16x16x32_bf16(Bt[n][k], At[m][k], acc[ai][bj][m][n], 0, 0, 0); __builtin_amdgcn_s_setprio(0); } while (0)
; #define PG8_WAIT_V(n) asm volatile("s_waitcnt vmcnt(" #n ")" ::: "memory")
; #define PG8_WAIT_L(n) asm volatile("s_waitcnt lgkmcnt(" #n ")" ::: "memory")
; #define PG8_BAR __builtin_amdgcn_s_barrier()
; #define PG8_SCHED __builtin_amdgcn_sched_barrier(0)
; template <class Epi, class Sched, bool ALIGN_EPI = false, bool SP2 = false>
; __device__ __forceinline__ void gemm_phase(PG8_LAS unsigned char* lds, const Gemm g, const Sched& S, const Epi& E) {
;     ...
;         for (int t = 0; t < nt; t += 2) {
;     ...
;             PG8_LDA(At, 1, 1); PG8_STAGE(PG8_SB(1, 0), b3, voffB); PG8_STAGE(PG8_SB(1, 1), b3 + hstep, voffB); PG8_STAGE(PG8_SA(1, 0), a3, voffA);
;             PG8_WAIT_V(8); PG8_WAIT_L(0); PG8_BAR; PG8_MMA(1, 0, At, B0); PG8_MMA(1, 1, At, B1); PG8_BAR; PG8_SCHED;
	s_add_i32 s38, s69, s44
	v_lshl_add_u64 v[218:219], v[218:219], 0, s[18:19]
	s_mov_b32 m0, s38
	ds_read_b128 v[186:189], v176 offset:49152
	ds_read_b128 v[190:193], v176 offset:50176
	ds_read_b128 v[194:197], v176 offset:51200
	ds_read_b128 v[198:201], v176 offset:52224
	ds_read_b128 v[202:205], v176 offset:53248
	ds_read_b128 v[206:209], v176 offset:54272
	ds_read_b128 v[210:213], v176 offset:55296
	ds_read_b128 v[214:217], v176 offset:56320
	global_load_lds_dwordx4 v[218:219], off
	v_lshl_add_u64 v[218:219], v[220:221], 0, s[18:19]
	s_add_i32 m0, s38, 0x2000
	s_add_i32 s38, s70, s44
	global_load_lds_dwordx4 v[218:219], off
	v_lshl_add_u64 v[218:219], v[222:223], 0, s[18:19]
	s_mov_b32 m0, s38
	s_nop 0
	global_load_lds_dwordx4 v[218:219], off
	v_lshl_add_u64 v[218:219], v[224:225], 0, s[18:19]
	s_add_i32 m0, s38, 0x2000
	s_nop 0
	global_load_lds_dwordx4 v[218:219], off
	v_lshl_add_u64 v[218:219], v[226:227], 0, s[18:19]
	s_mov_b32 m0, s50
	s_nop 0
	global_load_lds_dwordx4 v[218:219], off
	v_lshl_add_u64 v[218:219], v[228:229], 0, s[18:19]
	s_mov_b32 m0, s51
	s_nop 0
	global_load_lds_dwordx4 v[218:219], off
	s_waitcnt vmcnt(8)
	s_waitcnt lgkmcnt(0)
	s_barrier
	s_setprio 1
	s_waitcnt lgkmcnt(0)
	v_mfma_f32_16x16x32_bf16 v[60:63], v[128:131], v[186:189], v[60:63]
	v_mfma_f32_16x16x32_bf16 v[56:59], v[136:139], v[186:189], v[56:59]
	v_mfma_f32_16x16x32_bf16 v[44:47], v[128:131], v[194:197], v[44:47]
	v_mfma_f32_16x16x32_bf16 v[40:43], v[136:139], v[194:197], v[40:43]
	v_mfma_f32_16x16x32_bf16 v[28:31], v[128:131], v[202:205], v[28:31]
	v_mfma_f32_16x16x32_bf16 v[24:27], v[136:139], v[202:205], v[24:27]
	v_mfma_f32_16x16x32_bf16 v[12:15], v[128:131], v[210:213], v[12:15]
	v_mfma_f32_16x16x32_bf16 v[8:11], v[136:139], v[210:213], v[8:11]
	v_mfma_f32_16x16x32_bf16 v[60:63], v[132:135], v[190:193], v[60:63]
	v_mfma_f32_16x16x32_bf16 v[56:59], v[140:143], v[190:193], v[56:59]
	v_mfma_f32_16x16x32_bf16 v[44:47], v[132:135], v[198:201], v[44:47]
	v_mfma_f32_16x16x32_bf16 v[40:43], v[140:143], v[198:201], v[40:43]
	v_mfma_f32_16x16x32_bf16 v[28:31], v[132:135], v[206:209], v[28:31]
	v_mfma_f32_16x16x32_bf16 v[24:27], v[140:143], v[206:209], v[24:27]
	v_mfma_f32_16x16x32_bf16 v[12:15], v[132:135], v[214:217], v[12:15]
	v_mfma_f32_16x16x32_bf16 v[8:11], v[140:143], v[214:217], v[8:11]
	v_mfma_f32_16x16x32_bf16 v[52:55], v[166:169], v[186:189], v[52:55]
	v_mfma_f32_16x16x32_bf16 v[48:51], v[178:181], v[186:189], v[48:51]
	v_mfma_f32_16x16x32_bf16 v[36:39], v[166:169], v[194:197], v[36:39]
	v_mfma_f32_16x16x32_bf16 v[32:35], v[178:181], v[194:197], v[32:35]
	v_mfma_f32_16x16x32_bf16 v[20:23], v[166:169], v[202:205], v[20:23]
	v_mfma_f32_16x16x32_bf16 v[16:19], v[178:181], v[202:205], v[16:19]
	v_mfma_f32_16x16x32_bf16 v[4:7], v[166:169], v[210:213], v[4:7]
	v_mfma_f32_16x16x32_bf16 v[0:3], v[178:181], v[210:213], v[0:3]
	v_mfma_f32_16x16x32_bf16 v[52:55], v[170:173], v[190:193], v[52:55]
	v_mfma_f32_16x16x32_bf16 v[48:51], v[182:185], v[190:193], v[48:51]
	v_mfma_f32_16x16x32_bf16 v[36:39], v[170:173], v[198:201], v[36:39]
	v_mfma_f32_16x16x32_bf16 v[32:35], v[182:185], v[198:201], v[32:35]
	v_mfma_f32_16x16x32_bf16 v[20:23], v[170:173], v[206:209], v[20:23]
	v_mfma_f32_16x16x32_bf16 v[16:19], v[182:185], v[206:209], v[16:19]
	v_mfma_f32_16x16x32_bf16 v[4:7], v[170:173], v[214:217], v[4:7]
	v_mfma_f32_16x16x32_bf16 v[0:3], v[182:185], v[214:217], v[0:3]
	s_setprio 0
	s_barrier
	s_add_u32 s36, s36, 0x100
	s_addc_u32 s37, s37, 0
	s_add_u32 s0, s0, 0x100
	s_addc_u32 s1, s1, 0
	s_cmp_ge_i32 s68, s52
	s_mov_b32 s38, s68
	s_cbranch_scc0 .LBB0_1172

; #define PG8_STAGE(bufoff, gbase, voff) do { _Pragma("unroll") for (int _i = 0; _i < 2; ++_i) \
;         __builtin_amdgcn_global_load_lds((const unsigned*)((const char*)(gbase) + (voff)[_i]), (PG8_LAS unsigned*)(lds + (bufoff) + ldsw + _i * 8192), 16, 0, 0); } while (0)
; #define PG8_LDA(dst, b, h) do { _Pragma("unroll") for (int m = 0; m < 4; ++m) _Pragma("unroll") for (int k = 0; k < 2; ++k) dst[m][k] = *(const PG8_LAS bf16x8*)(lds + PG8_SA(b, h) + aoff + m * 2048 + k * 1024); } while (0)
; #define PG8_LDB(dst, b, h) do { _Pragma("unroll") for (int n = 0; n < 2; ++n) _Pragma("unroll") for (int k = 0; k < 2; ++k) dst[n][k] = *(const PG8_LAS bf16x8*)(lds + PG8_SB(b, h) + boff + n * 2048 + k * 1024); } while (0)
; #define PG8_MMA(ai, bj, At, Bt) do { __builtin_amdgcn_s_setprio(1); _Pragma("unroll") for (int m = 0; m < 4; ++m) _Pragma("unroll") for (int n = 0; n < 2; ++n) _Pragma("unroll") for (int k = 0; k < 2; ++k) \
;         acc[ai][bj][m][n] = __builtin_amdgcn_mfma_f32_16x16x32_bf16(Bt[n][k], At[m][k], acc[ai][bj][m][n], 0, 0, 0); __builtin_amdgcn_s_setprio(0); } while (0)
; #define PG8_WAIT_V(n) asm volatile("s_waitcnt vmcnt(" #n ")" ::: "memory")
; #define PG8_WAIT_L(n) asm volatile("s_waitcnt lgkmcnt(" #n ")" ::: "memory")
; #define PG8_BAR __builtin_amdgcn_s_barrier()
; #define PG8_SCHED __builtin_amdgcn_sched_barrier(0)
; template <class Epi, class Sched, bool ALIGN_EPI = false, bool SP2 = false>
; __device__ __forceinline__ void gemm_phase(PG8_LAS unsigned char* lds, const Gemm g, const Sched& S, const Epi& E) {
;     ...
;             const bool last = (t == nt - 2);
;             const char* a1 = cA + (size_t)(t + 1) * kstep;
;             const char* a2 = last ? nA : cA + (size_t)(t + 2) * kstep; const char* b2 = last ? nB : cB + (size_t)(t + 2) * kstep;
;             const char* a3 = a2 + kstep; const char* b3 = b2 + kstep;
;             if (last && has_next) S.a_ready(nxt);
;             if constexpr (SP2) {
;             PG8_LDB(B0, 0, 0); PG8_LDB(B1, 0, 1); PG8_SCHED; PG8_LDA(At, 0, 0); PG8_STAGE(PG8_SA(1, 1), a1 + hstep, voffA);
;             PG8_WAIT_V(8); PG8_WAIT_L(0); PG8_BAR; PG8_MMA(0, 0, At, B0); PG8_MMA(0, 1, At, B1); PG8_BAR; PG8_SCHED;
;             PG8_LDA(At, 0, 1); PG8_STAGE(PG8_SB(0, 0), b2, voffB); PG8_STAGE(PG8_SB(0, 1), b2 + hstep, voffB); PG8_STAGE(PG8_SA(0, 0), a2, voffA);
.LBB0_1259:
	ds_read_b128 v[144:147], v155
	ds_read_b128 v[160:163], v155 offset:1024
	ds_read_b128 v[164:167], v155 offset:2048
	ds_read_b128 v[168:171], v155 offset:3072
	ds_read_b128 v[172:175], v157
	ds_read_b128 v[176:179], v157 offset:1024
	ds_read_b128 v[180:183], v157 offset:2048
	ds_read_b128 v[184:187], v157 offset:3072
	s_add_i32 s74, s48, 2
	s_add_u32 s75, s46, 0x80
	s_addc_u32 s49, s47, 0
	s_cmp_eq_u32 s65, s48
	s_cselect_b32 s48, s8, s75
	s_cselect_b32 s49, s9, s49
	s_cselect_b32 s77, s45, s1
	s_cselect_b32 s76, s44, s0
	v_lshl_add_u64 v[148:149], s[46:47], 0, v[136:137]
	s_add_i32 m0, s55, 0xc000
	ds_read_b128 v[188:191], v158
	ds_read_b128 v[192:195], v158 offset:1024
	ds_read_b128 v[196:199], v158 offset:2048
	ds_read_b128 v[200:203], v158 offset:3072
	ds_read_b128 v[204:207], v158 offset:4096
	ds_read_b128 v[208:211], v158 offset:5120
	ds_read_b128 v[212:215], v158 offset:6144
	ds_read_b128 v[216:219], v158 offset:7168
	global_load_lds_dwordx4 v[148:149], off
	v_lshl_add_u64 v[148:149], s[46:47], 0, v[138:139]
	s_add_i32 m0, s55, 0xe000
	s_nop 0
	global_load_lds_dwordx4 v[148:149], off
	s_waitcnt vmcnt(8)
	s_waitcnt lgkmcnt(0)
	s_barrier
	s_setprio 1
	s_waitcnt lgkmcnt(0)
	v_mfma_f32_16x16x32_bf16 v[120:123], v[144:147], v[188:191], v[120:123]
	v_mfma_f32_16x16x32_bf16 v[124:127], v[164:167], v[188:191], v[124:127]
	v_mfma_f32_16x16x32_bf16 v[108:111], v[144:147], v[196:199], v[108:111]
	v_mfma_f32_16x16x32_bf16 v[104:107], v[164:167], v[196:199], v[104:107]
	v_mfma_f32_16x16x32_bf16 v[92:95], v[144:147], v[204:207], v[92:95]
	v_mfma_f32_16x16x32_bf16 v[88:91], v[164:167], v[204:207], v[88:91]
	v_mfma_f32_16x16x32_bf16 v[76:79], v[144:147], v[212:215], v[76:79]
	v_mfma_f32_16x16x32_bf16 v[72:75], v[164:167], v[212:215], v[72:75]
	v_mfma_f32_16x16x32_bf16 v[120:123], v[160:163], v[192:195], v[120:123]
	v_mfma_f32_16x16x32_bf16 v[124:127], v[168:171], v[192:195], v[124:127]
	v_mfma_f32_16x16x32_bf16 v[108:111], v[160:163], v[200:203], v[108:111]
	v_mfma_f32_16x16x32_bf16 v[104:107], v[168:171], v[200:203], v[104:107]
	v_mfma_f32_16x16x32_bf16 v[92:95], v[160:163], v[208:211], v[92:95]
	v_mfma_f32_16x16x32_bf16 v[88:91], v[168:171], v[208:211], v[88:91]
	v_mfma_f32_16x16x32_bf16 v[76:79], v[160:163], v[216:219], v[76:79]
	v_mfma_f32_16x16x32_bf16 v[72:75], v[168:171], v[216:219], v[72:75]
	v_mfma_f32_16x16x32_bf16 v[116:119], v[172:175], v[188:191], v[116:119]
	v_mfma_f32_16x16x32_bf16 v[112:115], v[180:183], v[188:191], v[112:115]
	v_mfma_f32_16x16x32_bf16 v[100:103], v[172:175], v[196:199], v[100:103]
	v_mfma_f32_16x16x32_bf16 v[96:99], v[180:183], v[196:199], v[96:99]
	v_mfma_f32_16x16x32_bf16 v[84:87], v[172:175], v[204:207], v[84:87]
	v_mfma_f32_16x16x32_bf16 v[80:83], v[180:183], v[204:207], v[80:83]
	v_mfma_f32_16x16x32_bf16 v[68:71], v[172:175], v[212:215], v[68:71]
	v_mfma_f32_16x16x32_bf16 v[64:67], v[180:183], v[212:215], v[64:67]
	v_mfma_f32_16x16x32_bf16 v[116:119], v[176:179], v[192:195], v[116:119]
	v_mfma_f32_16x16x32_bf16 v[112:115], v[184:187], v[192:195], v[112:115]
	v_mfma_f32_16x16x32_bf16 v[100:103], v[176:179], v[200:203], v[100:103]
	v_mfma_f32_16x16x32_bf16 v[96:99], v[184:187], v[200:203], v[96:99]
	v_mfma_f32_16x16x32_bf16 v[84:87], v[176:179], v[208:211], v[84:87]
	v_mfma_f32_16x16x32_bf16 v[80:83], v[184:187], v[208:211], v[80:83]
	v_mfma_f32_16x16x32_bf16 v[68:71], v[176:179], v[216:219], v[68:71]
	v_mfma_f32_16x16x32_bf16 v[64:67], v[184:187], v[216:219], v[64:67]
	s_setprio 0
	s_barrier
	s_add_i32 s75, s68, s54
	v_lshl_add_u64 v[148:149], s[76:77], 0, v[130:131]
	s_mov_b32 m0, s75
	ds_read_b128 v[188:191], v158 offset:16384
	ds_read_b128 v[192:195], v158 offset:17408
	ds_read_b128 v[196:199], v158 offset:18432
	ds_read_b128 v[200:203], v158 offset:19456
	ds_read_b128 v[204:207], v158 offset:20480
	ds_read_b128 v[208:211], v158 offset:21504
	ds_read_b128 v[212:215], v158 offset:22528
	ds_read_b128 v[216:219], v158 offset:23552
	global_load_lds_dwordx4 v[148:149], off
	s_add_i32 m0, s75, 0x2000
	v_lshl_add_u64 v[220:221], s[76:77], 0, v[134:135]
	s_add_u32 s76, s76, s10
	s_addc_u32 s77, s77, s11
	s_add_i32 s75, s69, s54
	global_load_lds_dwordx4 v[220:221], off
	v_lshl_add_u64 v[222:223], s[76:77], 0, v[130:131]
	s_mov_b32 m0, s75
	v_lshl_add_u64 v[224:225], s[76:77], 0, v[134:135]
	global_load_lds_dwordx4 v[222:223], off
	s_add_i32 m0, s75, 0x2000
	v_lshl_add_u64 v[226:227], s[48:49], 0, v[128:129]
	global_load_lds_dwordx4 v[224:225], off
	s_mov_b32 m0, s55
	v_lshl_add_u64 v[228:229], s[48:49], 0, v[132:133]
	global_load_lds_dwordx4 v[226:227], off
	s_mov_b32 m0, s58
	s_nop 0
	global_load_lds_dwordx4 v[228:229], off
	s_waitcnt vmcnt(8)
	s_waitcnt lgkmcnt(0)
	s_barrier
; #define PG8_STAGE(bufoff, gbase, voff) do { _Pragma("unroll") for (int _i = 0; _i < 2; ++_i) \
;         __builtin_amdgcn_global_load_lds((const unsigned*)((const char*)(gbase) + (voff)[_i]), (PG8_LAS unsigned*)(lds + (bufoff) + ldsw + _i * 8192), 16, 0, 0); } while (0)
; #define PG8_LDA(dst, b, h) do { _Pragma("unroll") for (int m = 0; m < 4; ++m) _Pragma("unroll") for (int k = 0; k < 2; ++k) dst[m][k] = *(const PG8_LAS bf16x8*)(lds + PG8_SA(b, h) + aoff + m * 2048 + k * 1024); } while (0)
; #define PG8_LDB(dst, b, h) do { _Pragma("unroll") for (int n = 0; n < 2; ++n) _Pragma("unroll") for (int k = 0; k < 2; ++k) dst[n][k] = *(const PG8_LAS bf16x8*)(lds + PG8_SB(b, h) + boff + n * 2048 + k * 1024); } while (0)
; #define PG8_MMA(ai, bj, At, Bt) do { __builtin_amdgcn_s_setprio(1); _Pragma("unroll") for (int m = 0; m < 4; ++m) _Pragma("unroll") for (int n = 0; n < 2; ++n) _Pragma("unroll") for (int k = 0; k < 2; ++k) \
;         acc[ai][bj][m][n] = __builtin_amdgcn_mfma_f32_16x16x32_bf16(Bt[n][k], At[m][k], acc[ai][bj][m][n], 0, 0, 0); __builtin_amdgcn_s_setprio(0); } while (0)
; #define PG8_WAIT_V(n) asm volatile("s_waitcnt vmcnt(" #n ")" ::: "memory")
; #define PG8_WAIT_L(n) asm volatile("s_waitcnt lgkmcnt(" #n ")" ::: "memory")
; #define PG8_BAR __builtin_amdgcn_s_barrier()
; #define PG8_SCHED __builtin_amdgcn_sched_barrier(0)
; template <class Epi, class Sched, bool ALIGN_EPI = false, bool SP2 = false>
; __device__ __forceinline__ void gemm_phase(PG8_LAS unsigned char* lds, const Gemm g, const Sched& S, const Epi& E) {
;     ...
;             PG8_WAIT_V(8); PG8_WAIT_L(0); PG8_BAR; PG8_MMA(1, 0, At, B0); PG8_MMA(1, 1, At, B1); PG8_BAR; PG8_SCHED;
;             PG8_LDB(B0, 1, 0); PG8_LDB(B1, 1, 1); PG8_SCHED; PG8_LDA(At, 1, 0); PG8_STAGE(PG8_SA(0, 1), a2 + hstep, voffA);
;             PG8_WAIT_V(8); PG8_WAIT_L(0); PG8_BAR; PG8_MMA(0, 0, At, B0); PG8_MMA(0, 1, At, B1); PG8_BAR; PG8_SCHED;
	s_setprio 1
	s_waitcnt lgkmcnt(0)
	v_mfma_f32_16x16x32_bf16 v[60:63], v[144:147], v[188:191], v[60:63]
	v_mfma_f32_16x16x32_bf16 v[56:59], v[164:167], v[188:191], v[56:59]
	v_mfma_f32_16x16x32_bf16 v[44:47], v[144:147], v[196:199], v[44:47]
	v_mfma_f32_16x16x32_bf16 v[40:43], v[164:167], v[196:199], v[40:43]
	v_mfma_f32_16x16x32_bf16 v[28:31], v[144:147], v[204:207], v[28:31]
	v_mfma_f32_16x16x32_bf16 v[24:27], v[164:167], v[204:207], v[24:27]
	v_mfma_f32_16x16x32_bf16 v[12:15], v[144:147], v[212:215], v[12:15]
	v_mfma_f32_16x16x32_bf16 v[8:11], v[164:167], v[212:215], v[8:11]
	v_mfma_f32_16x16x32_bf16 v[60:63], v[160:163], v[192:195], v[60:63]
	v_mfma_f32_16x16x32_bf16 v[56:59], v[168:171], v[192:195], v[56:59]
	v_mfma_f32_16x16x32_bf16 v[44:47], v[160:163], v[200:203], v[44:47]
	v_mfma_f32_16x16x32_bf16 v[40:43], v[168:171], v[200:203], v[40:43]
	v_mfma_f32_16x16x32_bf16 v[28:31], v[160:163], v[208:211], v[28:31]
	v_mfma_f32_16x16x32_bf16 v[24:27], v[168:171], v[208:211], v[24:27]
	v_mfma_f32_16x16x32_bf16 v[12:15], v[160:163], v[216:219], v[12:15]
	v_mfma_f32_16x16x32_bf16 v[8:11], v[168:171], v[216:219], v[8:11]
	v_mfma_f32_16x16x32_bf16 v[52:55], v[172:175], v[188:191], v[52:55]
	v_mfma_f32_16x16x32_bf16 v[48:51], v[180:183], v[188:191], v[48:51]
	v_mfma_f32_16x16x32_bf16 v[36:39], v[172:175], v[196:199], v[36:39]
	v_mfma_f32_16x16x32_bf16 v[32:35], v[180:183], v[196:199], v[32:35]
	v_mfma_f32_16x16x32_bf16 v[20:23], v[172:175], v[204:207], v[20:23]
	v_mfma_f32_16x16x32_bf16 v[16:19], v[180:183], v[204:207], v[16:19]
	v_mfma_f32_16x16x32_bf16 v[4:7], v[172:175], v[212:215], v[4:7]
	v_mfma_f32_16x16x32_bf16 v[0:3], v[180:183], v[212:215], v[0:3]
	v_mfma_f32_16x16x32_bf16 v[52:55], v[176:179], v[192:195], v[52:55]
	v_mfma_f32_16x16x32_bf16 v[48:51], v[184:187], v[192:195], v[48:51]
	v_mfma_f32_16x16x32_bf16 v[36:39], v[176:179], v[200:203], v[36:39]
	v_mfma_f32_16x16x32_bf16 v[32:35], v[184:187], v[200:203], v[32:35]
	v_mfma_f32_16x16x32_bf16 v[20:23], v[176:179], v[208:211], v[20:23]
	v_mfma_f32_16x16x32_bf16 v[16:19], v[184:187], v[208:211], v[16:19]
	v_mfma_f32_16x16x32_bf16 v[4:7], v[176:179], v[216:219], v[4:7]
	v_mfma_f32_16x16x32_bf16 v[0:3], v[184:187], v[216:219], v[0:3]
	s_setprio 0
	s_barrier
	s_add_i32 s75, 0, 0x18000
	v_add_u32_e32 v159, s75, v151
	s_add_i32 s76, 0, 0x1c000
	ds_read_b128 v[144:147], v159
	ds_read_b128 v[160:163], v159 offset:1024
	ds_read_b128 v[164:167], v159 offset:2048
	ds_read_b128 v[168:171], v159 offset:3072
	v_add_u32_e32 v159, s76, v151
	ds_read_b128 v[172:175], v159
	ds_read_b128 v[176:179], v159 offset:1024
	ds_read_b128 v[180:183], v159 offset:2048
	ds_read_b128 v[184:187], v159 offset:3072
	s_add_u32 s48, s48, s10
	s_addc_u32 s49, s49, s11
	s_mov_b32 m0, s59
	v_lshl_add_u64 v[230:231], s[48:49], 0, v[128:129]
	ds_read_b128 v[188:191], v158 offset:32768
	ds_read_b128 v[192:195], v158 offset:33792
	ds_read_b128 v[196:199], v158 offset:34816
	ds_read_b128 v[200:203], v158 offset:35840
	ds_read_b128 v[204:207], v158 offset:36864
	ds_read_b128 v[208:211], v158 offset:37888
	ds_read_b128 v[212:215], v158 offset:38912
	ds_read_b128 v[216:219], v158 offset:39936
	global_load_lds_dwordx4 v[230:231], off
	v_lshl_add_u64 v[230:231], s[48:49], 0, v[132:133]
	s_mov_b32 m0, s60
	s_nop 0
	global_load_lds_dwordx4 v[230:231], off
	s_waitcnt vmcnt(8)
	s_waitcnt lgkmcnt(0)
	s_barrier
	s_setprio 1
	s_waitcnt lgkmcnt(0)
	v_mfma_f32_16x16x32_bf16 v[120:123], v[144:147], v[188:191], v[120:123]
	v_mfma_f32_16x16x32_bf16 v[124:127], v[164:167], v[188:191], v[124:127]
	v_mfma_f32_16x16x32_bf16 v[108:111], v[144:147], v[196:199], v[108:111]
	v_mfma_f32_16x16x32_bf16 v[104:107], v[164:167], v[196:199], v[104:107]
	v_mfma_f32_16x16x32_bf16 v[92:95], v[144:147], v[204:207], v[92:95]
	v_mfma_f32_16x16x32_bf16 v[88:91], v[164:167], v[204:207], v[88:91]
	v_mfma_f32_16x16x32_bf16 v[76:79], v[144:147], v[212:215], v[76:79]
	v_mfma_f32_16x16x32_bf16 v[72:75], v[164:167], v[212:215], v[72:75]
	v_mfma_f32_16x16x32_bf16 v[120:123], v[160:163], v[192:195], v[120:123]
	v_mfma_f32_16x16x32_bf16 v[124:127], v[168:171], v[192:195], v[124:127]
	v_mfma_f32_16x16x32_bf16 v[108:111], v[160:163], v[200:203], v[108:111]
	v_mfma_f32_16x16x32_bf16 v[104:107], v[168:171], v[200:203], v[104:107]
	v_mfma_f32_16x16x32_bf16 v[92:95], v[160:163], v[208:211], v[92:95]
	v_mfma_f32_16x16x32_bf16 v[88:91], v[168:171], v[208:211], v[88:91]
	v_mfma_f32_16x16x32_bf16 v[76:79], v[160:163], v[216:219], v[76:79]
	v_mfma_f32_16x16x32_bf16 v[72:75], v[168:171], v[216:219], v[72:75]
	v_mfma_f32_16x16x32_bf16 v[116:119], v[172:175], v[188:191], v[116:119]
	v_mfma_f32_16x16x32_bf16 v[112:115], v[180:183], v[188:191], v[112:115]
	v_mfma_f32_16x16x32_bf16 v[100:103], v[172:175], v[196:199], v[100:103]
	v_mfma_f32_16x16x32_bf16 v[96:99], v[180:183], v[196:199], v[96:99]
	v_mfma_f32_16x16x32_bf16 v[84:87], v[172:175], v[204:207], v[84:87]
	v_mfma_f32_16x16x32_bf16 v[80:83], v[180:183], v[204:207], v[80:83]
	v_mfma_f32_16x16x32_bf16 v[68:71], v[172:175], v[212:215], v[68:71]
	v_mfma_f32_16x16x32_bf16 v[64:67], v[180:183], v[212:215], v[64:67]
	v_mfma_f32_16x16x32_bf16 v[116:119], v[176:179], v[192:195], v[116:119]
	v_mfma_f32_16x16x32_bf16 v[112:115], v[184:187], v[192:195], v[112:115]
	v_mfma_f32_16x16x32_bf16 v[100:103], v[176:179], v[200:203], v[100:103]
	v_mfma_f32_16x16x32_bf16 v[96:99], v[184:187], v[200:203], v[96:99]
	v_mfma_f32_16x16x32_bf16 v[84:87], v[176:179], v[208:211], v[84:87]
	v_mfma_f32_16x16x32_bf16 v[80:83], v[184:187], v[208:211], v[80:83]
	v_mfma_f32_16x16x32_bf16 v[68:71], v[176:179], v[216:219], v[68:71]
	v_mfma_f32_16x16x32_bf16 v[64:67], v[184:187], v[216:219], v[64:67]
	s_setprio 0
	s_barrier
; #define PG8_STAGE(bufoff, gbase, voff) do { _Pragma("unroll") for (int _i = 0; _i < 2; ++_i) \
;         __builtin_amdgcn_global_load_lds((const unsigned*)((const char*)(gbase) + (voff)[_i]), (PG8_LAS unsigned*)(lds + (bufoff) + ldsw + _i * 8192), 16, 0, 0); } while (0)
; #define PG8_LDA(dst, b, h) do { _Pragma("unroll") for (int m = 0; m < 4; ++m) _Pragma("unroll") for (int k = 0; k < 2; ++k) dst[m][k] = *(const PG8_LAS bf16x8*)(lds + PG8_SA(b, h) + aoff + m * 2048 + k * 1024); } while (0)
; #define PG8_MMA(ai, bj, At, Bt) do { __builtin_amdgcn_s_setprio(1); _Pragma("unroll") for (int m = 0; m < 4; ++m) _Pragma("unroll") for (int n = 0; n < 2; ++n) _Pragma("unroll") for (int k = 0; k < 2; ++k) \
;         acc[ai][bj][m][n] = __builtin_amdgcn_mfma_f32_16x16x32_bf16(Bt[n][k], At[m][k], acc[ai][bj][m][n], 0, 0, 0); __builtin_amdgcn_s_setprio(0); } while (0)
; #define PG8_WAIT_V(n) asm volatile("s_waitcnt vmcnt(" #n ")" ::: "memory")
; #define PG8_WAIT_L(n) asm volatile("s_waitcnt lgkmcnt(" #n ")" ::: "memory")
; #define PG8_BAR __builtin_amdgcn_s_barrier()
; #define PG8_SCHED __builtin_amdgcn_sched_barrier(0)
; template <class Epi, class Sched, bool ALIGN_EPI = false, bool SP2 = false>
; __device__ __forceinline__ void gemm_phase(PG8_LAS unsigned char* lds, const Gemm g, const Sched& S, const Epi& E) {
;     ...
;         for (int t = 0; t < nt; t += 2) {
;     ...
;             PG8_LDA(At, 1, 1); PG8_STAGE(PG8_SB(1, 0), b3, voffB); PG8_STAGE(PG8_SB(1, 1), b3 + hstep, voffB); PG8_STAGE(PG8_SA(1, 0), a3, voffA);
;             PG8_WAIT_V(8); PG8_WAIT_L(0); PG8_BAR; PG8_MMA(1, 0, At, B0); PG8_MMA(1, 1, At, B1); PG8_BAR; PG8_SCHED;
	s_add_i32 s48, s75, s54
	v_lshl_add_u64 v[148:149], v[148:149], 0, s[20:21]
	s_mov_b32 m0, s48
	ds_read_b128 v[188:191], v158 offset:49152
	ds_read_b128 v[192:195], v158 offset:50176
	ds_read_b128 v[196:199], v158 offset:51200
	ds_read_b128 v[200:203], v158 offset:52224
	ds_read_b128 v[204:207], v158 offset:53248
	ds_read_b128 v[208:211], v158 offset:54272
	ds_read_b128 v[212:215], v158 offset:55296
	ds_read_b128 v[216:219], v158 offset:56320
	global_load_lds_dwordx4 v[148:149], off
	v_lshl_add_u64 v[148:149], v[220:221], 0, s[20:21]
	s_add_i32 m0, s48, 0x2000
	s_add_i32 s48, s76, s54
	global_load_lds_dwordx4 v[148:149], off
	v_lshl_add_u64 v[148:149], v[222:223], 0, s[20:21]
	s_mov_b32 m0, s48
	s_nop 0
	global_load_lds_dwordx4 v[148:149], off
	v_lshl_add_u64 v[148:149], v[224:225], 0, s[20:21]
	s_add_i32 m0, s48, 0x2000
	s_nop 0
	global_load_lds_dwordx4 v[148:149], off
	v_lshl_add_u64 v[148:149], v[226:227], 0, s[20:21]
	s_mov_b32 m0, s62
	s_nop 0
	global_load_lds_dwordx4 v[148:149], off
	v_lshl_add_u64 v[148:149], v[228:229], 0, s[20:21]
	s_mov_b32 m0, s63
	s_nop 0
	global_load_lds_dwordx4 v[148:149], off
	s_waitcnt vmcnt(8)
	s_waitcnt lgkmcnt(0)
	s_barrier
	s_setprio 1
	s_waitcnt lgkmcnt(0)
	v_mfma_f32_16x16x32_bf16 v[60:63], v[144:147], v[188:191], v[60:63]
	v_mfma_f32_16x16x32_bf16 v[56:59], v[164:167], v[188:191], v[56:59]
	v_mfma_f32_16x16x32_bf16 v[44:47], v[144:147], v[196:199], v[44:47]
	v_mfma_f32_16x16x32_bf16 v[40:43], v[164:167], v[196:199], v[40:43]
	v_mfma_f32_16x16x32_bf16 v[28:31], v[144:147], v[204:207], v[28:31]
	v_mfma_f32_16x16x32_bf16 v[24:27], v[164:167], v[204:207], v[24:27]
	v_mfma_f32_16x16x32_bf16 v[12:15], v[144:147], v[212:215], v[12:15]
	v_mfma_f32_16x16x32_bf16 v[8:11], v[164:167], v[212:215], v[8:11]
	v_mfma_f32_16x16x32_bf16 v[60:63], v[160:163], v[192:195], v[60:63]
	v_mfma_f32_16x16x32_bf16 v[56:59], v[168:171], v[192:195], v[56:59]
	v_mfma_f32_16x16x32_bf16 v[44:47], v[160:163], v[200:203], v[44:47]
	v_mfma_f32_16x16x32_bf16 v[40:43], v[168:171], v[200:203], v[40:43]
	v_mfma_f32_16x16x32_bf16 v[28:31], v[160:163], v[208:211], v[28:31]
	v_mfma_f32_16x16x32_bf16 v[24:27], v[168:171], v[208:211], v[24:27]
	v_mfma_f32_16x16x32_bf16 v[12:15], v[160:163], v[216:219], v[12:15]
	v_mfma_f32_16x16x32_bf16 v[8:11], v[168:171], v[216:219], v[8:11]
	v_mfma_f32_16x16x32_bf16 v[52:55], v[172:175], v[188:191], v[52:55]
	v_mfma_f32_16x16x32_bf16 v[48:51], v[180:183], v[188:191], v[48:51]
	v_mfma_f32_16x16x32_bf16 v[36:39], v[172:175], v[196:199], v[36:39]
	v_mfma_f32_16x16x32_bf16 v[32:35], v[180:183], v[196:199], v[32:35]
	v_mfma_f32_16x16x32_bf16 v[20:23], v[172:175], v[204:207], v[20:23]
	v_mfma_f32_16x16x32_bf16 v[16:19], v[180:183], v[204:207], v[16:19]
	v_mfma_f32_16x16x32_bf16 v[4:7], v[172:175], v[212:215], v[4:7]
	v_mfma_f32_16x16x32_bf16 v[0:3], v[180:183], v[212:215], v[0:3]
	v_mfma_f32_16x16x32_bf16 v[52:55], v[176:179], v[192:195], v[52:55]
	v_mfma_f32_16x16x32_bf16 v[48:51], v[184:187], v[192:195], v[48:51]
	v_mfma_f32_16x16x32_bf16 v[36:39], v[176:179], v[200:203], v[36:39]
	v_mfma_f32_16x16x32_bf16 v[32:35], v[184:187], v[200:203], v[32:35]
	v_mfma_f32_16x16x32_bf16 v[20:23], v[176:179], v[208:211], v[20:23]
	v_mfma_f32_16x16x32_bf16 v[16:19], v[184:187], v[208:211], v[16:19]
	v_mfma_f32_16x16x32_bf16 v[4:7], v[176:179], v[216:219], v[4:7]
	v_mfma_f32_16x16x32_bf16 v[0:3], v[184:187], v[216:219], v[0:3]
	s_setprio 0
	s_barrier
	s_add_u32 s46, s46, 0x100
	s_addc_u32 s47, s47, 0
	s_add_u32 s0, s0, 0x100
	s_addc_u32 s1, s1, 0
	s_cmp_ge_i32 s74, s64
	s_mov_b32 s48, s74
	s_cbranch_scc0 .LBB0_1259

; #define PG8_STAGE(bufoff, gbase, voff) do { _Pragma("unroll") for (int _i = 0; _i < 2; ++_i) \
;         __builtin_amdgcn_global_load_lds((const unsigned*)((const char*)(gbase) + (voff)[_i]), (PG8_LAS unsigned*)(lds + (bufoff) + ldsw + _i * 8192), 16, 0, 0); } while (0)
; #define PG8_LDA(dst, b, h) do { _Pragma("unroll") for (int m = 0; m < 4; ++m) _Pragma("unroll") for (int k = 0; k < 2; ++k) dst[m][k] = *(const PG8_LAS bf16x8*)(lds + PG8_SA(b, h) + aoff + m * 2048 + k * 1024); } while (0)
; #define PG8_LDB(dst, b, h) do { _Pragma("unroll") for (int n = 0; n < 2; ++n) _Pragma("unroll") for (int k = 0; k < 2; ++k) dst[n][k] = *(const PG8_LAS bf16x8*)(lds + PG8_SB(b, h) + boff + n * 2048 + k * 1024); } while (0)
; #define PG8_MMA(ai, bj, At, Bt) do { __builtin_amdgcn_s_setprio(1); _Pragma("unroll") for (int m = 0; m < 4; ++m) _Pragma("unroll") for (int n = 0; n < 2; ++n) _Pragma("unroll") for (int k = 0; k < 2; ++k) \
;         acc[ai][bj][m][n] = __builtin_amdgcn_mfma_f32_16x16x32_bf16(Bt[n][k], At[m][k], acc[ai][bj][m][n], 0, 0, 0); __builtin_amdgcn_s_setprio(0); } while (0)
; #define PG8_WAIT_V(n) asm volatile("s_waitcnt vmcnt(" #n ")" ::: "memory")
; #define PG8_WAIT_L(n) asm volatile("s_waitcnt lgkmcnt(" #n ")" ::: "memory")
; #define PG8_BAR __builtin_amdgcn_s_barrier()
; #define PG8_SCHED __builtin_amdgcn_sched_barrier(0)
; template <class Epi, class Sched, bool ALIGN_EPI = false, bool SP2 = false>
; __device__ __forceinline__ void gemm_phase(PG8_LAS unsigned char* lds, const Gemm g, const Sched& S, const Epi& E) {
;     ...
;             const bool last = (t == nt - 2);
;             const char* a1 = cA + (size_t)(t + 1) * kstep;
;             const char* a2 = last ? nA : cA + (size_t)(t + 2) * kstep; const char* b2 = last ? nB : cB + (size_t)(t + 2) * kstep;
;             const char* a3 = a2 + kstep; const char* b3 = b2 + kstep;
;             if (last && has_next) S.a_ready(nxt);
;             if constexpr (SP2) {
;             PG8_LDB(B0, 0, 0); PG8_LDB(B1, 0, 1); PG8_SCHED; PG8_LDA(At, 0, 0); PG8_STAGE(PG8_SA(1, 1), a1 + hstep, voffA);
;             PG8_WAIT_V(8); PG8_WAIT_L(0); PG8_BAR; PG8_MMA(0, 0, At, B0); PG8_MMA(0, 1, At, B1); PG8_BAR; PG8_SCHED;
;             PG8_LDA(At, 0, 1); PG8_STAGE(PG8_SB(0, 0), b2, voffB); PG8_STAGE(PG8_SB(0, 1), b2 + hstep, voffB); PG8_STAGE(PG8_SA(0, 0), a2, voffA);
.LBB0_1345:
	v_add_u32_e32 v1, s66, v150
	ds_read_b128 v[158:161], v1
	ds_read_b128 v[162:165], v1 offset:1024
	ds_read_b128 v[166:169], v1 offset:2048
	ds_read_b128 v[170:173], v1 offset:3072
	v_add_u32_e32 v1, s67, v150
	ds_read_b128 v[174:177], v1
	ds_read_b128 v[178:181], v1 offset:1024
	ds_read_b128 v[182:185], v1 offset:2048
	ds_read_b128 v[186:189], v1 offset:3072
	s_add_i32 s72, s44, 2
	s_add_u32 s73, s42, 0x80
	s_addc_u32 s45, s43, 0
	s_cmp_eq_u32 s65, s44
	s_cselect_b32 s44, s10, s73
	s_cselect_b32 s45, s11, s45
	s_cselect_b32 s75, s41, s1
	s_cselect_b32 s74, s40, s0
	v_lshl_add_u64 v[2:3], s[42:43], 0, v[140:141]
	s_add_i32 m0, s55, 0xc000
	ds_read_b128 v[190:193], v151
	ds_read_b128 v[194:197], v151 offset:1024
	ds_read_b128 v[198:201], v151 offset:2048
	ds_read_b128 v[202:205], v151 offset:3072
	ds_read_b128 v[206:209], v151 offset:4096
	ds_read_b128 v[210:213], v151 offset:5120
	ds_read_b128 v[214:217], v151 offset:6144
	ds_read_b128 v[218:221], v151 offset:7168
	global_load_lds_dwordx4 v[2:3], off
	v_lshl_add_u64 v[2:3], s[42:43], 0, v[142:143]
	s_add_i32 m0, s55, 0xe000
	s_nop 0
	global_load_lds_dwordx4 v[2:3], off
	s_waitcnt vmcnt(8)
	s_waitcnt lgkmcnt(0)
	s_barrier
	s_setprio 1
	s_waitcnt lgkmcnt(0)
	v_mfma_f32_16x16x32_bf16 v[52:55], v[158:161], v[190:193], v[52:55]
	v_mfma_f32_16x16x32_bf16 v[48:51], v[166:169], v[190:193], v[48:51]
	v_mfma_f32_16x16x32_bf16 v[60:63], v[158:161], v[198:201], v[60:63]
	v_mfma_f32_16x16x32_bf16 v[56:59], v[166:169], v[198:201], v[56:59]
	v_mfma_f32_16x16x32_bf16 v[76:79], v[158:161], v[206:209], v[76:79]
	v_mfma_f32_16x16x32_bf16 v[72:75], v[166:169], v[206:209], v[72:75]
	v_mfma_f32_16x16x32_bf16 v[88:91], v[158:161], v[214:217], v[88:91]
	v_mfma_f32_16x16x32_bf16 v[80:83], v[166:169], v[214:217], v[80:83]
	v_mfma_f32_16x16x32_bf16 v[52:55], v[162:165], v[194:197], v[52:55]
	v_mfma_f32_16x16x32_bf16 v[48:51], v[170:173], v[194:197], v[48:51]
	v_mfma_f32_16x16x32_bf16 v[60:63], v[162:165], v[202:205], v[60:63]
	v_mfma_f32_16x16x32_bf16 v[56:59], v[170:173], v[202:205], v[56:59]
	v_mfma_f32_16x16x32_bf16 v[76:79], v[162:165], v[210:213], v[76:79]
	v_mfma_f32_16x16x32_bf16 v[72:75], v[170:173], v[210:213], v[72:75]
	v_mfma_f32_16x16x32_bf16 v[88:91], v[162:165], v[218:221], v[88:91]
	v_mfma_f32_16x16x32_bf16 v[80:83], v[170:173], v[218:221], v[80:83]
	v_mfma_f32_16x16x32_bf16 v[2:5], v[174:177], v[190:193], v[4:7]
	v_mfma_f32_16x16x32_bf16 v[128:131], v[182:185], v[190:193], v[128:131]
	v_mfma_f32_16x16x32_bf16 v[12:15], v[174:177], v[198:201], v[12:15]
	v_mfma_f32_16x16x32_bf16 v[6:9], v[182:185], v[198:201], v[8:11]
	v_mfma_f32_16x16x32_bf16 v[20:23], v[174:177], v[206:209], v[20:23]
	v_mfma_f32_16x16x32_bf16 v[16:19], v[182:185], v[206:209], v[16:19]
	v_mfma_f32_16x16x32_bf16 v[28:31], v[174:177], v[214:217], v[28:31]
	v_mfma_f32_16x16x32_bf16 v[24:27], v[182:185], v[214:217], v[24:27]
	v_mfma_f32_16x16x32_bf16 v[2:5], v[178:181], v[194:197], v[2:5]
	v_mfma_f32_16x16x32_bf16 v[128:131], v[186:189], v[194:197], v[128:131]
	v_mfma_f32_16x16x32_bf16 v[12:15], v[178:181], v[202:205], v[12:15]
	v_mfma_f32_16x16x32_bf16 v[8:11], v[186:189], v[202:205], v[6:9]
	v_mfma_f32_16x16x32_bf16 v[20:23], v[178:181], v[210:213], v[20:23]
	v_mfma_f32_16x16x32_bf16 v[16:19], v[186:189], v[210:213], v[16:19]
	v_mfma_f32_16x16x32_bf16 v[28:31], v[178:181], v[218:221], v[28:31]
	v_mfma_f32_16x16x32_bf16 v[24:27], v[186:189], v[218:221], v[24:27]
	s_setprio 0
	s_barrier
	s_add_i32 s73, s66, s54
	v_lshl_add_u64 v[222:223], s[74:75], 0, v[134:135]
	s_mov_b32 m0, s73
	ds_read_b128 v[190:193], v151 offset:16384
	ds_read_b128 v[194:197], v151 offset:17408
	ds_read_b128 v[198:201], v151 offset:18432
	ds_read_b128 v[202:205], v151 offset:19456
	ds_read_b128 v[206:209], v151 offset:20480
	ds_read_b128 v[210:213], v151 offset:21504
	ds_read_b128 v[214:217], v151 offset:22528
	ds_read_b128 v[218:221], v151 offset:23552
	global_load_lds_dwordx4 v[222:223], off
	s_add_i32 m0, s73, 0x2000
	v_lshl_add_u64 v[224:225], s[74:75], 0, v[138:139]
	s_add_u32 s74, s74, s24
	s_addc_u32 s75, s75, s25
	s_add_i32 s73, s67, s54
	global_load_lds_dwordx4 v[224:225], off
	v_lshl_add_u64 v[226:227], s[74:75], 0, v[134:135]
	s_mov_b32 m0, s73
	v_lshl_add_u64 v[228:229], s[74:75], 0, v[138:139]
	global_load_lds_dwordx4 v[226:227], off
	s_add_i32 m0, s73, 0x2000
	v_lshl_add_u64 v[230:231], s[44:45], 0, v[132:133]
	global_load_lds_dwordx4 v[228:229], off
	s_mov_b32 m0, s55
	v_lshl_add_u64 v[232:233], s[44:45], 0, v[136:137]
	global_load_lds_dwordx4 v[230:231], off
	s_mov_b32 m0, s58
	s_nop 0
	global_load_lds_dwordx4 v[232:233], off
	s_waitcnt vmcnt(8)
	s_waitcnt lgkmcnt(0)
	s_barrier
; #define PG8_STAGE(bufoff, gbase, voff) do { _Pragma("unroll") for (int _i = 0; _i < 2; ++_i) \
;         __builtin_amdgcn_global_load_lds((const unsigned*)((const char*)(gbase) + (voff)[_i]), (PG8_LAS unsigned*)(lds + (bufoff) + ldsw + _i * 8192), 16, 0, 0); } while (0)
; #define PG8_LDA(dst, b, h) do { _Pragma("unroll") for (int m = 0; m < 4; ++m) _Pragma("unroll") for (int k = 0; k < 2; ++k) dst[m][k] = *(const PG8_LAS bf16x8*)(lds + PG8_SA(b, h) + aoff + m * 2048 + k * 1024); } while (0)
; #define PG8_LDB(dst, b, h) do { _Pragma("unroll") for (int n = 0; n < 2; ++n) _Pragma("unroll") for (int k = 0; k < 2; ++k) dst[n][k] = *(const PG8_LAS bf16x8*)(lds + PG8_SB(b, h) + boff + n * 2048 + k * 1024); } while (0)
; #define PG8_MMA(ai, bj, At, Bt) do { __builtin_amdgcn_s_setprio(1); _Pragma("unroll") for (int m = 0; m < 4; ++m) _Pragma("unroll") for (int n = 0; n < 2; ++n) _Pragma("unroll") for (int k = 0; k < 2; ++k) \
;         acc[ai][bj][m][n] = __builtin_amdgcn_mfma_f32_16x16x32_bf16(Bt[n][k], At[m][k], acc[ai][bj][m][n], 0, 0, 0); __builtin_amdgcn_s_setprio(0); } while (0)
; #define PG8_WAIT_V(n) asm volatile("s_waitcnt vmcnt(" #n ")" ::: "memory")
; #define PG8_WAIT_L(n) asm volatile("s_waitcnt lgkmcnt(" #n ")" ::: "memory")
; #define PG8_BAR __builtin_amdgcn_s_barrier()
; #define PG8_SCHED __builtin_amdgcn_sched_barrier(0)
; template <class Epi, class Sched, bool ALIGN_EPI = false, bool SP2 = false>
; __device__ __forceinline__ void gemm_phase(PG8_LAS unsigned char* lds, const Gemm g, const Sched& S, const Epi& E) {
;     ...
;             PG8_WAIT_V(8); PG8_WAIT_L(0); PG8_BAR; PG8_MMA(1, 0, At, B0); PG8_MMA(1, 1, At, B1); PG8_BAR; PG8_SCHED;
;             PG8_LDB(B0, 1, 0); PG8_LDB(B1, 1, 1); PG8_SCHED; PG8_LDA(At, 1, 0); PG8_STAGE(PG8_SA(0, 1), a2 + hstep, voffA);
;             PG8_WAIT_V(8); PG8_WAIT_L(0); PG8_BAR; PG8_MMA(0, 0, At, B0); PG8_MMA(0, 1, At, B1); PG8_BAR; PG8_SCHED;
	s_setprio 1
	s_waitcnt lgkmcnt(0)
	v_mfma_f32_16x16x32_bf16 v[100:103], v[158:161], v[190:193], v[100:103]
	v_mfma_f32_16x16x32_bf16 v[96:99], v[166:169], v[190:193], v[96:99]
	v_mfma_f32_16x16x32_bf16 v[108:111], v[158:161], v[198:201], v[108:111]
	v_mfma_f32_16x16x32_bf16 v[104:107], v[166:169], v[198:201], v[104:107]
	v_mfma_f32_16x16x32_bf16 v[124:127], v[158:161], v[206:209], v[124:127]
	v_mfma_f32_16x16x32_bf16 v[120:123], v[166:169], v[206:209], v[120:123]
	v_mfma_f32_16x16x32_bf16 v[116:119], v[158:161], v[214:217], v[116:119]
	v_mfma_f32_16x16x32_bf16 v[112:115], v[166:169], v[214:217], v[112:115]
	v_mfma_f32_16x16x32_bf16 v[100:103], v[162:165], v[194:197], v[100:103]
	v_mfma_f32_16x16x32_bf16 v[96:99], v[170:173], v[194:197], v[96:99]
	v_mfma_f32_16x16x32_bf16 v[108:111], v[162:165], v[202:205], v[108:111]
	v_mfma_f32_16x16x32_bf16 v[104:107], v[170:173], v[202:205], v[104:107]
	v_mfma_f32_16x16x32_bf16 v[124:127], v[162:165], v[210:213], v[124:127]
	v_mfma_f32_16x16x32_bf16 v[120:123], v[170:173], v[210:213], v[120:123]
	v_mfma_f32_16x16x32_bf16 v[116:119], v[162:165], v[218:221], v[116:119]
	v_mfma_f32_16x16x32_bf16 v[112:115], v[170:173], v[218:221], v[112:115]
	v_mfma_f32_16x16x32_bf16 v[36:39], v[174:177], v[190:193], v[36:39]
	v_mfma_f32_16x16x32_bf16 v[32:35], v[182:185], v[190:193], v[32:35]
	v_mfma_f32_16x16x32_bf16 v[44:47], v[174:177], v[198:201], v[44:47]
	v_mfma_f32_16x16x32_bf16 v[40:43], v[182:185], v[198:201], v[40:43]
	v_mfma_f32_16x16x32_bf16 v[68:71], v[174:177], v[206:209], v[68:71]
	v_mfma_f32_16x16x32_bf16 v[64:67], v[182:185], v[206:209], v[64:67]
	v_mfma_f32_16x16x32_bf16 v[92:95], v[174:177], v[214:217], v[92:95]
	v_mfma_f32_16x16x32_bf16 v[84:87], v[182:185], v[214:217], v[84:87]
	v_mfma_f32_16x16x32_bf16 v[36:39], v[178:181], v[194:197], v[36:39]
	v_mfma_f32_16x16x32_bf16 v[32:35], v[186:189], v[194:197], v[32:35]
	v_mfma_f32_16x16x32_bf16 v[44:47], v[178:181], v[202:205], v[44:47]
	v_mfma_f32_16x16x32_bf16 v[40:43], v[186:189], v[202:205], v[40:43]
	v_mfma_f32_16x16x32_bf16 v[68:71], v[178:181], v[210:213], v[68:71]
	v_mfma_f32_16x16x32_bf16 v[64:67], v[186:189], v[210:213], v[64:67]
	v_mfma_f32_16x16x32_bf16 v[92:95], v[178:181], v[218:221], v[92:95]
	v_mfma_f32_16x16x32_bf16 v[84:87], v[186:189], v[218:221], v[84:87]
	s_setprio 0
	s_barrier
	s_add_i32 s73, 0, 0x18000
	v_add_u32_e32 v1, s73, v150
	s_add_i32 s74, 0, 0x1c000
	ds_read_b128 v[158:161], v1
	ds_read_b128 v[162:165], v1 offset:1024
	ds_read_b128 v[166:169], v1 offset:2048
	ds_read_b128 v[170:173], v1 offset:3072
	v_add_u32_e32 v1, s74, v150
	ds_read_b128 v[174:177], v1
	ds_read_b128 v[178:181], v1 offset:1024
	ds_read_b128 v[182:185], v1 offset:2048
	ds_read_b128 v[186:189], v1 offset:3072
	s_add_u32 s44, s44, s24
	s_addc_u32 s45, s45, s25
	s_mov_b32 m0, s59
	v_lshl_add_u64 v[6:7], s[44:45], 0, v[132:133]
	ds_read_b128 v[190:193], v151 offset:32768
	ds_read_b128 v[194:197], v151 offset:33792
	ds_read_b128 v[198:201], v151 offset:34816
	ds_read_b128 v[202:205], v151 offset:35840
	ds_read_b128 v[206:209], v151 offset:36864
	ds_read_b128 v[210:213], v151 offset:37888
	ds_read_b128 v[214:217], v151 offset:38912
	ds_read_b128 v[218:221], v151 offset:39936
	global_load_lds_dwordx4 v[6:7], off
	v_lshl_add_u64 v[6:7], s[44:45], 0, v[136:137]
	s_mov_b32 m0, s60
	s_nop 0
	global_load_lds_dwordx4 v[6:7], off
	s_waitcnt vmcnt(8)
	s_waitcnt lgkmcnt(0)
	s_barrier
	s_setprio 1
	s_waitcnt lgkmcnt(0)
	v_mfma_f32_16x16x32_bf16 v[52:55], v[158:161], v[190:193], v[52:55]
	v_mfma_f32_16x16x32_bf16 v[48:51], v[166:169], v[190:193], v[48:51]
	v_mfma_f32_16x16x32_bf16 v[60:63], v[158:161], v[198:201], v[60:63]
	v_mfma_f32_16x16x32_bf16 v[56:59], v[166:169], v[198:201], v[56:59]
	v_mfma_f32_16x16x32_bf16 v[76:79], v[158:161], v[206:209], v[76:79]
	v_mfma_f32_16x16x32_bf16 v[72:75], v[166:169], v[206:209], v[72:75]
	v_mfma_f32_16x16x32_bf16 v[88:91], v[158:161], v[214:217], v[88:91]
	v_mfma_f32_16x16x32_bf16 v[80:83], v[166:169], v[214:217], v[80:83]
	v_mfma_f32_16x16x32_bf16 v[52:55], v[162:165], v[194:197], v[52:55]
	v_mfma_f32_16x16x32_bf16 v[48:51], v[170:173], v[194:197], v[48:51]
	v_mfma_f32_16x16x32_bf16 v[60:63], v[162:165], v[202:205], v[60:63]
	v_mfma_f32_16x16x32_bf16 v[56:59], v[170:173], v[202:205], v[56:59]
	v_mfma_f32_16x16x32_bf16 v[76:79], v[162:165], v[210:213], v[76:79]
	v_mfma_f32_16x16x32_bf16 v[72:75], v[170:173], v[210:213], v[72:75]
	v_mfma_f32_16x16x32_bf16 v[88:91], v[162:165], v[218:221], v[88:91]
	v_mfma_f32_16x16x32_bf16 v[80:83], v[170:173], v[218:221], v[80:83]
	v_mfma_f32_16x16x32_bf16 v[2:5], v[174:177], v[190:193], v[2:5]
	v_mfma_f32_16x16x32_bf16 v[128:131], v[182:185], v[190:193], v[128:131]
	v_mfma_f32_16x16x32_bf16 v[12:15], v[174:177], v[198:201], v[12:15]
	v_mfma_f32_16x16x32_bf16 v[8:11], v[182:185], v[198:201], v[8:11]
	v_mfma_f32_16x16x32_bf16 v[20:23], v[174:177], v[206:209], v[20:23]
	v_mfma_f32_16x16x32_bf16 v[16:19], v[182:185], v[206:209], v[16:19]
	v_mfma_f32_16x16x32_bf16 v[28:31], v[174:177], v[214:217], v[28:31]
	v_mfma_f32_16x16x32_bf16 v[24:27], v[182:185], v[214:217], v[24:27]
	v_mfma_f32_16x16x32_bf16 v[4:7], v[178:181], v[194:197], v[2:5]
	v_mfma_f32_16x16x32_bf16 v[128:131], v[186:189], v[194:197], v[128:131]
	v_mfma_f32_16x16x32_bf16 v[12:15], v[178:181], v[202:205], v[12:15]
	v_mfma_f32_16x16x32_bf16 v[8:11], v[186:189], v[202:205], v[8:11]
	v_mfma_f32_16x16x32_bf16 v[20:23], v[178:181], v[210:213], v[20:23]
	v_mfma_f32_16x16x32_bf16 v[16:19], v[186:189], v[210:213], v[16:19]
	v_mfma_f32_16x16x32_bf16 v[28:31], v[178:181], v[218:221], v[28:31]
	v_mfma_f32_16x16x32_bf16 v[24:27], v[186:189], v[218:221], v[24:27]
	s_setprio 0
	s_barrier
; #define PG8_STAGE(bufoff, gbase, voff) do { _Pragma("unroll") for (int _i = 0; _i < 2; ++_i) \
;         __builtin_amdgcn_global_load_lds((const unsigned*)((const char*)(gbase) + (voff)[_i]), (PG8_LAS unsigned*)(lds + (bufoff) + ldsw + _i * 8192), 16, 0, 0); } while (0)
; #define PG8_LDA(dst, b, h) do { _Pragma("unroll") for (int m = 0; m < 4; ++m) _Pragma("unroll") for (int k = 0; k < 2; ++k) dst[m][k] = *(const PG8_LAS bf16x8*)(lds + PG8_SA(b, h) + aoff + m * 2048 + k * 1024); } while (0)
; #define PG8_MMA(ai, bj, At, Bt) do { __builtin_amdgcn_s_setprio(1); _Pragma("unroll") for (int m = 0; m < 4; ++m) _Pragma("unroll") for (int n = 0; n < 2; ++n) _Pragma("unroll") for (int k = 0; k < 2; ++k) \
;         acc[ai][bj][m][n] = __builtin_amdgcn_mfma_f32_16x16x32_bf16(Bt[n][k], At[m][k], acc[ai][bj][m][n], 0, 0, 0); __builtin_amdgcn_s_setprio(0); } while (0)
; #define PG8_WAIT_V(n) asm volatile("s_waitcnt vmcnt(" #n ")" ::: "memory")
; #define PG8_WAIT_L(n) asm volatile("s_waitcnt lgkmcnt(" #n ")" ::: "memory")
; #define PG8_BAR __builtin_amdgcn_s_barrier()
; #define PG8_SCHED __builtin_amdgcn_sched_barrier(0)
; template <class Epi, class Sched, bool ALIGN_EPI = false, bool SP2 = false>
; __device__ __forceinline__ void gemm_phase(PG8_LAS unsigned char* lds, const Gemm g, const Sched& S, const Epi& E) {
;     ...
;         for (int t = 0; t < nt; t += 2) {
;     ...
;             PG8_LDA(At, 1, 1); PG8_STAGE(PG8_SB(1, 0), b3, voffB); PG8_STAGE(PG8_SB(1, 1), b3 + hstep, voffB); PG8_STAGE(PG8_SA(1, 0), a3, voffA);
;             PG8_WAIT_V(8); PG8_WAIT_L(0); PG8_BAR; PG8_MMA(1, 0, At, B0); PG8_MMA(1, 1, At, B1); PG8_BAR; PG8_SCHED;
	s_add_i32 s44, s73, s54
	v_lshl_add_u64 v[2:3], v[222:223], 0, s[36:37]
	s_mov_b32 m0, s44
	ds_read_b128 v[190:193], v151 offset:49152
	ds_read_b128 v[194:197], v151 offset:50176
	ds_read_b128 v[198:201], v151 offset:51200
	ds_read_b128 v[202:205], v151 offset:52224
	ds_read_b128 v[206:209], v151 offset:53248
	ds_read_b128 v[210:213], v151 offset:54272
	ds_read_b128 v[214:217], v151 offset:55296
	ds_read_b128 v[218:221], v151 offset:56320
	global_load_lds_dwordx4 v[2:3], off
	v_lshl_add_u64 v[2:3], v[224:225], 0, s[36:37]
	s_add_i32 m0, s44, 0x2000
	s_add_i32 s44, s74, s54
	global_load_lds_dwordx4 v[2:3], off
	v_lshl_add_u64 v[2:3], v[226:227], 0, s[36:37]
	s_mov_b32 m0, s44
	s_nop 0
	global_load_lds_dwordx4 v[2:3], off
	v_lshl_add_u64 v[2:3], v[228:229], 0, s[36:37]
	s_add_i32 m0, s44, 0x2000
	s_nop 0
	global_load_lds_dwordx4 v[2:3], off
	v_lshl_add_u64 v[2:3], v[230:231], 0, s[36:37]
	s_mov_b32 m0, s61
	s_nop 0
	global_load_lds_dwordx4 v[2:3], off
	v_lshl_add_u64 v[2:3], v[232:233], 0, s[36:37]
	s_mov_b32 m0, s63
	s_nop 0
	global_load_lds_dwordx4 v[2:3], off
	s_waitcnt vmcnt(8)
	s_waitcnt lgkmcnt(0)
	s_barrier
	s_setprio 1
	s_waitcnt lgkmcnt(0)
	v_mfma_f32_16x16x32_bf16 v[100:103], v[158:161], v[190:193], v[100:103]
	v_mfma_f32_16x16x32_bf16 v[96:99], v[166:169], v[190:193], v[96:99]
	v_mfma_f32_16x16x32_bf16 v[108:111], v[158:161], v[198:201], v[108:111]
	v_mfma_f32_16x16x32_bf16 v[104:107], v[166:169], v[198:201], v[104:107]
	v_mfma_f32_16x16x32_bf16 v[124:127], v[158:161], v[206:209], v[124:127]
	v_mfma_f32_16x16x32_bf16 v[120:123], v[166:169], v[206:209], v[120:123]
	v_mfma_f32_16x16x32_bf16 v[116:119], v[158:161], v[214:217], v[116:119]
	v_mfma_f32_16x16x32_bf16 v[112:115], v[166:169], v[214:217], v[112:115]
	v_mfma_f32_16x16x32_bf16 v[100:103], v[162:165], v[194:197], v[100:103]
	v_mfma_f32_16x16x32_bf16 v[96:99], v[170:173], v[194:197], v[96:99]
	v_mfma_f32_16x16x32_bf16 v[108:111], v[162:165], v[202:205], v[108:111]
	v_mfma_f32_16x16x32_bf16 v[104:107], v[170:173], v[202:205], v[104:107]
	v_mfma_f32_16x16x32_bf16 v[124:127], v[162:165], v[210:213], v[124:127]
	v_mfma_f32_16x16x32_bf16 v[120:123], v[170:173], v[210:213], v[120:123]
	v_mfma_f32_16x16x32_bf16 v[116:119], v[162:165], v[218:221], v[116:119]
	v_mfma_f32_16x16x32_bf16 v[112:115], v[170:173], v[218:221], v[112:115]
	v_mfma_f32_16x16x32_bf16 v[36:39], v[174:177], v[190:193], v[36:39]
	v_mfma_f32_16x16x32_bf16 v[32:35], v[182:185], v[190:193], v[32:35]
	v_mfma_f32_16x16x32_bf16 v[44:47], v[174:177], v[198:201], v[44:47]
	v_mfma_f32_16x16x32_bf16 v[40:43], v[182:185], v[198:201], v[40:43]
	v_mfma_f32_16x16x32_bf16 v[68:71], v[174:177], v[206:209], v[68:71]
	v_mfma_f32_16x16x32_bf16 v[64:67], v[182:185], v[206:209], v[64:67]
	v_mfma_f32_16x16x32_bf16 v[92:95], v[174:177], v[214:217], v[92:95]
	v_mfma_f32_16x16x32_bf16 v[84:87], v[182:185], v[214:217], v[84:87]
	v_mfma_f32_16x16x32_bf16 v[36:39], v[178:181], v[194:197], v[36:39]
	v_mfma_f32_16x16x32_bf16 v[32:35], v[186:189], v[194:197], v[32:35]
	v_mfma_f32_16x16x32_bf16 v[44:47], v[178:181], v[202:205], v[44:47]
	v_mfma_f32_16x16x32_bf16 v[40:43], v[186:189], v[202:205], v[40:43]
	v_mfma_f32_16x16x32_bf16 v[68:71], v[178:181], v[210:213], v[68:71]
	v_mfma_f32_16x16x32_bf16 v[64:67], v[186:189], v[210:213], v[64:67]
	v_mfma_f32_16x16x32_bf16 v[92:95], v[178:181], v[218:221], v[92:95]
	v_mfma_f32_16x16x32_bf16 v[84:87], v[186:189], v[218:221], v[84:87]
	s_setprio 0
	s_barrier
	s_add_u32 s42, s42, 0x100
	s_addc_u32 s43, s43, 0
	s_add_u32 s0, s0, 0x100
	s_addc_u32 s1, s1, 0
	s_cmp_ge_i32 s72, s64
	s_mov_b32 s44, s72
	s_cbranch_scc0 .LBB0_1345

; #define PG8_STAGE(bufoff, gbase, voff) do { _Pragma("unroll") for (int _i = 0; _i < 2; ++_i) \
;         __builtin_amdgcn_global_load_lds((const unsigned*)((const char*)(gbase) + (voff)[_i]), (PG8_LAS unsigned*)(lds + (bufoff) + ldsw + _i * 8192), 16, 0, 0); } while (0)
; #define PG8_LDA(dst, b, h) do { _Pragma("unroll") for (int m = 0; m < 4; ++m) _Pragma("unroll") for (int k = 0; k < 2; ++k) dst[m][k] = *(const PG8_LAS bf16x8*)(lds + PG8_SA(b, h) + aoff + m * 2048 + k * 1024); } while (0)
; #define PG8_LDB(dst, b, h) do { _Pragma("unroll") for (int n = 0; n < 2; ++n) _Pragma("unroll") for (int k = 0; k < 2; ++k) dst[n][k] = *(const PG8_LAS bf16x8*)(lds + PG8_SB(b, h) + boff + n * 2048 + k * 1024); } while (0)
; #define PG8_MMA(ai, bj, At, Bt) do { __builtin_amdgcn_s_setprio(1); _Pragma("unroll") for (int m = 0; m < 4; ++m) _Pragma("unroll") for (int n = 0; n < 2; ++n) _Pragma("unroll") for (int k = 0; k < 2; ++k) \
;         acc[ai][bj][m][n] = __builtin_amdgcn_mfma_f32_16x16x32_bf16(Bt[n][k], At[m][k], acc[ai][bj][m][n], 0, 0, 0); __builtin_amdgcn_s_setprio(0); } while (0)
; #define PG8_WAIT_V(n) asm volatile("s_waitcnt vmcnt(" #n ")" ::: "memory")
; #define PG8_WAIT_L(n) asm volatile("s_waitcnt lgkmcnt(" #n ")" ::: "memory")
; #define PG8_BAR __builtin_amdgcn_s_barrier()
; #define PG8_SCHED __builtin_amdgcn_sched_barrier(0)
; template <class Epi, class Sched, bool ALIGN_EPI = false, bool SP2 = false>
; __device__ __forceinline__ void gemm_phase(PG8_LAS unsigned char* lds, const Gemm g, const Sched& S, const Epi& E) {
;     ...
;             const bool last = (t == nt - 2);
;             const char* a1 = cA + (size_t)(t + 1) * kstep;
;             const char* a2 = last ? nA : cA + (size_t)(t + 2) * kstep; const char* b2 = last ? nB : cB + (size_t)(t + 2) * kstep;
;             const char* a3 = a2 + kstep; const char* b3 = b2 + kstep;
;             if (last && has_next) S.a_ready(nxt);
;             if constexpr (SP2) {
;             PG8_LDB(B0, 0, 0); PG8_LDB(B1, 0, 1); PG8_SCHED; PG8_LDA(At, 0, 0); PG8_STAGE(PG8_SA(1, 1), a1 + hstep, voffA);
;             PG8_WAIT_V(8); PG8_WAIT_L(0); PG8_BAR; PG8_MMA(0, 0, At, B0); PG8_MMA(0, 1, At, B1); PG8_BAR; PG8_SCHED;
;             PG8_LDA(At, 0, 1); PG8_STAGE(PG8_SB(0, 0), b2, voffB); PG8_STAGE(PG8_SB(0, 1), b2 + hstep, voffB); PG8_STAGE(PG8_SA(0, 0), a2, voffA);
.LBB0_1533:
	ds_read_b128 v[166:169], v163
	ds_read_b128 v[170:173], v163 offset:1024
	ds_read_b128 v[174:177], v163 offset:2048
	ds_read_b128 v[178:181], v163 offset:3072
	ds_read_b128 v[182:185], v164
	ds_read_b128 v[186:189], v164 offset:1024
	ds_read_b128 v[190:193], v164 offset:2048
	ds_read_b128 v[194:197], v164 offset:3072
	s_add_i32 s55, s28, 2
	s_add_u32 s58, s26, 0x80
	s_addc_u32 s29, s27, 0
	s_cmp_eq_u32 s45, s28
	s_cselect_b32 s28, s8, s58
	s_cselect_b32 s29, s9, s29
	s_cselect_b32 s59, s25, s1
	s_cselect_b32 s58, s24, s0
	v_lshl_add_u64 v[230:231], s[26:27], 0, v[136:137]
	s_add_i32 m0, s37, 0xc000
	ds_read_b128 v[198:201], v165
	ds_read_b128 v[202:205], v165 offset:1024
	ds_read_b128 v[206:209], v165 offset:2048
	ds_read_b128 v[210:213], v165 offset:3072
	ds_read_b128 v[214:217], v165 offset:4096
	ds_read_b128 v[218:221], v165 offset:5120
	ds_read_b128 v[222:225], v165 offset:6144
	ds_read_b128 v[226:229], v165 offset:7168
	global_load_lds_dwordx4 v[230:231], off
	v_lshl_add_u64 v[230:231], s[26:27], 0, v[138:139]
	s_add_i32 m0, s37, 0xe000
	s_nop 0
	global_load_lds_dwordx4 v[230:231], off
	s_waitcnt vmcnt(8)
	s_waitcnt lgkmcnt(0)
	s_barrier
	s_setprio 1
	s_waitcnt lgkmcnt(0)
	v_mfma_f32_16x16x32_bf16 v[124:127], v[166:169], v[198:201], v[124:127]
	v_mfma_f32_16x16x32_bf16 v[116:119], v[174:177], v[198:201], v[116:119]
	v_mfma_f32_16x16x32_bf16 v[108:111], v[166:169], v[206:209], v[108:111]
	v_mfma_f32_16x16x32_bf16 v[100:103], v[174:177], v[206:209], v[100:103]
	v_mfma_f32_16x16x32_bf16 v[92:95], v[166:169], v[214:217], v[92:95]
	v_mfma_f32_16x16x32_bf16 v[84:87], v[174:177], v[214:217], v[84:87]
	v_mfma_f32_16x16x32_bf16 v[76:79], v[166:169], v[222:225], v[76:79]
	v_mfma_f32_16x16x32_bf16 v[68:71], v[174:177], v[222:225], v[68:71]
	v_mfma_f32_16x16x32_bf16 v[124:127], v[170:173], v[202:205], v[124:127]
	v_mfma_f32_16x16x32_bf16 v[116:119], v[178:181], v[202:205], v[116:119]
	v_mfma_f32_16x16x32_bf16 v[108:111], v[170:173], v[210:213], v[108:111]
	v_mfma_f32_16x16x32_bf16 v[100:103], v[178:181], v[210:213], v[100:103]
	v_mfma_f32_16x16x32_bf16 v[92:95], v[170:173], v[218:221], v[92:95]
	v_mfma_f32_16x16x32_bf16 v[84:87], v[178:181], v[218:221], v[84:87]
	v_mfma_f32_16x16x32_bf16 v[76:79], v[170:173], v[226:229], v[76:79]
	v_mfma_f32_16x16x32_bf16 v[68:71], v[178:181], v[226:229], v[68:71]
	v_mfma_f32_16x16x32_bf16 v[120:123], v[182:185], v[198:201], v[120:123]
	v_mfma_f32_16x16x32_bf16 v[112:115], v[190:193], v[198:201], v[112:115]
	v_mfma_f32_16x16x32_bf16 v[104:107], v[182:185], v[206:209], v[104:107]
	v_mfma_f32_16x16x32_bf16 v[96:99], v[190:193], v[206:209], v[96:99]
	v_mfma_f32_16x16x32_bf16 v[88:91], v[182:185], v[214:217], v[88:91]
	v_mfma_f32_16x16x32_bf16 v[80:83], v[190:193], v[214:217], v[80:83]
	v_mfma_f32_16x16x32_bf16 v[72:75], v[182:185], v[222:225], v[72:75]
	v_mfma_f32_16x16x32_bf16 v[64:67], v[190:193], v[222:225], v[64:67]
	v_mfma_f32_16x16x32_bf16 v[120:123], v[186:189], v[202:205], v[120:123]
	v_mfma_f32_16x16x32_bf16 v[112:115], v[194:197], v[202:205], v[112:115]
	v_mfma_f32_16x16x32_bf16 v[104:107], v[186:189], v[210:213], v[104:107]
	v_mfma_f32_16x16x32_bf16 v[96:99], v[194:197], v[210:213], v[96:99]
	v_mfma_f32_16x16x32_bf16 v[88:91], v[186:189], v[218:221], v[88:91]
	v_mfma_f32_16x16x32_bf16 v[80:83], v[194:197], v[218:221], v[80:83]
	v_mfma_f32_16x16x32_bf16 v[72:75], v[186:189], v[226:229], v[72:75]
	v_mfma_f32_16x16x32_bf16 v[64:67], v[194:197], v[226:229], v[64:67]
	s_setprio 0
	s_barrier
	s_add_i32 s60, s48, s36
	v_lshl_add_u64 v[230:231], s[58:59], 0, v[130:131]
	s_mov_b32 m0, s60
	ds_read_b128 v[198:201], v165 offset:16384
	ds_read_b128 v[202:205], v165 offset:17408
	ds_read_b128 v[206:209], v165 offset:18432
	ds_read_b128 v[210:213], v165 offset:19456
	ds_read_b128 v[214:217], v165 offset:20480
	ds_read_b128 v[218:221], v165 offset:21504
	ds_read_b128 v[222:225], v165 offset:22528
	ds_read_b128 v[226:229], v165 offset:23552
	global_load_lds_dwordx4 v[230:231], off
	s_add_i32 m0, s60, 0x2000
	v_lshl_add_u64 v[232:233], s[58:59], 0, v[134:135]
	s_add_u32 s58, s58, s10
	s_addc_u32 s59, s59, s11
	s_add_i32 s60, s49, s36
	global_load_lds_dwordx4 v[232:233], off
	v_lshl_add_u64 v[234:235], s[58:59], 0, v[130:131]
	s_mov_b32 m0, s60
	v_lshl_add_u64 v[236:237], s[58:59], 0, v[134:135]
	global_load_lds_dwordx4 v[234:235], off
	s_add_i32 m0, s60, 0x2000
	v_lshl_add_u64 v[238:239], s[28:29], 0, v[128:129]
	global_load_lds_dwordx4 v[236:237], off
	s_mov_b32 m0, s37
	v_lshl_add_u64 v[240:241], s[28:29], 0, v[132:133]
	global_load_lds_dwordx4 v[238:239], off
	s_mov_b32 m0, s38
	s_nop 0
	global_load_lds_dwordx4 v[240:241], off
	s_waitcnt vmcnt(8)
	s_waitcnt lgkmcnt(0)
	s_barrier
; #define PG8_STAGE(bufoff, gbase, voff) do { _Pragma("unroll") for (int _i = 0; _i < 2; ++_i) \
;         __builtin_amdgcn_global_load_lds((const unsigned*)((const char*)(gbase) + (voff)[_i]), (PG8_LAS unsigned*)(lds + (bufoff) + ldsw + _i * 8192), 16, 0, 0); } while (0)
; #define PG8_LDA(dst, b, h) do { _Pragma("unroll") for (int m = 0; m < 4; ++m) _Pragma("unroll") for (int k = 0; k < 2; ++k) dst[m][k] = *(const PG8_LAS bf16x8*)(lds + PG8_SA(b, h) + aoff + m * 2048 + k * 1024); } while (0)
; #define PG8_LDB(dst, b, h) do { _Pragma("unroll") for (int n = 0; n < 2; ++n) _Pragma("unroll") for (int k = 0; k < 2; ++k) dst[n][k] = *(const PG8_LAS bf16x8*)(lds + PG8_SB(b, h) + boff + n * 2048 + k * 1024); } while (0)
; #define PG8_MMA(ai, bj, At, Bt) do { __builtin_amdgcn_s_setprio(1); _Pragma("unroll") for (int m = 0; m < 4; ++m) _Pragma("unroll") for (int n = 0; n < 2; ++n) _Pragma("unroll") for (int k = 0; k < 2; ++k) \
;         acc[ai][bj][m][n] = __builtin_amdgcn_mfma_f32_16x16x32_bf16(Bt[n][k], At[m][k], acc[ai][bj][m][n], 0, 0, 0); __builtin_amdgcn_s_setprio(0); } while (0)
; #define PG8_WAIT_V(n) asm volatile("s_waitcnt vmcnt(" #n ")" ::: "memory")
; #define PG8_WAIT_L(n) asm volatile("s_waitcnt lgkmcnt(" #n ")" ::: "memory")
; #define PG8_BAR __builtin_amdgcn_s_barrier()
; #define PG8_SCHED __builtin_amdgcn_sched_barrier(0)
; template <class Epi, class Sched, bool ALIGN_EPI = false, bool SP2 = false>
; __device__ __forceinline__ void gemm_phase(PG8_LAS unsigned char* lds, const Gemm g, const Sched& S, const Epi& E) {
;     ...
;             PG8_WAIT_V(8); PG8_WAIT_L(0); PG8_BAR; PG8_MMA(1, 0, At, B0); PG8_MMA(1, 1, At, B1); PG8_BAR; PG8_SCHED;
;             PG8_LDB(B0, 1, 0); PG8_LDB(B1, 1, 1); PG8_SCHED; PG8_LDA(At, 1, 0); PG8_STAGE(PG8_SA(0, 1), a2 + hstep, voffA);
;             PG8_WAIT_V(8); PG8_WAIT_L(0); PG8_BAR; PG8_MMA(0, 0, At, B0); PG8_MMA(0, 1, At, B1); PG8_BAR; PG8_SCHED;
	s_setprio 1
	s_waitcnt lgkmcnt(0)
	v_mfma_f32_16x16x32_bf16 v[60:63], v[166:169], v[198:201], v[60:63]
	v_mfma_f32_16x16x32_bf16 v[52:55], v[174:177], v[198:201], v[52:55]
	v_mfma_f32_16x16x32_bf16 v[44:47], v[166:169], v[206:209], v[44:47]
	v_mfma_f32_16x16x32_bf16 v[36:39], v[174:177], v[206:209], v[36:39]
	v_mfma_f32_16x16x32_bf16 v[28:31], v[166:169], v[214:217], v[28:31]
	v_mfma_f32_16x16x32_bf16 v[20:23], v[174:177], v[214:217], v[20:23]
	v_mfma_f32_16x16x32_bf16 v[12:15], v[166:169], v[222:225], v[12:15]
	v_mfma_f32_16x16x32_bf16 v[4:7], v[174:177], v[222:225], v[4:7]
	v_mfma_f32_16x16x32_bf16 v[60:63], v[170:173], v[202:205], v[60:63]
	v_mfma_f32_16x16x32_bf16 v[52:55], v[178:181], v[202:205], v[52:55]
	v_mfma_f32_16x16x32_bf16 v[44:47], v[170:173], v[210:213], v[44:47]
	v_mfma_f32_16x16x32_bf16 v[36:39], v[178:181], v[210:213], v[36:39]
	v_mfma_f32_16x16x32_bf16 v[28:31], v[170:173], v[218:221], v[28:31]
	v_mfma_f32_16x16x32_bf16 v[20:23], v[178:181], v[218:221], v[20:23]
	v_mfma_f32_16x16x32_bf16 v[12:15], v[170:173], v[226:229], v[12:15]
	v_mfma_f32_16x16x32_bf16 v[4:7], v[178:181], v[226:229], v[4:7]
	v_mfma_f32_16x16x32_bf16 v[56:59], v[182:185], v[198:201], v[56:59]
	v_mfma_f32_16x16x32_bf16 v[48:51], v[190:193], v[198:201], v[48:51]
	v_mfma_f32_16x16x32_bf16 v[40:43], v[182:185], v[206:209], v[40:43]
	v_mfma_f32_16x16x32_bf16 v[32:35], v[190:193], v[206:209], v[32:35]
	v_mfma_f32_16x16x32_bf16 v[24:27], v[182:185], v[214:217], v[24:27]
	v_mfma_f32_16x16x32_bf16 v[16:19], v[190:193], v[214:217], v[16:19]
	v_mfma_f32_16x16x32_bf16 v[8:11], v[182:185], v[222:225], v[8:11]
	v_mfma_f32_16x16x32_bf16 v[0:3], v[190:193], v[222:225], v[0:3]
	v_mfma_f32_16x16x32_bf16 v[56:59], v[186:189], v[202:205], v[56:59]
	v_mfma_f32_16x16x32_bf16 v[48:51], v[194:197], v[202:205], v[48:51]
	v_mfma_f32_16x16x32_bf16 v[40:43], v[186:189], v[210:213], v[40:43]
	v_mfma_f32_16x16x32_bf16 v[32:35], v[194:197], v[210:213], v[32:35]
	v_mfma_f32_16x16x32_bf16 v[24:27], v[186:189], v[218:221], v[24:27]
	v_mfma_f32_16x16x32_bf16 v[16:19], v[194:197], v[218:221], v[16:19]
	v_mfma_f32_16x16x32_bf16 v[8:11], v[186:189], v[226:229], v[8:11]
	v_mfma_f32_16x16x32_bf16 v[0:3], v[194:197], v[226:229], v[0:3]
	s_setprio 0
	s_barrier
	s_add_i32 s58, 0, 0x18000
	s_add_i32 s59, 0, 0x1c000
	v_add_u32_e32 v178, s58, v161
	v_add_u32_e32 v194, s59, v161
	ds_read_b128 v[166:169], v178
	ds_read_b128 v[170:173], v178 offset:1024
	ds_read_b128 v[174:177], v178 offset:2048
	ds_read_b128 v[178:181], v178 offset:3072
	ds_read_b128 v[182:185], v194
	ds_read_b128 v[186:189], v194 offset:1024
	ds_read_b128 v[190:193], v194 offset:2048
	ds_read_b128 v[194:197], v194 offset:3072
	s_add_u32 s28, s28, s10
	s_addc_u32 s29, s29, s11
	s_mov_b32 m0, s39
	v_lshl_add_u64 v[242:243], s[28:29], 0, v[128:129]
	ds_read_b128 v[198:201], v165 offset:32768
	ds_read_b128 v[202:205], v165 offset:33792
	ds_read_b128 v[206:209], v165 offset:34816
	ds_read_b128 v[210:213], v165 offset:35840
	ds_read_b128 v[214:217], v165 offset:36864
	ds_read_b128 v[218:221], v165 offset:37888
	ds_read_b128 v[222:225], v165 offset:38912
	ds_read_b128 v[226:229], v165 offset:39936
	global_load_lds_dwordx4 v[242:243], off
	v_lshl_add_u64 v[242:243], s[28:29], 0, v[132:133]
	s_mov_b32 m0, s40
	s_nop 0
	global_load_lds_dwordx4 v[242:243], off
	s_waitcnt vmcnt(8)
	s_waitcnt lgkmcnt(0)
	s_barrier
	s_setprio 1
	s_waitcnt lgkmcnt(0)
	v_mfma_f32_16x16x32_bf16 v[124:127], v[166:169], v[198:201], v[124:127]
	v_mfma_f32_16x16x32_bf16 v[116:119], v[174:177], v[198:201], v[116:119]
	v_mfma_f32_16x16x32_bf16 v[108:111], v[166:169], v[206:209], v[108:111]
	v_mfma_f32_16x16x32_bf16 v[100:103], v[174:177], v[206:209], v[100:103]
	v_mfma_f32_16x16x32_bf16 v[92:95], v[166:169], v[214:217], v[92:95]
	v_mfma_f32_16x16x32_bf16 v[84:87], v[174:177], v[214:217], v[84:87]
	v_mfma_f32_16x16x32_bf16 v[76:79], v[166:169], v[222:225], v[76:79]
	v_mfma_f32_16x16x32_bf16 v[68:71], v[174:177], v[222:225], v[68:71]
	v_mfma_f32_16x16x32_bf16 v[124:127], v[170:173], v[202:205], v[124:127]
	v_mfma_f32_16x16x32_bf16 v[116:119], v[178:181], v[202:205], v[116:119]
	v_mfma_f32_16x16x32_bf16 v[108:111], v[170:173], v[210:213], v[108:111]
	v_mfma_f32_16x16x32_bf16 v[100:103], v[178:181], v[210:213], v[100:103]
	v_mfma_f32_16x16x32_bf16 v[92:95], v[170:173], v[218:221], v[92:95]
	v_mfma_f32_16x16x32_bf16 v[84:87], v[178:181], v[218:221], v[84:87]
	v_mfma_f32_16x16x32_bf16 v[76:79], v[170:173], v[226:229], v[76:79]
	v_mfma_f32_16x16x32_bf16 v[68:71], v[178:181], v[226:229], v[68:71]
	v_mfma_f32_16x16x32_bf16 v[120:123], v[182:185], v[198:201], v[120:123]
	v_mfma_f32_16x16x32_bf16 v[112:115], v[190:193], v[198:201], v[112:115]
	v_mfma_f32_16x16x32_bf16 v[104:107], v[182:185], v[206:209], v[104:107]
	v_mfma_f32_16x16x32_bf16 v[96:99], v[190:193], v[206:209], v[96:99]
	v_mfma_f32_16x16x32_bf16 v[88:91], v[182:185], v[214:217], v[88:91]
	v_mfma_f32_16x16x32_bf16 v[80:83], v[190:193], v[214:217], v[80:83]
	v_mfma_f32_16x16x32_bf16 v[72:75], v[182:185], v[222:225], v[72:75]
	v_mfma_f32_16x16x32_bf16 v[64:67], v[190:193], v[222:225], v[64:67]
	v_mfma_f32_16x16x32_bf16 v[120:123], v[186:189], v[202:205], v[120:123]
	v_mfma_f32_16x16x32_bf16 v[112:115], v[194:197], v[202:205], v[112:115]
	v_mfma_f32_16x16x32_bf16 v[104:107], v[186:189], v[210:213], v[104:107]
	v_mfma_f32_16x16x32_bf16 v[96:99], v[194:197], v[210:213], v[96:99]
	v_mfma_f32_16x16x32_bf16 v[88:91], v[186:189], v[218:221], v[88:91]
	v_mfma_f32_16x16x32_bf16 v[80:83], v[194:197], v[218:221], v[80:83]
	v_mfma_f32_16x16x32_bf16 v[72:75], v[186:189], v[226:229], v[72:75]
	v_mfma_f32_16x16x32_bf16 v[64:67], v[194:197], v[226:229], v[64:67]
	s_setprio 0
	s_barrier
; #define PG8_STAGE(bufoff, gbase, voff) do { _Pragma("unroll") for (int _i = 0; _i < 2; ++_i) \
;         __builtin_amdgcn_global_load_lds((const unsigned*)((const char*)(gbase) + (voff)[_i]), (PG8_LAS unsigned*)(lds + (bufoff) + ldsw + _i * 8192), 16, 0, 0); } while (0)
; #define PG8_LDA(dst, b, h) do { _Pragma("unroll") for (int m = 0; m < 4; ++m) _Pragma("unroll") for (int k = 0; k < 2; ++k) dst[m][k] = *(const PG8_LAS bf16x8*)(lds + PG8_SA(b, h) + aoff + m * 2048 + k * 1024); } while (0)
; #define PG8_MMA(ai, bj, At, Bt) do { __builtin_amdgcn_s_setprio(1); _Pragma("unroll") for (int m = 0; m < 4; ++m) _Pragma("unroll") for (int n = 0; n < 2; ++n) _Pragma("unroll") for (int k = 0; k < 2; ++k) \
;         acc[ai][bj][m][n] = __builtin_amdgcn_mfma_f32_16x16x32_bf16(Bt[n][k], At[m][k], acc[ai][bj][m][n], 0, 0, 0); __builtin_amdgcn_s_setprio(0); } while (0)
; #define PG8_WAIT_V(n) asm volatile("s_waitcnt vmcnt(" #n ")" ::: "memory")
; #define PG8_WAIT_L(n) asm volatile("s_waitcnt lgkmcnt(" #n ")" ::: "memory")
; #define PG8_BAR __builtin_amdgcn_s_barrier()
; #define PG8_SCHED __builtin_amdgcn_sched_barrier(0)
; template <class Epi, class Sched, bool ALIGN_EPI = false, bool SP2 = false>
; __device__ __forceinline__ void gemm_phase(PG8_LAS unsigned char* lds, const Gemm g, const Sched& S, const Epi& E) {
;     ...
;         for (int t = 0; t < nt; t += 2) {
;             const bool last = (t == nt - 2);
;     ...
;             PG8_LDA(At, 1, 1); PG8_STAGE(PG8_SB(1, 0), b3, voffB); PG8_STAGE(PG8_SB(1, 1), b3 + hstep, voffB); PG8_STAGE(PG8_SA(1, 0), a3, voffA);
;             PG8_WAIT_V(8); PG8_WAIT_L(0); PG8_BAR; PG8_MMA(1, 0, At, B0); PG8_MMA(1, 1, At, B1); PG8_BAR; PG8_SCHED;
	s_add_i32 s28, s58, s36
	v_lshl_add_u64 v[230:231], v[230:231], 0, s[18:19]
	s_mov_b32 m0, s28
	ds_read_b128 v[198:201], v165 offset:49152
	ds_read_b128 v[202:205], v165 offset:50176
	ds_read_b128 v[206:209], v165 offset:51200
	ds_read_b128 v[210:213], v165 offset:52224
	ds_read_b128 v[214:217], v165 offset:53248
	ds_read_b128 v[218:221], v165 offset:54272
	ds_read_b128 v[222:225], v165 offset:55296
	ds_read_b128 v[226:229], v165 offset:56320
	global_load_lds_dwordx4 v[230:231], off
	v_lshl_add_u64 v[230:231], v[232:233], 0, s[18:19]
	s_add_i32 m0, s28, 0x2000
	s_add_i32 s28, s59, s36
	global_load_lds_dwordx4 v[230:231], off
	v_lshl_add_u64 v[230:231], v[234:235], 0, s[18:19]
	s_mov_b32 m0, s28
	s_nop 0
	global_load_lds_dwordx4 v[230:231], off
	v_lshl_add_u64 v[230:231], v[236:237], 0, s[18:19]
	s_add_i32 m0, s28, 0x2000
	s_nop 0
	global_load_lds_dwordx4 v[230:231], off
	v_lshl_add_u64 v[230:231], v[238:239], 0, s[18:19]
	s_mov_b32 m0, s42
	s_nop 0
	global_load_lds_dwordx4 v[230:231], off
	v_lshl_add_u64 v[230:231], v[240:241], 0, s[18:19]
	s_mov_b32 m0, s43
	s_nop 0
	global_load_lds_dwordx4 v[230:231], off
	s_waitcnt vmcnt(8)
	s_waitcnt lgkmcnt(0)
	s_barrier
	s_setprio 1
	s_waitcnt lgkmcnt(0)
	v_mfma_f32_16x16x32_bf16 v[60:63], v[166:169], v[198:201], v[60:63]
	v_mfma_f32_16x16x32_bf16 v[52:55], v[174:177], v[198:201], v[52:55]
	v_mfma_f32_16x16x32_bf16 v[44:47], v[166:169], v[206:209], v[44:47]
	v_mfma_f32_16x16x32_bf16 v[36:39], v[174:177], v[206:209], v[36:39]
	v_mfma_f32_16x16x32_bf16 v[28:31], v[166:169], v[214:217], v[28:31]
	v_mfma_f32_16x16x32_bf16 v[20:23], v[174:177], v[214:217], v[20:23]
	v_mfma_f32_16x16x32_bf16 v[12:15], v[166:169], v[222:225], v[12:15]
	v_mfma_f32_16x16x32_bf16 v[4:7], v[174:177], v[222:225], v[4:7]
	v_mfma_f32_16x16x32_bf16 v[60:63], v[170:173], v[202:205], v[60:63]
	v_mfma_f32_16x16x32_bf16 v[52:55], v[178:181], v[202:205], v[52:55]
	v_mfma_f32_16x16x32_bf16 v[44:47], v[170:173], v[210:213], v[44:47]
	v_mfma_f32_16x16x32_bf16 v[36:39], v[178:181], v[210:213], v[36:39]
	v_mfma_f32_16x16x32_bf16 v[28:31], v[170:173], v[218:221], v[28:31]
	v_mfma_f32_16x16x32_bf16 v[20:23], v[178:181], v[218:221], v[20:23]
	v_mfma_f32_16x16x32_bf16 v[12:15], v[170:173], v[226:229], v[12:15]
	v_mfma_f32_16x16x32_bf16 v[4:7], v[178:181], v[226:229], v[4:7]
	v_mfma_f32_16x16x32_bf16 v[56:59], v[182:185], v[198:201], v[56:59]
	v_mfma_f32_16x16x32_bf16 v[48:51], v[190:193], v[198:201], v[48:51]
	v_mfma_f32_16x16x32_bf16 v[40:43], v[182:185], v[206:209], v[40:43]
	v_mfma_f32_16x16x32_bf16 v[32:35], v[190:193], v[206:209], v[32:35]
	v_mfma_f32_16x16x32_bf16 v[24:27], v[182:185], v[214:217], v[24:27]
	v_mfma_f32_16x16x32_bf16 v[16:19], v[190:193], v[214:217], v[16:19]
	v_mfma_f32_16x16x32_bf16 v[8:11], v[182:185], v[222:225], v[8:11]
	v_mfma_f32_16x16x32_bf16 v[0:3], v[190:193], v[222:225], v[0:3]
	v_mfma_f32_16x16x32_bf16 v[56:59], v[186:189], v[202:205], v[56:59]
	v_mfma_f32_16x16x32_bf16 v[48:51], v[194:197], v[202:205], v[48:51]
	v_mfma_f32_16x16x32_bf16 v[40:43], v[186:189], v[210:213], v[40:43]
	v_mfma_f32_16x16x32_bf16 v[32:35], v[194:197], v[210:213], v[32:35]
	v_mfma_f32_16x16x32_bf16 v[24:27], v[186:189], v[218:221], v[24:27]
	v_mfma_f32_16x16x32_bf16 v[16:19], v[194:197], v[218:221], v[16:19]
	v_mfma_f32_16x16x32_bf16 v[8:11], v[186:189], v[226:229], v[8:11]
	v_mfma_f32_16x16x32_bf16 v[0:3], v[194:197], v[226:229], v[0:3]
	s_setprio 0
	s_barrier
	s_add_u32 s26, s26, 0x100
	s_addc_u32 s27, s27, 0
	s_add_u32 s0, s0, 0x100
	s_addc_u32 s1, s1, 0
	s_cmp_ge_i32 s55, s44
	s_mov_b32 s28, s55
	s_cbranch_scc0 .LBB0_1533

; #define PG8_STAGE(bufoff, gbase, voff) do { _Pragma("unroll") for (int _i = 0; _i < 2; ++_i) \
;         __builtin_amdgcn_global_load_lds((const unsigned*)((const char*)(gbase) + (voff)[_i]), (PG8_LAS unsigned*)(lds + (bufoff) + ldsw + _i * 8192), 16, 0, 0); } while (0)
; #define PG8_LDA(dst, b, h) do { _Pragma("unroll") for (int m = 0; m < 4; ++m) _Pragma("unroll") for (int k = 0; k < 2; ++k) dst[m][k] = *(const PG8_LAS bf16x8*)(lds + PG8_SA(b, h) + aoff + m * 2048 + k * 1024); } while (0)
; #define PG8_LDB(dst, b, h) do { _Pragma("unroll") for (int n = 0; n < 2; ++n) _Pragma("unroll") for (int k = 0; k < 2; ++k) dst[n][k] = *(const PG8_LAS bf16x8*)(lds + PG8_SB(b, h) + boff + n * 2048 + k * 1024); } while (0)
; #define PG8_MMA(ai, bj, At, Bt) do { __builtin_amdgcn_s_setprio(1); _Pragma("unroll") for (int m = 0; m < 4; ++m) _Pragma("unroll") for (int n = 0; n < 2; ++n) _Pragma("unroll") for (int k = 0; k < 2; ++k) \
;         acc[ai][bj][m][n] = __builtin_amdgcn_mfma_f32_16x16x32_bf16(Bt[n][k], At[m][k], acc[ai][bj][m][n], 0, 0, 0); __builtin_amdgcn_s_setprio(0); } while (0)
; #define PG8_WAIT_V(n) asm volatile("s_waitcnt vmcnt(" #n ")" ::: "memory")
; #define PG8_WAIT_L(n) asm volatile("s_waitcnt lgkmcnt(" #n ")" ::: "memory")
; template <class Epi, class Sched, bool ALIGN_EPI = false, bool SP2 = false>
; __device__ __forceinline__ void gemm_phase(PG8_LAS unsigned char* lds, const Gemm g, const Sched& S, const Epi& E) {
;     ...
;             const bool last = (t == nt - 2);
;             const char* a1 = cA + (size_t)(t + 1) * kstep;
;             const char* a2 = last ? nA : cA + (size_t)(t + 2) * kstep; const char* b2 = last ? nB : cB + (size_t)(t + 2) * kstep;
;             const char* a3 = a2 + kstep; const char* b3 = b2 + kstep;
;             if (last && has_next) S.a_ready(nxt);
;             if constexpr (SP2) {
;             PG8_LDB(B0, 0, 0); PG8_LDB(B1, 0, 1); PG8_SCHED; PG8_LDA(At, 0, 0); PG8_STAGE(PG8_SA(1, 1), a1 + hstep, voffA);
;             PG8_WAIT_V(8); PG8_WAIT_L(0); PG8_BAR; PG8_MMA(0, 0, At, B0); PG8_MMA(0, 1, At, B1); PG8_BAR; PG8_SCHED;
;             PG8_LDA(At, 0, 1); PG8_STAGE(PG8_SB(0, 0), b2, voffB); PG8_STAGE(PG8_SB(0, 1), b2 + hstep, voffB); PG8_STAGE(PG8_SA(0, 0), a2, voffA);
;             PG8_WAIT_V(8); PG8_WAIT_L(0); PG8_BAR; PG8_MMA(1, 0, At, B0); PG8_MMA(1, 1, At, B1); PG8_BAR; PG8_SCHED;
.LBB0_1569:
	ds_read_b128 v[166:169], v163
	ds_read_b128 v[170:173], v163 offset:1024
	ds_read_b128 v[174:177], v163 offset:2048
	ds_read_b128 v[178:181], v163 offset:3072
	ds_read_b128 v[182:185], v164
	ds_read_b128 v[186:189], v164 offset:1024
	ds_read_b128 v[190:193], v164 offset:2048
	ds_read_b128 v[194:197], v164 offset:3072
	s_add_i32 s68, s38, 2
	s_add_u32 s69, s36, 0x80
	s_addc_u32 s39, s37, 0
	s_cmp_eq_u32 s54, s38
	s_cselect_b32 s38, s8, s69
	s_cselect_b32 s39, s9, s39
	s_cselect_b32 s71, s35, s1
	s_cselect_b32 s70, s34, s0
	v_lshl_add_u64 v[230:231], s[36:37], 0, v[136:137]
	s_add_i32 m0, s46, 0xc000
	ds_read_b128 v[198:201], v165
	ds_read_b128 v[202:205], v165 offset:1024
	ds_read_b128 v[206:209], v165 offset:2048
	ds_read_b128 v[210:213], v165 offset:3072
	ds_read_b128 v[214:217], v165 offset:4096
	ds_read_b128 v[218:221], v165 offset:5120
	ds_read_b128 v[222:225], v165 offset:6144
	ds_read_b128 v[226:229], v165 offset:7168
	global_load_lds_dwordx4 v[230:231], off
	v_lshl_add_u64 v[230:231], s[36:37], 0, v[138:139]
	s_add_i32 m0, s46, 0xe000
	s_nop 0
	global_load_lds_dwordx4 v[230:231], off
	s_waitcnt vmcnt(8)
	s_waitcnt lgkmcnt(0)
	s_barrier
	s_setprio 1
	s_waitcnt lgkmcnt(0)
	v_mfma_f32_16x16x32_bf16 v[120:123], v[166:169], v[198:201], v[120:123]
	v_mfma_f32_16x16x32_bf16 v[124:127], v[174:177], v[198:201], v[124:127]
	v_mfma_f32_16x16x32_bf16 v[108:111], v[166:169], v[206:209], v[108:111]
	v_mfma_f32_16x16x32_bf16 v[104:107], v[174:177], v[206:209], v[104:107]
	v_mfma_f32_16x16x32_bf16 v[92:95], v[166:169], v[214:217], v[92:95]
	v_mfma_f32_16x16x32_bf16 v[88:91], v[174:177], v[214:217], v[88:91]
	v_mfma_f32_16x16x32_bf16 v[76:79], v[166:169], v[222:225], v[76:79]
	v_mfma_f32_16x16x32_bf16 v[72:75], v[174:177], v[222:225], v[72:75]
	v_mfma_f32_16x16x32_bf16 v[120:123], v[170:173], v[202:205], v[120:123]
	v_mfma_f32_16x16x32_bf16 v[124:127], v[178:181], v[202:205], v[124:127]
	v_mfma_f32_16x16x32_bf16 v[108:111], v[170:173], v[210:213], v[108:111]
	v_mfma_f32_16x16x32_bf16 v[104:107], v[178:181], v[210:213], v[104:107]
	v_mfma_f32_16x16x32_bf16 v[92:95], v[170:173], v[218:221], v[92:95]
	v_mfma_f32_16x16x32_bf16 v[88:91], v[178:181], v[218:221], v[88:91]
	v_mfma_f32_16x16x32_bf16 v[76:79], v[170:173], v[226:229], v[76:79]
	v_mfma_f32_16x16x32_bf16 v[72:75], v[178:181], v[226:229], v[72:75]
	v_mfma_f32_16x16x32_bf16 v[116:119], v[182:185], v[198:201], v[116:119]
	v_mfma_f32_16x16x32_bf16 v[112:115], v[190:193], v[198:201], v[112:115]
	v_mfma_f32_16x16x32_bf16 v[100:103], v[182:185], v[206:209], v[100:103]
	v_mfma_f32_16x16x32_bf16 v[96:99], v[190:193], v[206:209], v[96:99]
	v_mfma_f32_16x16x32_bf16 v[84:87], v[182:185], v[214:217], v[84:87]
	v_mfma_f32_16x16x32_bf16 v[80:83], v[190:193], v[214:217], v[80:83]
	v_mfma_f32_16x16x32_bf16 v[68:71], v[182:185], v[222:225], v[68:71]
	v_mfma_f32_16x16x32_bf16 v[64:67], v[190:193], v[222:225], v[64:67]
	v_mfma_f32_16x16x32_bf16 v[116:119], v[186:189], v[202:205], v[116:119]
	v_mfma_f32_16x16x32_bf16 v[112:115], v[194:197], v[202:205], v[112:115]
	v_mfma_f32_16x16x32_bf16 v[100:103], v[186:189], v[210:213], v[100:103]
	v_mfma_f32_16x16x32_bf16 v[96:99], v[194:197], v[210:213], v[96:99]
	v_mfma_f32_16x16x32_bf16 v[84:87], v[186:189], v[218:221], v[84:87]
	v_mfma_f32_16x16x32_bf16 v[80:83], v[194:197], v[218:221], v[80:83]
	v_mfma_f32_16x16x32_bf16 v[68:71], v[186:189], v[226:229], v[68:71]
	v_mfma_f32_16x16x32_bf16 v[64:67], v[194:197], v[226:229], v[64:67]
	s_setprio 0
	s_barrier
	s_add_i32 s69, s59, s45
	v_lshl_add_u64 v[230:231], s[70:71], 0, v[130:131]
	s_mov_b32 m0, s69
	ds_read_b128 v[198:201], v165 offset:16384
	ds_read_b128 v[202:205], v165 offset:17408
	ds_read_b128 v[206:209], v165 offset:18432
	ds_read_b128 v[210:213], v165 offset:19456
	ds_read_b128 v[214:217], v165 offset:20480
	ds_read_b128 v[218:221], v165 offset:21504
	ds_read_b128 v[222:225], v165 offset:22528
	ds_read_b128 v[226:229], v165 offset:23552
	global_load_lds_dwordx4 v[230:231], off
	s_add_i32 m0, s69, 0x2000
	v_lshl_add_u64 v[232:233], s[70:71], 0, v[134:135]
	s_add_u32 s70, s70, s10
	s_addc_u32 s71, s71, s11
	s_add_i32 s69, s60, s45
	global_load_lds_dwordx4 v[232:233], off
	v_lshl_add_u64 v[234:235], s[70:71], 0, v[130:131]
	s_mov_b32 m0, s69
	v_lshl_add_u64 v[236:237], s[70:71], 0, v[134:135]
	global_load_lds_dwordx4 v[234:235], off
	s_add_i32 m0, s69, 0x2000
	v_lshl_add_u64 v[238:239], s[38:39], 0, v[128:129]
	global_load_lds_dwordx4 v[236:237], off
	s_mov_b32 m0, s46
	v_lshl_add_u64 v[240:241], s[38:39], 0, v[132:133]
	global_load_lds_dwordx4 v[238:239], off
	s_mov_b32 m0, s47
	s_nop 0
	global_load_lds_dwordx4 v[240:241], off
	s_waitcnt vmcnt(8)
	s_waitcnt lgkmcnt(0)
	s_barrier
; #define PG8_STAGE(bufoff, gbase, voff) do { _Pragma("unroll") for (int _i = 0; _i < 2; ++_i) \
;         __builtin_amdgcn_global_load_lds((const unsigned*)((const char*)(gbase) + (voff)[_i]), (PG8_LAS unsigned*)(lds + (bufoff) + ldsw + _i * 8192), 16, 0, 0); } while (0)
; #define PG8_LDA(dst, b, h) do { _Pragma("unroll") for (int m = 0; m < 4; ++m) _Pragma("unroll") for (int k = 0; k < 2; ++k) dst[m][k] = *(const PG8_LAS bf16x8*)(lds + PG8_SA(b, h) + aoff + m * 2048 + k * 1024); } while (0)
; #define PG8_LDB(dst, b, h) do { _Pragma("unroll") for (int n = 0; n < 2; ++n) _Pragma("unroll") for (int k = 0; k < 2; ++k) dst[n][k] = *(const PG8_LAS bf16x8*)(lds + PG8_SB(b, h) + boff + n * 2048 + k * 1024); } while (0)
; #define PG8_MMA(ai, bj, At, Bt) do { __builtin_amdgcn_s_setprio(1); _Pragma("unroll") for (int m = 0; m < 4; ++m) _Pragma("unroll") for (int n = 0; n < 2; ++n) _Pragma("unroll") for (int k = 0; k < 2; ++k) \
;         acc[ai][bj][m][n] = __builtin_amdgcn_mfma_f32_16x16x32_bf16(Bt[n][k], At[m][k], acc[ai][bj][m][n], 0, 0, 0); __builtin_amdgcn_s_setprio(0); } while (0)
; #define PG8_WAIT_V(n) asm volatile("s_waitcnt vmcnt(" #n ")" ::: "memory")
; #define PG8_WAIT_L(n) asm volatile("s_waitcnt lgkmcnt(" #n ")" ::: "memory")
; #define PG8_BAR __builtin_amdgcn_s_barrier()
; #define PG8_SCHED __builtin_amdgcn_sched_barrier(0)
; template <class Epi, class Sched, bool ALIGN_EPI = false, bool SP2 = false>
; __device__ __forceinline__ void gemm_phase(PG8_LAS unsigned char* lds, const Gemm g, const Sched& S, const Epi& E) {
;     ...
;             PG8_WAIT_V(8); PG8_WAIT_L(0); PG8_BAR; PG8_MMA(1, 0, At, B0); PG8_MMA(1, 1, At, B1); PG8_BAR; PG8_SCHED;
;             PG8_LDB(B0, 1, 0); PG8_LDB(B1, 1, 1); PG8_SCHED; PG8_LDA(At, 1, 0); PG8_STAGE(PG8_SA(0, 1), a2 + hstep, voffA);
;             PG8_WAIT_V(8); PG8_WAIT_L(0); PG8_BAR; PG8_MMA(0, 0, At, B0); PG8_MMA(0, 1, At, B1); PG8_BAR; PG8_SCHED;
	s_setprio 1
	s_waitcnt lgkmcnt(0)
	v_mfma_f32_16x16x32_bf16 v[60:63], v[166:169], v[198:201], v[60:63]
	v_mfma_f32_16x16x32_bf16 v[56:59], v[174:177], v[198:201], v[56:59]
	v_mfma_f32_16x16x32_bf16 v[44:47], v[166:169], v[206:209], v[44:47]
	v_mfma_f32_16x16x32_bf16 v[40:43], v[174:177], v[206:209], v[40:43]
	v_mfma_f32_16x16x32_bf16 v[28:31], v[166:169], v[214:217], v[28:31]
	v_mfma_f32_16x16x32_bf16 v[24:27], v[174:177], v[214:217], v[24:27]
	v_mfma_f32_16x16x32_bf16 v[12:15], v[166:169], v[222:225], v[12:15]
	v_mfma_f32_16x16x32_bf16 v[8:11], v[174:177], v[222:225], v[8:11]
	v_mfma_f32_16x16x32_bf16 v[60:63], v[170:173], v[202:205], v[60:63]
	v_mfma_f32_16x16x32_bf16 v[56:59], v[178:181], v[202:205], v[56:59]
	v_mfma_f32_16x16x32_bf16 v[44:47], v[170:173], v[210:213], v[44:47]
	v_mfma_f32_16x16x32_bf16 v[40:43], v[178:181], v[210:213], v[40:43]
	v_mfma_f32_16x16x32_bf16 v[28:31], v[170:173], v[218:221], v[28:31]
	v_mfma_f32_16x16x32_bf16 v[24:27], v[178:181], v[218:221], v[24:27]
	v_mfma_f32_16x16x32_bf16 v[12:15], v[170:173], v[226:229], v[12:15]
	v_mfma_f32_16x16x32_bf16 v[8:11], v[178:181], v[226:229], v[8:11]
	v_mfma_f32_16x16x32_bf16 v[52:55], v[182:185], v[198:201], v[52:55]
	v_mfma_f32_16x16x32_bf16 v[48:51], v[190:193], v[198:201], v[48:51]
	v_mfma_f32_16x16x32_bf16 v[36:39], v[182:185], v[206:209], v[36:39]
	v_mfma_f32_16x16x32_bf16 v[32:35], v[190:193], v[206:209], v[32:35]
	v_mfma_f32_16x16x32_bf16 v[20:23], v[182:185], v[214:217], v[20:23]
	v_mfma_f32_16x16x32_bf16 v[16:19], v[190:193], v[214:217], v[16:19]
	v_mfma_f32_16x16x32_bf16 v[4:7], v[182:185], v[222:225], v[4:7]
	v_mfma_f32_16x16x32_bf16 v[0:3], v[190:193], v[222:225], v[0:3]
	v_mfma_f32_16x16x32_bf16 v[52:55], v[186:189], v[202:205], v[52:55]
	v_mfma_f32_16x16x32_bf16 v[48:51], v[194:197], v[202:205], v[48:51]
	v_mfma_f32_16x16x32_bf16 v[36:39], v[186:189], v[210:213], v[36:39]
	v_mfma_f32_16x16x32_bf16 v[32:35], v[194:197], v[210:213], v[32:35]
	v_mfma_f32_16x16x32_bf16 v[20:23], v[186:189], v[218:221], v[20:23]
	v_mfma_f32_16x16x32_bf16 v[16:19], v[194:197], v[218:221], v[16:19]
	v_mfma_f32_16x16x32_bf16 v[4:7], v[186:189], v[226:229], v[4:7]
	v_mfma_f32_16x16x32_bf16 v[0:3], v[194:197], v[226:229], v[0:3]
	s_setprio 0
	s_barrier
	s_add_i32 s69, 0, 0x18000
	s_add_i32 s70, 0, 0x1c000
	v_add_u32_e32 v178, s69, v161
	v_add_u32_e32 v194, s70, v161
	ds_read_b128 v[166:169], v178
	ds_read_b128 v[170:173], v178 offset:1024
	ds_read_b128 v[174:177], v178 offset:2048
	ds_read_b128 v[178:181], v178 offset:3072
	ds_read_b128 v[182:185], v194
	ds_read_b128 v[186:189], v194 offset:1024
	ds_read_b128 v[190:193], v194 offset:2048
	ds_read_b128 v[194:197], v194 offset:3072
	s_add_u32 s38, s38, s10
	s_addc_u32 s39, s39, s11
	s_mov_b32 m0, s48
	v_lshl_add_u64 v[242:243], s[38:39], 0, v[128:129]
	ds_read_b128 v[198:201], v165 offset:32768
	ds_read_b128 v[202:205], v165 offset:33792
	ds_read_b128 v[206:209], v165 offset:34816
	ds_read_b128 v[210:213], v165 offset:35840
	ds_read_b128 v[214:217], v165 offset:36864
	ds_read_b128 v[218:221], v165 offset:37888
	ds_read_b128 v[222:225], v165 offset:38912
	ds_read_b128 v[226:229], v165 offset:39936
	global_load_lds_dwordx4 v[242:243], off
	v_lshl_add_u64 v[242:243], s[38:39], 0, v[132:133]
	s_mov_b32 m0, s49
	s_nop 0
	global_load_lds_dwordx4 v[242:243], off
	s_waitcnt vmcnt(8)
	s_waitcnt lgkmcnt(0)
	s_barrier
	s_setprio 1
	s_waitcnt lgkmcnt(0)
	v_mfma_f32_16x16x32_bf16 v[120:123], v[166:169], v[198:201], v[120:123]
	v_mfma_f32_16x16x32_bf16 v[124:127], v[174:177], v[198:201], v[124:127]
	v_mfma_f32_16x16x32_bf16 v[108:111], v[166:169], v[206:209], v[108:111]
	v_mfma_f32_16x16x32_bf16 v[104:107], v[174:177], v[206:209], v[104:107]
	v_mfma_f32_16x16x32_bf16 v[92:95], v[166:169], v[214:217], v[92:95]
	v_mfma_f32_16x16x32_bf16 v[88:91], v[174:177], v[214:217], v[88:91]
	v_mfma_f32_16x16x32_bf16 v[76:79], v[166:169], v[222:225], v[76:79]
	v_mfma_f32_16x16x32_bf16 v[72:75], v[174:177], v[222:225], v[72:75]
	v_mfma_f32_16x16x32_bf16 v[120:123], v[170:173], v[202:205], v[120:123]
	v_mfma_f32_16x16x32_bf16 v[124:127], v[178:181], v[202:205], v[124:127]
	v_mfma_f32_16x16x32_bf16 v[108:111], v[170:173], v[210:213], v[108:111]
	v_mfma_f32_16x16x32_bf16 v[104:107], v[178:181], v[210:213], v[104:107]
	v_mfma_f32_16x16x32_bf16 v[92:95], v[170:173], v[218:221], v[92:95]
	v_mfma_f32_16x16x32_bf16 v[88:91], v[178:181], v[218:221], v[88:91]
	v_mfma_f32_16x16x32_bf16 v[76:79], v[170:173], v[226:229], v[76:79]
	v_mfma_f32_16x16x32_bf16 v[72:75], v[178:181], v[226:229], v[72:75]
	v_mfma_f32_16x16x32_bf16 v[116:119], v[182:185], v[198:201], v[116:119]
	v_mfma_f32_16x16x32_bf16 v[112:115], v[190:193], v[198:201], v[112:115]
	v_mfma_f32_16x16x32_bf16 v[100:103], v[182:185], v[206:209], v[100:103]
	v_mfma_f32_16x16x32_bf16 v[96:99], v[190:193], v[206:209], v[96:99]
	v_mfma_f32_16x16x32_bf16 v[84:87], v[182:185], v[214:217], v[84:87]
	v_mfma_f32_16x16x32_bf16 v[80:83], v[190:193], v[214:217], v[80:83]
	v_mfma_f32_16x16x32_bf16 v[68:71], v[182:185], v[222:225], v[68:71]
	v_mfma_f32_16x16x32_bf16 v[64:67], v[190:193], v[222:225], v[64:67]
	v_mfma_f32_16x16x32_bf16 v[116:119], v[186:189], v[202:205], v[116:119]
	v_mfma_f32_16x16x32_bf16 v[112:115], v[194:197], v[202:205], v[112:115]
	v_mfma_f32_16x16x32_bf16 v[100:103], v[186:189], v[210:213], v[100:103]
	v_mfma_f32_16x16x32_bf16 v[96:99], v[194:197], v[210:213], v[96:99]
	v_mfma_f32_16x16x32_bf16 v[84:87], v[186:189], v[218:221], v[84:87]
	v_mfma_f32_16x16x32_bf16 v[80:83], v[194:197], v[218:221], v[80:83]
	v_mfma_f32_16x16x32_bf16 v[68:71], v[186:189], v[226:229], v[68:71]
	v_mfma_f32_16x16x32_bf16 v[64:67], v[194:197], v[226:229], v[64:67]
	s_setprio 0
	s_barrier
; #define PG8_STAGE(bufoff, gbase, voff) do { _Pragma("unroll") for (int _i = 0; _i < 2; ++_i) \
;         __builtin_amdgcn_global_load_lds((const unsigned*)((const char*)(gbase) + (voff)[_i]), (PG8_LAS unsigned*)(lds + (bufoff) + ldsw + _i * 8192), 16, 0, 0); } while (0)
; #define PG8_LDA(dst, b, h) do { _Pragma("unroll") for (int m = 0; m < 4; ++m) _Pragma("unroll") for (int k = 0; k < 2; ++k) dst[m][k] = *(const PG8_LAS bf16x8*)(lds + PG8_SA(b, h) + aoff + m * 2048 + k * 1024); } while (0)
; #define PG8_MMA(ai, bj, At, Bt) do { __builtin_amdgcn_s_setprio(1); _Pragma("unroll") for (int m = 0; m < 4; ++m) _Pragma("unroll") for (int n = 0; n < 2; ++n) _Pragma("unroll") for (int k = 0; k < 2; ++k) \
;         acc[ai][bj][m][n] = __builtin_amdgcn_mfma_f32_16x16x32_bf16(Bt[n][k], At[m][k], acc[ai][bj][m][n], 0, 0, 0); __builtin_amdgcn_s_setprio(0); } while (0)
; #define PG8_WAIT_V(n) asm volatile("s_waitcnt vmcnt(" #n ")" ::: "memory")
; #define PG8_WAIT_L(n) asm volatile("s_waitcnt lgkmcnt(" #n ")" ::: "memory")
; #define PG8_BAR __builtin_amdgcn_s_barrier()
; #define PG8_SCHED __builtin_amdgcn_sched_barrier(0)
; template <class Epi, class Sched, bool ALIGN_EPI = false, bool SP2 = false>
; __device__ __forceinline__ void gemm_phase(PG8_LAS unsigned char* lds, const Gemm g, const Sched& S, const Epi& E) {
;     ...
;         for (int t = 0; t < nt; t += 2) {
;             const bool last = (t == nt - 2);
;     ...
;             PG8_LDA(At, 1, 1); PG8_STAGE(PG8_SB(1, 0), b3, voffB); PG8_STAGE(PG8_SB(1, 1), b3 + hstep, voffB); PG8_STAGE(PG8_SA(1, 0), a3, voffA);
;             PG8_WAIT_V(8); PG8_WAIT_L(0); PG8_BAR; PG8_MMA(1, 0, At, B0); PG8_MMA(1, 1, At, B1); PG8_BAR; PG8_SCHED;
	s_add_i32 s38, s69, s45
	v_lshl_add_u64 v[230:231], v[230:231], 0, s[18:19]
	s_mov_b32 m0, s38
	ds_read_b128 v[198:201], v165 offset:49152
	ds_read_b128 v[202:205], v165 offset:50176
	ds_read_b128 v[206:209], v165 offset:51200
	ds_read_b128 v[210:213], v165 offset:52224
	ds_read_b128 v[214:217], v165 offset:53248
	ds_read_b128 v[218:221], v165 offset:54272
	ds_read_b128 v[222:225], v165 offset:55296
	ds_read_b128 v[226:229], v165 offset:56320
	global_load_lds_dwordx4 v[230:231], off
	v_lshl_add_u64 v[230:231], v[232:233], 0, s[18:19]
	s_add_i32 m0, s38, 0x2000
	s_add_i32 s38, s70, s45
	global_load_lds_dwordx4 v[230:231], off
	v_lshl_add_u64 v[230:231], v[234:235], 0, s[18:19]
	s_mov_b32 m0, s38
	s_nop 0
	global_load_lds_dwordx4 v[230:231], off
	v_lshl_add_u64 v[230:231], v[236:237], 0, s[18:19]
	s_add_i32 m0, s38, 0x2000
	s_nop 0
	global_load_lds_dwordx4 v[230:231], off
	v_lshl_add_u64 v[230:231], v[238:239], 0, s[18:19]
	s_mov_b32 m0, s51
	s_nop 0
	global_load_lds_dwordx4 v[230:231], off
	v_lshl_add_u64 v[230:231], v[240:241], 0, s[18:19]
	s_mov_b32 m0, s52
	s_nop 0
	global_load_lds_dwordx4 v[230:231], off
	s_waitcnt vmcnt(8)
	s_waitcnt lgkmcnt(0)
	s_barrier
	s_setprio 1
	s_waitcnt lgkmcnt(0)
	v_mfma_f32_16x16x32_bf16 v[60:63], v[166:169], v[198:201], v[60:63]
	v_mfma_f32_16x16x32_bf16 v[56:59], v[174:177], v[198:201], v[56:59]
	v_mfma_f32_16x16x32_bf16 v[44:47], v[166:169], v[206:209], v[44:47]
	v_mfma_f32_16x16x32_bf16 v[40:43], v[174:177], v[206:209], v[40:43]
	v_mfma_f32_16x16x32_bf16 v[28:31], v[166:169], v[214:217], v[28:31]
	v_mfma_f32_16x16x32_bf16 v[24:27], v[174:177], v[214:217], v[24:27]
	v_mfma_f32_16x16x32_bf16 v[12:15], v[166:169], v[222:225], v[12:15]
	v_mfma_f32_16x16x32_bf16 v[8:11], v[174:177], v[222:225], v[8:11]
	v_mfma_f32_16x16x32_bf16 v[60:63], v[170:173], v[202:205], v[60:63]
	v_mfma_f32_16x16x32_bf16 v[56:59], v[178:181], v[202:205], v[56:59]
	v_mfma_f32_16x16x32_bf16 v[44:47], v[170:173], v[210:213], v[44:47]
	v_mfma_f32_16x16x32_bf16 v[40:43], v[178:181], v[210:213], v[40:43]
	v_mfma_f32_16x16x32_bf16 v[28:31], v[170:173], v[218:221], v[28:31]
	v_mfma_f32_16x16x32_bf16 v[24:27], v[178:181], v[218:221], v[24:27]
	v_mfma_f32_16x16x32_bf16 v[12:15], v[170:173], v[226:229], v[12:15]
	v_mfma_f32_16x16x32_bf16 v[8:11], v[178:181], v[226:229], v[8:11]
	v_mfma_f32_16x16x32_bf16 v[52:55], v[182:185], v[198:201], v[52:55]
	v_mfma_f32_16x16x32_bf16 v[48:51], v[190:193], v[198:201], v[48:51]
	v_mfma_f32_16x16x32_bf16 v[36:39], v[182:185], v[206:209], v[36:39]
	v_mfma_f32_16x16x32_bf16 v[32:35], v[190:193], v[206:209], v[32:35]
	v_mfma_f32_16x16x32_bf16 v[20:23], v[182:185], v[214:217], v[20:23]
	v_mfma_f32_16x16x32_bf16 v[16:19], v[190:193], v[214:217], v[16:19]
	v_mfma_f32_16x16x32_bf16 v[4:7], v[182:185], v[222:225], v[4:7]
	v_mfma_f32_16x16x32_bf16 v[0:3], v[190:193], v[222:225], v[0:3]
	v_mfma_f32_16x16x32_bf16 v[52:55], v[186:189], v[202:205], v[52:55]
	v_mfma_f32_16x16x32_bf16 v[48:51], v[194:197], v[202:205], v[48:51]
	v_mfma_f32_16x16x32_bf16 v[36:39], v[186:189], v[210:213], v[36:39]
	v_mfma_f32_16x16x32_bf16 v[32:35], v[194:197], v[210:213], v[32:35]
	v_mfma_f32_16x16x32_bf16 v[20:23], v[186:189], v[218:221], v[20:23]
	v_mfma_f32_16x16x32_bf16 v[16:19], v[194:197], v[218:221], v[16:19]
	v_mfma_f32_16x16x32_bf16 v[4:7], v[186:189], v[226:229], v[4:7]
	v_mfma_f32_16x16x32_bf16 v[0:3], v[194:197], v[226:229], v[0:3]
	s_setprio 0
	s_barrier
	s_add_u32 s36, s36, 0x100
	s_addc_u32 s37, s37, 0
	s_add_u32 s0, s0, 0x100
	s_addc_u32 s1, s1, 0
	s_cmp_ge_i32 s68, s53
	s_mov_b32 s38, s68
	s_cbranch_scc0 .LBB0_1569

; #define PG8_STAGE(bufoff, gbase, voff) do { _Pragma("unroll") for (int _i = 0; _i < 2; ++_i) \
;         __builtin_amdgcn_global_load_lds((const unsigned*)((const char*)(gbase) + (voff)[_i]), (PG8_LAS unsigned*)(lds + (bufoff) + ldsw + _i * 8192), 16, 0, 0); } while (0)
; #define PG8_LDA(dst, b, h) do { _Pragma("unroll") for (int m = 0; m < 4; ++m) _Pragma("unroll") for (int k = 0; k < 2; ++k) dst[m][k] = *(const PG8_LAS bf16x8*)(lds + PG8_SA(b, h) + aoff + m * 2048 + k * 1024); } while (0)
; #define PG8_LDB(dst, b, h) do { _Pragma("unroll") for (int n = 0; n < 2; ++n) _Pragma("unroll") for (int k = 0; k < 2; ++k) dst[n][k] = *(const PG8_LAS bf16x8*)(lds + PG8_SB(b, h) + boff + n * 2048 + k * 1024); } while (0)
; #define PG8_MMA(ai, bj, At, Bt) do { __builtin_amdgcn_s_setprio(1); _Pragma("unroll") for (int m = 0; m < 4; ++m) _Pragma("unroll") for (int n = 0; n < 2; ++n) _Pragma("unroll") for (int k = 0; k < 2; ++k) \
;         acc[ai][bj][m][n] = __builtin_amdgcn_mfma_f32_16x16x32_bf16(Bt[n][k], At[m][k], acc[ai][bj][m][n], 0, 0, 0); __builtin_amdgcn_s_setprio(0); } while (0)
; #define PG8_WAIT_V(n) asm volatile("s_waitcnt vmcnt(" #n ")" ::: "memory")
; #define PG8_WAIT_L(n) asm volatile("s_waitcnt lgkmcnt(" #n ")" ::: "memory")
; template <class Epi, class Sched, bool ALIGN_EPI = false, bool SP2 = false>
; __device__ __forceinline__ void gemm_phase(PG8_LAS unsigned char* lds, const Gemm g, const Sched& S, const Epi& E) {
;     ...
;             const bool last = (t == nt - 2);
;             const char* a1 = cA + (size_t)(t + 1) * kstep;
;             const char* a2 = last ? nA : cA + (size_t)(t + 2) * kstep; const char* b2 = last ? nB : cB + (size_t)(t + 2) * kstep;
;             const char* a3 = a2 + kstep; const char* b3 = b2 + kstep;
;             if (last && has_next) S.a_ready(nxt);
;             if constexpr (SP2) {
;             PG8_LDB(B0, 0, 0); PG8_LDB(B1, 0, 1); PG8_SCHED; PG8_LDA(At, 0, 0); PG8_STAGE(PG8_SA(1, 1), a1 + hstep, voffA);
;             PG8_WAIT_V(8); PG8_WAIT_L(0); PG8_BAR; PG8_MMA(0, 0, At, B0); PG8_MMA(0, 1, At, B1); PG8_BAR; PG8_SCHED;
;             PG8_LDA(At, 0, 1); PG8_STAGE(PG8_SB(0, 0), b2, voffB); PG8_STAGE(PG8_SB(0, 1), b2 + hstep, voffB); PG8_STAGE(PG8_SA(0, 0), a2, voffA);
;             PG8_WAIT_V(8); PG8_WAIT_L(0); PG8_BAR; PG8_MMA(1, 0, At, B0); PG8_MMA(1, 1, At, B1); PG8_BAR; PG8_SCHED;
.LBB0_1602:
	ds_read_b128 v[158:161], v144
	ds_read_b128 v[162:165], v144 offset:1024
	ds_read_b128 v[166:169], v144 offset:2048
	ds_read_b128 v[170:173], v144 offset:3072
	ds_read_b128 v[174:177], v145
	ds_read_b128 v[178:181], v145 offset:1024
	ds_read_b128 v[182:185], v145 offset:2048
	ds_read_b128 v[186:189], v145 offset:3072
	s_add_i32 s67, s38, 2
	s_add_u32 s68, s36, 0x80
	s_addc_u32 s39, s37, 0
	s_cmp_eq_u32 s53, s38
	s_cselect_b32 s38, s8, s68
	s_cselect_b32 s39, s9, s39
	s_cselect_b32 s69, s35, s1
	s_cselect_b32 s68, s34, s0
	v_lshl_add_u64 v[148:149], s[36:37], 0, v[136:137]
	s_add_i32 m0, s45, 0xc000
	ds_read_b128 v[190:193], v146
	ds_read_b128 v[194:197], v146 offset:1024
	ds_read_b128 v[198:201], v146 offset:2048
	ds_read_b128 v[202:205], v146 offset:3072
	ds_read_b128 v[206:209], v146 offset:4096
	ds_read_b128 v[210:213], v146 offset:5120
	ds_read_b128 v[214:217], v146 offset:6144
	ds_read_b128 v[218:221], v146 offset:7168
	global_load_lds_dwordx4 v[148:149], off
	v_lshl_add_u64 v[148:149], s[36:37], 0, v[138:139]
	s_add_i32 m0, s45, 0xe000
	s_nop 0
	global_load_lds_dwordx4 v[148:149], off
	s_waitcnt vmcnt(8)
	s_waitcnt lgkmcnt(0)
	s_barrier
	s_setprio 1
	s_waitcnt lgkmcnt(0)
	v_mfma_f32_16x16x32_bf16 v[120:123], v[158:161], v[190:193], v[120:123]
	v_mfma_f32_16x16x32_bf16 v[124:127], v[166:169], v[190:193], v[124:127]
	v_mfma_f32_16x16x32_bf16 v[108:111], v[158:161], v[198:201], v[108:111]
	v_mfma_f32_16x16x32_bf16 v[104:107], v[166:169], v[198:201], v[104:107]
	v_mfma_f32_16x16x32_bf16 v[92:95], v[158:161], v[206:209], v[92:95]
	v_mfma_f32_16x16x32_bf16 v[88:91], v[166:169], v[206:209], v[88:91]
	v_mfma_f32_16x16x32_bf16 v[76:79], v[158:161], v[214:217], v[76:79]
	v_mfma_f32_16x16x32_bf16 v[72:75], v[166:169], v[214:217], v[72:75]
	v_mfma_f32_16x16x32_bf16 v[120:123], v[162:165], v[194:197], v[120:123]
	v_mfma_f32_16x16x32_bf16 v[124:127], v[170:173], v[194:197], v[124:127]
	v_mfma_f32_16x16x32_bf16 v[108:111], v[162:165], v[202:205], v[108:111]
	v_mfma_f32_16x16x32_bf16 v[104:107], v[170:173], v[202:205], v[104:107]
	v_mfma_f32_16x16x32_bf16 v[92:95], v[162:165], v[210:213], v[92:95]
	v_mfma_f32_16x16x32_bf16 v[88:91], v[170:173], v[210:213], v[88:91]
	v_mfma_f32_16x16x32_bf16 v[76:79], v[162:165], v[218:221], v[76:79]
	v_mfma_f32_16x16x32_bf16 v[72:75], v[170:173], v[218:221], v[72:75]
	v_mfma_f32_16x16x32_bf16 v[116:119], v[174:177], v[190:193], v[116:119]
	v_mfma_f32_16x16x32_bf16 v[112:115], v[182:185], v[190:193], v[112:115]
	v_mfma_f32_16x16x32_bf16 v[100:103], v[174:177], v[198:201], v[100:103]
	v_mfma_f32_16x16x32_bf16 v[96:99], v[182:185], v[198:201], v[96:99]
	v_mfma_f32_16x16x32_bf16 v[84:87], v[174:177], v[206:209], v[84:87]
	v_mfma_f32_16x16x32_bf16 v[80:83], v[182:185], v[206:209], v[80:83]
	v_mfma_f32_16x16x32_bf16 v[68:71], v[174:177], v[214:217], v[68:71]
	v_mfma_f32_16x16x32_bf16 v[64:67], v[182:185], v[214:217], v[64:67]
	v_mfma_f32_16x16x32_bf16 v[116:119], v[178:181], v[194:197], v[116:119]
	v_mfma_f32_16x16x32_bf16 v[112:115], v[186:189], v[194:197], v[112:115]
	v_mfma_f32_16x16x32_bf16 v[100:103], v[178:181], v[202:205], v[100:103]
	v_mfma_f32_16x16x32_bf16 v[96:99], v[186:189], v[202:205], v[96:99]
	v_mfma_f32_16x16x32_bf16 v[84:87], v[178:181], v[210:213], v[84:87]
	v_mfma_f32_16x16x32_bf16 v[80:83], v[186:189], v[210:213], v[80:83]
	v_mfma_f32_16x16x32_bf16 v[68:71], v[178:181], v[218:221], v[68:71]
	v_mfma_f32_16x16x32_bf16 v[64:67], v[186:189], v[218:221], v[64:67]
	s_setprio 0
	s_barrier
	s_add_i32 s70, s58, s44
	v_lshl_add_u64 v[148:149], s[68:69], 0, v[130:131]
	s_mov_b32 m0, s70
	ds_read_b128 v[190:193], v146 offset:16384
	ds_read_b128 v[194:197], v146 offset:17408
	ds_read_b128 v[198:201], v146 offset:18432
	ds_read_b128 v[202:205], v146 offset:19456
	ds_read_b128 v[206:209], v146 offset:20480
	ds_read_b128 v[210:213], v146 offset:21504
	ds_read_b128 v[214:217], v146 offset:22528
	ds_read_b128 v[218:221], v146 offset:23552
	global_load_lds_dwordx4 v[148:149], off
	s_add_i32 m0, s70, 0x2000
	v_lshl_add_u64 v[222:223], s[68:69], 0, v[134:135]
	s_add_u32 s68, s68, s10
	s_addc_u32 s69, s69, s11
	s_add_i32 s70, s59, s44
	global_load_lds_dwordx4 v[222:223], off
	v_lshl_add_u64 v[224:225], s[68:69], 0, v[130:131]
	s_mov_b32 m0, s70
	v_lshl_add_u64 v[226:227], s[68:69], 0, v[134:135]
	global_load_lds_dwordx4 v[224:225], off
	s_add_i32 m0, s70, 0x2000
	v_lshl_add_u64 v[228:229], s[38:39], 0, v[128:129]
	global_load_lds_dwordx4 v[226:227], off
	s_mov_b32 m0, s45
	v_lshl_add_u64 v[230:231], s[38:39], 0, v[132:133]
	global_load_lds_dwordx4 v[228:229], off
	s_mov_b32 m0, s46
	s_nop 0
	global_load_lds_dwordx4 v[230:231], off
	s_waitcnt vmcnt(8)
	s_waitcnt lgkmcnt(0)
	s_barrier
; #define PG8_STAGE(bufoff, gbase, voff) do { _Pragma("unroll") for (int _i = 0; _i < 2; ++_i) \
;         __builtin_amdgcn_global_load_lds((const unsigned*)((const char*)(gbase) + (voff)[_i]), (PG8_LAS unsigned*)(lds + (bufoff) + ldsw + _i * 8192), 16, 0, 0); } while (0)
; #define PG8_LDA(dst, b, h) do { _Pragma("unroll") for (int m = 0; m < 4; ++m) _Pragma("unroll") for (int k = 0; k < 2; ++k) dst[m][k] = *(const PG8_LAS bf16x8*)(lds + PG8_SA(b, h) + aoff + m * 2048 + k * 1024); } while (0)
; #define PG8_LDB(dst, b, h) do { _Pragma("unroll") for (int n = 0; n < 2; ++n) _Pragma("unroll") for (int k = 0; k < 2; ++k) dst[n][k] = *(const PG8_LAS bf16x8*)(lds + PG8_SB(b, h) + boff + n * 2048 + k * 1024); } while (0)
; #define PG8_MMA(ai, bj, At, Bt) do { __builtin_amdgcn_s_setprio(1); _Pragma("unroll") for (int m = 0; m < 4; ++m) _Pragma("unroll") for (int n = 0; n < 2; ++n) _Pragma("unroll") for (int k = 0; k < 2; ++k) \
;         acc[ai][bj][m][n] = __builtin_amdgcn_mfma_f32_16x16x32_bf16(Bt[n][k], At[m][k], acc[ai][bj][m][n], 0, 0, 0); __builtin_amdgcn_s_setprio(0); } while (0)
; #define PG8_WAIT_V(n) asm volatile("s_waitcnt vmcnt(" #n ")" ::: "memory")
; #define PG8_WAIT_L(n) asm volatile("s_waitcnt lgkmcnt(" #n ")" ::: "memory")
; #define PG8_BAR __builtin_amdgcn_s_barrier()
; #define PG8_SCHED __builtin_amdgcn_sched_barrier(0)
; template <class Epi, class Sched, bool ALIGN_EPI = false, bool SP2 = false>
; __device__ __forceinline__ void gemm_phase(PG8_LAS unsigned char* lds, const Gemm g, const Sched& S, const Epi& E) {
;     ...
;             PG8_WAIT_V(8); PG8_WAIT_L(0); PG8_BAR; PG8_MMA(1, 0, At, B0); PG8_MMA(1, 1, At, B1); PG8_BAR; PG8_SCHED;
;             PG8_LDB(B0, 1, 0); PG8_LDB(B1, 1, 1); PG8_SCHED; PG8_LDA(At, 1, 0); PG8_STAGE(PG8_SA(0, 1), a2 + hstep, voffA);
;             PG8_WAIT_V(8); PG8_WAIT_L(0); PG8_BAR; PG8_MMA(0, 0, At, B0); PG8_MMA(0, 1, At, B1); PG8_BAR; PG8_SCHED;
	s_setprio 1
	s_waitcnt lgkmcnt(0)
	v_mfma_f32_16x16x32_bf16 v[60:63], v[158:161], v[190:193], v[60:63]
	v_mfma_f32_16x16x32_bf16 v[56:59], v[166:169], v[190:193], v[56:59]
	v_mfma_f32_16x16x32_bf16 v[44:47], v[158:161], v[198:201], v[44:47]
	v_mfma_f32_16x16x32_bf16 v[40:43], v[166:169], v[198:201], v[40:43]
	v_mfma_f32_16x16x32_bf16 v[28:31], v[158:161], v[206:209], v[28:31]
	v_mfma_f32_16x16x32_bf16 v[24:27], v[166:169], v[206:209], v[24:27]
	v_mfma_f32_16x16x32_bf16 v[12:15], v[158:161], v[214:217], v[12:15]
	v_mfma_f32_16x16x32_bf16 v[8:11], v[166:169], v[214:217], v[8:11]
	v_mfma_f32_16x16x32_bf16 v[60:63], v[162:165], v[194:197], v[60:63]
	v_mfma_f32_16x16x32_bf16 v[56:59], v[170:173], v[194:197], v[56:59]
	v_mfma_f32_16x16x32_bf16 v[44:47], v[162:165], v[202:205], v[44:47]
	v_mfma_f32_16x16x32_bf16 v[40:43], v[170:173], v[202:205], v[40:43]
	v_mfma_f32_16x16x32_bf16 v[28:31], v[162:165], v[210:213], v[28:31]
	v_mfma_f32_16x16x32_bf16 v[24:27], v[170:173], v[210:213], v[24:27]
	v_mfma_f32_16x16x32_bf16 v[12:15], v[162:165], v[218:221], v[12:15]
	v_mfma_f32_16x16x32_bf16 v[8:11], v[170:173], v[218:221], v[8:11]
	v_mfma_f32_16x16x32_bf16 v[52:55], v[174:177], v[190:193], v[52:55]
	v_mfma_f32_16x16x32_bf16 v[48:51], v[182:185], v[190:193], v[48:51]
	v_mfma_f32_16x16x32_bf16 v[36:39], v[174:177], v[198:201], v[36:39]
	v_mfma_f32_16x16x32_bf16 v[32:35], v[182:185], v[198:201], v[32:35]
	v_mfma_f32_16x16x32_bf16 v[20:23], v[174:177], v[206:209], v[20:23]
	v_mfma_f32_16x16x32_bf16 v[16:19], v[182:185], v[206:209], v[16:19]
	v_mfma_f32_16x16x32_bf16 v[4:7], v[174:177], v[214:217], v[4:7]
	v_mfma_f32_16x16x32_bf16 v[0:3], v[182:185], v[214:217], v[0:3]
	v_mfma_f32_16x16x32_bf16 v[52:55], v[178:181], v[194:197], v[52:55]
	v_mfma_f32_16x16x32_bf16 v[48:51], v[186:189], v[194:197], v[48:51]
	v_mfma_f32_16x16x32_bf16 v[36:39], v[178:181], v[202:205], v[36:39]
	v_mfma_f32_16x16x32_bf16 v[32:35], v[186:189], v[202:205], v[32:35]
	v_mfma_f32_16x16x32_bf16 v[20:23], v[178:181], v[210:213], v[20:23]
	v_mfma_f32_16x16x32_bf16 v[16:19], v[186:189], v[210:213], v[16:19]
	v_mfma_f32_16x16x32_bf16 v[4:7], v[178:181], v[218:221], v[4:7]
	v_mfma_f32_16x16x32_bf16 v[0:3], v[186:189], v[218:221], v[0:3]
	s_setprio 0
	s_barrier
	s_add_i32 s68, 0, 0x18000
	v_add_u32_e32 v151, s68, v150
	s_add_i32 s69, 0, 0x1c000
	ds_read_b128 v[158:161], v151
	ds_read_b128 v[162:165], v151 offset:1024
	ds_read_b128 v[166:169], v151 offset:2048
	ds_read_b128 v[170:173], v151 offset:3072
	v_add_u32_e32 v151, s69, v150
	ds_read_b128 v[174:177], v151
	ds_read_b128 v[178:181], v151 offset:1024
	ds_read_b128 v[182:185], v151 offset:2048
	ds_read_b128 v[186:189], v151 offset:3072
	s_add_u32 s38, s38, s10
	s_addc_u32 s39, s39, s11
	s_mov_b32 m0, s47
	v_lshl_add_u64 v[232:233], s[38:39], 0, v[128:129]
	ds_read_b128 v[190:193], v146 offset:32768
	ds_read_b128 v[194:197], v146 offset:33792
	ds_read_b128 v[198:201], v146 offset:34816
	ds_read_b128 v[202:205], v146 offset:35840
	ds_read_b128 v[206:209], v146 offset:36864
	ds_read_b128 v[210:213], v146 offset:37888
	ds_read_b128 v[214:217], v146 offset:38912
	ds_read_b128 v[218:221], v146 offset:39936
	global_load_lds_dwordx4 v[232:233], off
	v_lshl_add_u64 v[232:233], s[38:39], 0, v[132:133]
	s_mov_b32 m0, s48
	s_nop 0
	global_load_lds_dwordx4 v[232:233], off
	s_waitcnt vmcnt(8)
	s_waitcnt lgkmcnt(0)
	s_barrier
	s_setprio 1
	s_waitcnt lgkmcnt(0)
	v_mfma_f32_16x16x32_bf16 v[120:123], v[158:161], v[190:193], v[120:123]
	v_mfma_f32_16x16x32_bf16 v[124:127], v[166:169], v[190:193], v[124:127]
	v_mfma_f32_16x16x32_bf16 v[108:111], v[158:161], v[198:201], v[108:111]
	v_mfma_f32_16x16x32_bf16 v[104:107], v[166:169], v[198:201], v[104:107]
	v_mfma_f32_16x16x32_bf16 v[92:95], v[158:161], v[206:209], v[92:95]
	v_mfma_f32_16x16x32_bf16 v[88:91], v[166:169], v[206:209], v[88:91]
	v_mfma_f32_16x16x32_bf16 v[76:79], v[158:161], v[214:217], v[76:79]
	v_mfma_f32_16x16x32_bf16 v[72:75], v[166:169], v[214:217], v[72:75]
	v_mfma_f32_16x16x32_bf16 v[120:123], v[162:165], v[194:197], v[120:123]
	v_mfma_f32_16x16x32_bf16 v[124:127], v[170:173], v[194:197], v[124:127]
	v_mfma_f32_16x16x32_bf16 v[108:111], v[162:165], v[202:205], v[108:111]
	v_mfma_f32_16x16x32_bf16 v[104:107], v[170:173], v[202:205], v[104:107]
	v_mfma_f32_16x16x32_bf16 v[92:95], v[162:165], v[210:213], v[92:95]
	v_mfma_f32_16x16x32_bf16 v[88:91], v[170:173], v[210:213], v[88:91]
	v_mfma_f32_16x16x32_bf16 v[76:79], v[162:165], v[218:221], v[76:79]
	v_mfma_f32_16x16x32_bf16 v[72:75], v[170:173], v[218:221], v[72:75]
	v_mfma_f32_16x16x32_bf16 v[116:119], v[174:177], v[190:193], v[116:119]
	v_mfma_f32_16x16x32_bf16 v[112:115], v[182:185], v[190:193], v[112:115]
	v_mfma_f32_16x16x32_bf16 v[100:103], v[174:177], v[198:201], v[100:103]
	v_mfma_f32_16x16x32_bf16 v[96:99], v[182:185], v[198:201], v[96:99]
	v_mfma_f32_16x16x32_bf16 v[84:87], v[174:177], v[206:209], v[84:87]
	v_mfma_f32_16x16x32_bf16 v[80:83], v[182:185], v[206:209], v[80:83]
	v_mfma_f32_16x16x32_bf16 v[68:71], v[174:177], v[214:217], v[68:71]
	v_mfma_f32_16x16x32_bf16 v[64:67], v[182:185], v[214:217], v[64:67]
	v_mfma_f32_16x16x32_bf16 v[116:119], v[178:181], v[194:197], v[116:119]
	v_mfma_f32_16x16x32_bf16 v[112:115], v[186:189], v[194:197], v[112:115]
	v_mfma_f32_16x16x32_bf16 v[100:103], v[178:181], v[202:205], v[100:103]
	v_mfma_f32_16x16x32_bf16 v[96:99], v[186:189], v[202:205], v[96:99]
	v_mfma_f32_16x16x32_bf16 v[84:87], v[178:181], v[210:213], v[84:87]
	v_mfma_f32_16x16x32_bf16 v[80:83], v[186:189], v[210:213], v[80:83]
	v_mfma_f32_16x16x32_bf16 v[68:71], v[178:181], v[218:221], v[68:71]
	v_mfma_f32_16x16x32_bf16 v[64:67], v[186:189], v[218:221], v[64:67]
	s_setprio 0
	s_barrier
; #define PG8_STAGE(bufoff, gbase, voff) do { _Pragma("unroll") for (int _i = 0; _i < 2; ++_i) \
;         __builtin_amdgcn_global_load_lds((const unsigned*)((const char*)(gbase) + (voff)[_i]), (PG8_LAS unsigned*)(lds + (bufoff) + ldsw + _i * 8192), 16, 0, 0); } while (0)
; #define PG8_LDA(dst, b, h) do { _Pragma("unroll") for (int m = 0; m < 4; ++m) _Pragma("unroll") for (int k = 0; k < 2; ++k) dst[m][k] = *(const PG8_LAS bf16x8*)(lds + PG8_SA(b, h) + aoff + m * 2048 + k * 1024); } while (0)
; #define PG8_MMA(ai, bj, At, Bt) do { __builtin_amdgcn_s_setprio(1); _Pragma("unroll") for (int m = 0; m < 4; ++m) _Pragma("unroll") for (int n = 0; n < 2; ++n) _Pragma("unroll") for (int k = 0; k < 2; ++k) \
;         acc[ai][bj][m][n] = __builtin_amdgcn_mfma_f32_16x16x32_bf16(Bt[n][k], At[m][k], acc[ai][bj][m][n], 0, 0, 0); __builtin_amdgcn_s_setprio(0); } while (0)
; #define PG8_WAIT_V(n) asm volatile("s_waitcnt vmcnt(" #n ")" ::: "memory")
; #define PG8_WAIT_L(n) asm volatile("s_waitcnt lgkmcnt(" #n ")" ::: "memory")
; #define PG8_BAR __builtin_amdgcn_s_barrier()
; #define PG8_SCHED __builtin_amdgcn_sched_barrier(0)
; template <class Epi, class Sched, bool ALIGN_EPI = false, bool SP2 = false>
; __device__ __forceinline__ void gemm_phase(PG8_LAS unsigned char* lds, const Gemm g, const Sched& S, const Epi& E) {
;     ...
;         for (int t = 0; t < nt; t += 2) {
;             const bool last = (t == nt - 2);
;     ...
;             PG8_LDA(At, 1, 1); PG8_STAGE(PG8_SB(1, 0), b3, voffB); PG8_STAGE(PG8_SB(1, 1), b3 + hstep, voffB); PG8_STAGE(PG8_SA(1, 0), a3, voffA);
;             PG8_WAIT_V(8); PG8_WAIT_L(0); PG8_BAR; PG8_MMA(1, 0, At, B0); PG8_MMA(1, 1, At, B1); PG8_BAR; PG8_SCHED;
	s_add_i32 s38, s68, s44
	v_lshl_add_u64 v[148:149], v[148:149], 0, s[18:19]
	s_mov_b32 m0, s38
	ds_read_b128 v[190:193], v146 offset:49152
	ds_read_b128 v[194:197], v146 offset:50176
	ds_read_b128 v[198:201], v146 offset:51200
	ds_read_b128 v[202:205], v146 offset:52224
	ds_read_b128 v[206:209], v146 offset:53248
	ds_read_b128 v[210:213], v146 offset:54272
	ds_read_b128 v[214:217], v146 offset:55296
	ds_read_b128 v[218:221], v146 offset:56320
	global_load_lds_dwordx4 v[148:149], off
	v_lshl_add_u64 v[148:149], v[222:223], 0, s[18:19]
	s_add_i32 m0, s38, 0x2000
	s_add_i32 s38, s69, s44
	global_load_lds_dwordx4 v[148:149], off
	v_lshl_add_u64 v[148:149], v[224:225], 0, s[18:19]
	s_mov_b32 m0, s38
	s_nop 0
	global_load_lds_dwordx4 v[148:149], off
	v_lshl_add_u64 v[148:149], v[226:227], 0, s[18:19]
	s_add_i32 m0, s38, 0x2000
	s_nop 0
	global_load_lds_dwordx4 v[148:149], off
	v_lshl_add_u64 v[148:149], v[228:229], 0, s[18:19]
	s_mov_b32 m0, s50
	s_nop 0
	global_load_lds_dwordx4 v[148:149], off
	v_lshl_add_u64 v[148:149], v[230:231], 0, s[18:19]
	s_mov_b32 m0, s51
	s_nop 0
	global_load_lds_dwordx4 v[148:149], off
	s_waitcnt vmcnt(8)
	s_waitcnt lgkmcnt(0)
	s_barrier
	s_setprio 1
	s_waitcnt lgkmcnt(0)
	v_mfma_f32_16x16x32_bf16 v[60:63], v[158:161], v[190:193], v[60:63]
	v_mfma_f32_16x16x32_bf16 v[56:59], v[166:169], v[190:193], v[56:59]
	v_mfma_f32_16x16x32_bf16 v[44:47], v[158:161], v[198:201], v[44:47]
	v_mfma_f32_16x16x32_bf16 v[40:43], v[166:169], v[198:201], v[40:43]
	v_mfma_f32_16x16x32_bf16 v[28:31], v[158:161], v[206:209], v[28:31]
	v_mfma_f32_16x16x32_bf16 v[24:27], v[166:169], v[206:209], v[24:27]
	v_mfma_f32_16x16x32_bf16 v[12:15], v[158:161], v[214:217], v[12:15]
	v_mfma_f32_16x16x32_bf16 v[8:11], v[166:169], v[214:217], v[8:11]
	v_mfma_f32_16x16x32_bf16 v[60:63], v[162:165], v[194:197], v[60:63]
	v_mfma_f32_16x16x32_bf16 v[56:59], v[170:173], v[194:197], v[56:59]
	v_mfma_f32_16x16x32_bf16 v[44:47], v[162:165], v[202:205], v[44:47]
	v_mfma_f32_16x16x32_bf16 v[40:43], v[170:173], v[202:205], v[40:43]
	v_mfma_f32_16x16x32_bf16 v[28:31], v[162:165], v[210:213], v[28:31]
	v_mfma_f32_16x16x32_bf16 v[24:27], v[170:173], v[210:213], v[24:27]
	v_mfma_f32_16x16x32_bf16 v[12:15], v[162:165], v[218:221], v[12:15]
	v_mfma_f32_16x16x32_bf16 v[8:11], v[170:173], v[218:221], v[8:11]
	v_mfma_f32_16x16x32_bf16 v[52:55], v[174:177], v[190:193], v[52:55]
	v_mfma_f32_16x16x32_bf16 v[48:51], v[182:185], v[190:193], v[48:51]
	v_mfma_f32_16x16x32_bf16 v[36:39], v[174:177], v[198:201], v[36:39]
	v_mfma_f32_16x16x32_bf16 v[32:35], v[182:185], v[198:201], v[32:35]
	v_mfma_f32_16x16x32_bf16 v[20:23], v[174:177], v[206:209], v[20:23]
	v_mfma_f32_16x16x32_bf16 v[16:19], v[182:185], v[206:209], v[16:19]
	v_mfma_f32_16x16x32_bf16 v[4:7], v[174:177], v[214:217], v[4:7]
	v_mfma_f32_16x16x32_bf16 v[0:3], v[182:185], v[214:217], v[0:3]
	v_mfma_f32_16x16x32_bf16 v[52:55], v[178:181], v[194:197], v[52:55]
	v_mfma_f32_16x16x32_bf16 v[48:51], v[186:189], v[194:197], v[48:51]
	v_mfma_f32_16x16x32_bf16 v[36:39], v[178:181], v[202:205], v[36:39]
	v_mfma_f32_16x16x32_bf16 v[32:35], v[186:189], v[202:205], v[32:35]
	v_mfma_f32_16x16x32_bf16 v[20:23], v[178:181], v[210:213], v[20:23]
	v_mfma_f32_16x16x32_bf16 v[16:19], v[186:189], v[210:213], v[16:19]
	v_mfma_f32_16x16x32_bf16 v[4:7], v[178:181], v[218:221], v[4:7]
	v_mfma_f32_16x16x32_bf16 v[0:3], v[186:189], v[218:221], v[0:3]
	s_setprio 0
	s_barrier
	s_add_u32 s36, s36, 0x100
	s_addc_u32 s37, s37, 0
	s_add_u32 s0, s0, 0x100
	s_addc_u32 s1, s1, 0
	s_cmp_ge_i32 s67, s52
	s_mov_b32 s38, s67
	s_cbranch_scc0 .LBB0_1602

; #define PG8_STAGE(bufoff, gbase, voff) do { _Pragma("unroll") for (int _i = 0; _i < 2; ++_i) \
;         __builtin_amdgcn_global_load_lds((const unsigned*)((const char*)(gbase) + (voff)[_i]), (PG8_LAS unsigned*)(lds + (bufoff) + ldsw + _i * 8192), 16, 0, 0); } while (0)
; #define PG8_LDA(dst, b, h) do { _Pragma("unroll") for (int m = 0; m < 4; ++m) _Pragma("unroll") for (int k = 0; k < 2; ++k) dst[m][k] = *(const PG8_LAS bf16x8*)(lds + PG8_SA(b, h) + aoff + m * 2048 + k * 1024); } while (0)
; #define PG8_LDB(dst, b, h) do { _Pragma("unroll") for (int n = 0; n < 2; ++n) _Pragma("unroll") for (int k = 0; k < 2; ++k) dst[n][k] = *(const PG8_LAS bf16x8*)(lds + PG8_SB(b, h) + boff + n * 2048 + k * 1024); } while (0)
; #define PG8_MMA(ai, bj, At, Bt) do { __builtin_amdgcn_s_setprio(1); _Pragma("unroll") for (int m = 0; m < 4; ++m) _Pragma("unroll") for (int n = 0; n < 2; ++n) _Pragma("unroll") for (int k = 0; k < 2; ++k) \
;         acc[ai][bj][m][n] = __builtin_amdgcn_mfma_f32_16x16x32_bf16(Bt[n][k], At[m][k], acc[ai][bj][m][n], 0, 0, 0); __builtin_amdgcn_s_setprio(0); } while (0)
; #define PG8_WAIT_V(n) asm volatile("s_waitcnt vmcnt(" #n ")" ::: "memory")
; #define PG8_WAIT_L(n) asm volatile("s_waitcnt lgkmcnt(" #n ")" ::: "memory")
; template <class Epi, class Sched, bool ALIGN_EPI = false, bool SP2 = false>
; __device__ __forceinline__ void gemm_phase(PG8_LAS unsigned char* lds, const Gemm g, const Sched& S, const Epi& E) {
;     ...
;             const bool last = (t == nt - 2);
;             const char* a1 = cA + (size_t)(t + 1) * kstep;
;             const char* a2 = last ? nA : cA + (size_t)(t + 2) * kstep; const char* b2 = last ? nB : cB + (size_t)(t + 2) * kstep;
;             const char* a3 = a2 + kstep; const char* b3 = b2 + kstep;
;             if (last && has_next) S.a_ready(nxt);
;             if constexpr (SP2) {
;             PG8_LDB(B0, 0, 0); PG8_LDB(B1, 0, 1); PG8_SCHED; PG8_LDA(At, 0, 0); PG8_STAGE(PG8_SA(1, 1), a1 + hstep, voffA);
;             PG8_WAIT_V(8); PG8_WAIT_L(0); PG8_BAR; PG8_MMA(0, 0, At, B0); PG8_MMA(0, 1, At, B1); PG8_BAR; PG8_SCHED;
;             PG8_LDA(At, 0, 1); PG8_STAGE(PG8_SB(0, 0), b2, voffB); PG8_STAGE(PG8_SB(0, 1), b2 + hstep, voffB); PG8_STAGE(PG8_SA(0, 0), a2, voffA);
;             PG8_WAIT_V(8); PG8_WAIT_L(0); PG8_BAR; PG8_MMA(1, 0, At, B0); PG8_MMA(1, 1, At, B1); PG8_BAR; PG8_SCHED;
.LBB0_1688:
	v_add_u32_e32 v1, s66, v150
	ds_read_b128 v[158:161], v1
	ds_read_b128 v[162:165], v1 offset:1024
	ds_read_b128 v[166:169], v1 offset:2048
	ds_read_b128 v[170:173], v1 offset:3072
	v_add_u32_e32 v1, s67, v150
	ds_read_b128 v[174:177], v1
	ds_read_b128 v[178:181], v1 offset:1024
	ds_read_b128 v[182:185], v1 offset:2048
	ds_read_b128 v[186:189], v1 offset:3072
	s_add_i32 s72, s44, 2
	s_add_u32 s73, s42, 0x80
	s_addc_u32 s45, s43, 0
	s_cmp_eq_u32 s65, s44
	s_cselect_b32 s44, s10, s73
	s_cselect_b32 s45, s11, s45
	s_cselect_b32 s75, s41, s1
	s_cselect_b32 s74, s40, s0
	v_lshl_add_u64 v[2:3], s[42:43], 0, v[140:141]
	s_add_i32 m0, s55, 0xc000
	ds_read_b128 v[190:193], v151
	ds_read_b128 v[194:197], v151 offset:1024
	ds_read_b128 v[198:201], v151 offset:2048
	ds_read_b128 v[202:205], v151 offset:3072
	ds_read_b128 v[206:209], v151 offset:4096
	ds_read_b128 v[210:213], v151 offset:5120
	ds_read_b128 v[214:217], v151 offset:6144
	ds_read_b128 v[218:221], v151 offset:7168
	global_load_lds_dwordx4 v[2:3], off
	v_lshl_add_u64 v[2:3], s[42:43], 0, v[142:143]
	s_add_i32 m0, s55, 0xe000
	s_nop 0
	global_load_lds_dwordx4 v[2:3], off
	s_waitcnt vmcnt(8)
	s_waitcnt lgkmcnt(0)
	s_barrier
	s_setprio 1
	s_waitcnt lgkmcnt(0)
	v_mfma_f32_16x16x32_bf16 v[44:47], v[158:161], v[190:193], v[44:47]
	v_mfma_f32_16x16x32_bf16 v[40:43], v[166:169], v[190:193], v[40:43]
	v_mfma_f32_16x16x32_bf16 v[60:63], v[158:161], v[198:201], v[60:63]
	v_mfma_f32_16x16x32_bf16 v[56:59], v[166:169], v[198:201], v[56:59]
	v_mfma_f32_16x16x32_bf16 v[68:71], v[158:161], v[206:209], v[68:71]
	v_mfma_f32_16x16x32_bf16 v[64:67], v[166:169], v[206:209], v[64:67]
	v_mfma_f32_16x16x32_bf16 v[84:87], v[158:161], v[214:217], v[84:87]
	v_mfma_f32_16x16x32_bf16 v[80:83], v[166:169], v[214:217], v[80:83]
	v_mfma_f32_16x16x32_bf16 v[44:47], v[162:165], v[194:197], v[44:47]
	v_mfma_f32_16x16x32_bf16 v[40:43], v[170:173], v[194:197], v[40:43]
	v_mfma_f32_16x16x32_bf16 v[60:63], v[162:165], v[202:205], v[60:63]
	v_mfma_f32_16x16x32_bf16 v[56:59], v[170:173], v[202:205], v[56:59]
	v_mfma_f32_16x16x32_bf16 v[68:71], v[162:165], v[210:213], v[68:71]
	v_mfma_f32_16x16x32_bf16 v[64:67], v[170:173], v[210:213], v[64:67]
	v_mfma_f32_16x16x32_bf16 v[84:87], v[162:165], v[218:221], v[84:87]
	v_mfma_f32_16x16x32_bf16 v[80:83], v[170:173], v[218:221], v[80:83]
	v_mfma_f32_16x16x32_bf16 v[2:5], v[174:177], v[190:193], v[4:7]
	v_mfma_f32_16x16x32_bf16 v[128:131], v[182:185], v[190:193], v[128:131]
	v_mfma_f32_16x16x32_bf16 v[12:15], v[174:177], v[198:201], v[12:15]
	v_mfma_f32_16x16x32_bf16 v[6:9], v[182:185], v[198:201], v[8:11]
	v_mfma_f32_16x16x32_bf16 v[20:23], v[174:177], v[206:209], v[20:23]
	v_mfma_f32_16x16x32_bf16 v[16:19], v[182:185], v[206:209], v[16:19]
	v_mfma_f32_16x16x32_bf16 v[28:31], v[174:177], v[214:217], v[28:31]
	v_mfma_f32_16x16x32_bf16 v[24:27], v[182:185], v[214:217], v[24:27]
	v_mfma_f32_16x16x32_bf16 v[2:5], v[178:181], v[194:197], v[2:5]
	v_mfma_f32_16x16x32_bf16 v[128:131], v[186:189], v[194:197], v[128:131]
	v_mfma_f32_16x16x32_bf16 v[12:15], v[178:181], v[202:205], v[12:15]
	v_mfma_f32_16x16x32_bf16 v[8:11], v[186:189], v[202:205], v[6:9]
	v_mfma_f32_16x16x32_bf16 v[20:23], v[178:181], v[210:213], v[20:23]
	v_mfma_f32_16x16x32_bf16 v[16:19], v[186:189], v[210:213], v[16:19]
	v_mfma_f32_16x16x32_bf16 v[28:31], v[178:181], v[218:221], v[28:31]
	v_mfma_f32_16x16x32_bf16 v[24:27], v[186:189], v[218:221], v[24:27]
	s_setprio 0
	s_barrier
	s_add_i32 s73, s66, s54
	v_lshl_add_u64 v[222:223], s[74:75], 0, v[134:135]
	s_mov_b32 m0, s73
	ds_read_b128 v[190:193], v151 offset:16384
	ds_read_b128 v[194:197], v151 offset:17408
	ds_read_b128 v[198:201], v151 offset:18432
	ds_read_b128 v[202:205], v151 offset:19456
	ds_read_b128 v[206:209], v151 offset:20480
	ds_read_b128 v[210:213], v151 offset:21504
	ds_read_b128 v[214:217], v151 offset:22528
	ds_read_b128 v[218:221], v151 offset:23552
	global_load_lds_dwordx4 v[222:223], off
	s_add_i32 m0, s73, 0x2000
	v_lshl_add_u64 v[224:225], s[74:75], 0, v[138:139]
	s_add_u32 s74, s74, s24
	s_addc_u32 s75, s75, s25
	s_add_i32 s73, s67, s54
	global_load_lds_dwordx4 v[224:225], off
	v_lshl_add_u64 v[226:227], s[74:75], 0, v[134:135]
	s_mov_b32 m0, s73
	v_lshl_add_u64 v[228:229], s[74:75], 0, v[138:139]
	global_load_lds_dwordx4 v[226:227], off
	s_add_i32 m0, s73, 0x2000
	v_lshl_add_u64 v[230:231], s[44:45], 0, v[132:133]
	global_load_lds_dwordx4 v[228:229], off
	s_mov_b32 m0, s55
	v_lshl_add_u64 v[232:233], s[44:45], 0, v[136:137]
	global_load_lds_dwordx4 v[230:231], off
	s_mov_b32 m0, s58
	s_nop 0
	global_load_lds_dwordx4 v[232:233], off
	s_waitcnt vmcnt(8)
	s_waitcnt lgkmcnt(0)
	s_barrier
; #define PG8_STAGE(bufoff, gbase, voff) do { _Pragma("unroll") for (int _i = 0; _i < 2; ++_i) \
;         __builtin_amdgcn_global_load_lds((const unsigned*)((const char*)(gbase) + (voff)[_i]), (PG8_LAS unsigned*)(lds + (bufoff) + ldsw + _i * 8192), 16, 0, 0); } while (0)
; #define PG8_LDA(dst, b, h) do { _Pragma("unroll") for (int m = 0; m < 4; ++m) _Pragma("unroll") for (int k = 0; k < 2; ++k) dst[m][k] = *(const PG8_LAS bf16x8*)(lds + PG8_SA(b, h) + aoff + m * 2048 + k * 1024); } while (0)
; #define PG8_LDB(dst, b, h) do { _Pragma("unroll") for (int n = 0; n < 2; ++n) _Pragma("unroll") for (int k = 0; k < 2; ++k) dst[n][k] = *(const PG8_LAS bf16x8*)(lds + PG8_SB(b, h) + boff + n * 2048 + k * 1024); } while (0)
; #define PG8_MMA(ai, bj, At, Bt) do { __builtin_amdgcn_s_setprio(1); _Pragma("unroll") for (int m = 0; m < 4; ++m) _Pragma("unroll") for (int n = 0; n < 2; ++n) _Pragma("unroll") for (int k = 0; k < 2; ++k) \
;         acc[ai][bj][m][n] = __builtin_amdgcn_mfma_f32_16x16x32_bf16(Bt[n][k], At[m][k], acc[ai][bj][m][n], 0, 0, 0); __builtin_amdgcn_s_setprio(0); } while (0)
; #define PG8_WAIT_V(n) asm volatile("s_waitcnt vmcnt(" #n ")" ::: "memory")
; #define PG8_WAIT_L(n) asm volatile("s_waitcnt lgkmcnt(" #n ")" ::: "memory")
; #define PG8_BAR __builtin_amdgcn_s_barrier()
; #define PG8_SCHED __builtin_amdgcn_sched_barrier(0)
; template <class Epi, class Sched, bool ALIGN_EPI = false, bool SP2 = false>
; __device__ __forceinline__ void gemm_phase(PG8_LAS unsigned char* lds, const Gemm g, const Sched& S, const Epi& E) {
;     ...
;             PG8_WAIT_V(8); PG8_WAIT_L(0); PG8_BAR; PG8_MMA(1, 0, At, B0); PG8_MMA(1, 1, At, B1); PG8_BAR; PG8_SCHED;
;             PG8_LDB(B0, 1, 0); PG8_LDB(B1, 1, 1); PG8_SCHED; PG8_LDA(At, 1, 0); PG8_STAGE(PG8_SA(0, 1), a2 + hstep, voffA);
;             PG8_WAIT_V(8); PG8_WAIT_L(0); PG8_BAR; PG8_MMA(0, 0, At, B0); PG8_MMA(0, 1, At, B1); PG8_BAR; PG8_SCHED;
	s_setprio 1
	s_waitcnt lgkmcnt(0)
	v_mfma_f32_16x16x32_bf16 v[96:99], v[158:161], v[190:193], v[96:99]
	v_mfma_f32_16x16x32_bf16 v[88:91], v[166:169], v[190:193], v[88:91]
	v_mfma_f32_16x16x32_bf16 v[116:119], v[158:161], v[198:201], v[116:119]
	v_mfma_f32_16x16x32_bf16 v[112:115], v[166:169], v[198:201], v[112:115]
	v_mfma_f32_16x16x32_bf16 v[124:127], v[158:161], v[206:209], v[124:127]
	v_mfma_f32_16x16x32_bf16 v[120:123], v[166:169], v[206:209], v[120:123]
	v_mfma_f32_16x16x32_bf16 v[108:111], v[158:161], v[214:217], v[108:111]
	v_mfma_f32_16x16x32_bf16 v[104:107], v[166:169], v[214:217], v[104:107]
	v_mfma_f32_16x16x32_bf16 v[96:99], v[162:165], v[194:197], v[96:99]
	v_mfma_f32_16x16x32_bf16 v[88:91], v[170:173], v[194:197], v[88:91]
	v_mfma_f32_16x16x32_bf16 v[116:119], v[162:165], v[202:205], v[116:119]
	v_mfma_f32_16x16x32_bf16 v[112:115], v[170:173], v[202:205], v[112:115]
	v_mfma_f32_16x16x32_bf16 v[124:127], v[162:165], v[210:213], v[124:127]
	v_mfma_f32_16x16x32_bf16 v[120:123], v[170:173], v[210:213], v[120:123]
	v_mfma_f32_16x16x32_bf16 v[108:111], v[162:165], v[218:221], v[108:111]
	v_mfma_f32_16x16x32_bf16 v[104:107], v[170:173], v[218:221], v[104:107]
	v_mfma_f32_16x16x32_bf16 v[36:39], v[174:177], v[190:193], v[36:39]
	v_mfma_f32_16x16x32_bf16 v[32:35], v[182:185], v[190:193], v[32:35]
	v_mfma_f32_16x16x32_bf16 v[52:55], v[174:177], v[198:201], v[52:55]
	v_mfma_f32_16x16x32_bf16 v[48:51], v[182:185], v[198:201], v[48:51]
	v_mfma_f32_16x16x32_bf16 v[76:79], v[174:177], v[206:209], v[76:79]
	v_mfma_f32_16x16x32_bf16 v[72:75], v[182:185], v[206:209], v[72:75]
	v_mfma_f32_16x16x32_bf16 v[100:103], v[174:177], v[214:217], v[100:103]
	v_mfma_f32_16x16x32_bf16 v[92:95], v[182:185], v[214:217], v[92:95]
	v_mfma_f32_16x16x32_bf16 v[36:39], v[178:181], v[194:197], v[36:39]
	v_mfma_f32_16x16x32_bf16 v[32:35], v[186:189], v[194:197], v[32:35]
	v_mfma_f32_16x16x32_bf16 v[52:55], v[178:181], v[202:205], v[52:55]
	v_mfma_f32_16x16x32_bf16 v[48:51], v[186:189], v[202:205], v[48:51]
	v_mfma_f32_16x16x32_bf16 v[76:79], v[178:181], v[210:213], v[76:79]
	v_mfma_f32_16x16x32_bf16 v[72:75], v[186:189], v[210:213], v[72:75]
	v_mfma_f32_16x16x32_bf16 v[100:103], v[178:181], v[218:221], v[100:103]
	v_mfma_f32_16x16x32_bf16 v[92:95], v[186:189], v[218:221], v[92:95]
	s_setprio 0
	s_barrier
	s_add_i32 s73, 0, 0x18000
	v_add_u32_e32 v1, s73, v150
	s_add_i32 s74, 0, 0x1c000
	ds_read_b128 v[158:161], v1
	ds_read_b128 v[162:165], v1 offset:1024
	ds_read_b128 v[166:169], v1 offset:2048
	ds_read_b128 v[170:173], v1 offset:3072
	v_add_u32_e32 v1, s74, v150
	ds_read_b128 v[174:177], v1
	ds_read_b128 v[178:181], v1 offset:1024
	ds_read_b128 v[182:185], v1 offset:2048
	ds_read_b128 v[186:189], v1 offset:3072
	s_add_u32 s44, s44, s24
	s_addc_u32 s45, s45, s25
	s_mov_b32 m0, s59
	v_lshl_add_u64 v[6:7], s[44:45], 0, v[132:133]
	ds_read_b128 v[190:193], v151 offset:32768
	ds_read_b128 v[194:197], v151 offset:33792
	ds_read_b128 v[198:201], v151 offset:34816
	ds_read_b128 v[202:205], v151 offset:35840
	ds_read_b128 v[206:209], v151 offset:36864
	ds_read_b128 v[210:213], v151 offset:37888
	ds_read_b128 v[214:217], v151 offset:38912
	ds_read_b128 v[218:221], v151 offset:39936
	global_load_lds_dwordx4 v[6:7], off
	v_lshl_add_u64 v[6:7], s[44:45], 0, v[136:137]
	s_mov_b32 m0, s60
	s_nop 0
	global_load_lds_dwordx4 v[6:7], off
	s_waitcnt vmcnt(8)
	s_waitcnt lgkmcnt(0)
	s_barrier
	s_setprio 1
	s_waitcnt lgkmcnt(0)
	v_mfma_f32_16x16x32_bf16 v[44:47], v[158:161], v[190:193], v[44:47]
	v_mfma_f32_16x16x32_bf16 v[40:43], v[166:169], v[190:193], v[40:43]
	v_mfma_f32_16x16x32_bf16 v[60:63], v[158:161], v[198:201], v[60:63]
	v_mfma_f32_16x16x32_bf16 v[56:59], v[166:169], v[198:201], v[56:59]
	v_mfma_f32_16x16x32_bf16 v[68:71], v[158:161], v[206:209], v[68:71]
	v_mfma_f32_16x16x32_bf16 v[64:67], v[166:169], v[206:209], v[64:67]
	v_mfma_f32_16x16x32_bf16 v[84:87], v[158:161], v[214:217], v[84:87]
	v_mfma_f32_16x16x32_bf16 v[80:83], v[166:169], v[214:217], v[80:83]
	v_mfma_f32_16x16x32_bf16 v[44:47], v[162:165], v[194:197], v[44:47]
	v_mfma_f32_16x16x32_bf16 v[40:43], v[170:173], v[194:197], v[40:43]
	v_mfma_f32_16x16x32_bf16 v[60:63], v[162:165], v[202:205], v[60:63]
	v_mfma_f32_16x16x32_bf16 v[56:59], v[170:173], v[202:205], v[56:59]
	v_mfma_f32_16x16x32_bf16 v[68:71], v[162:165], v[210:213], v[68:71]
	v_mfma_f32_16x16x32_bf16 v[64:67], v[170:173], v[210:213], v[64:67]
	v_mfma_f32_16x16x32_bf16 v[84:87], v[162:165], v[218:221], v[84:87]
	v_mfma_f32_16x16x32_bf16 v[80:83], v[170:173], v[218:221], v[80:83]
	v_mfma_f32_16x16x32_bf16 v[2:5], v[174:177], v[190:193], v[2:5]
	v_mfma_f32_16x16x32_bf16 v[128:131], v[182:185], v[190:193], v[128:131]
	v_mfma_f32_16x16x32_bf16 v[12:15], v[174:177], v[198:201], v[12:15]
	v_mfma_f32_16x16x32_bf16 v[8:11], v[182:185], v[198:201], v[8:11]
	v_mfma_f32_16x16x32_bf16 v[20:23], v[174:177], v[206:209], v[20:23]
	v_mfma_f32_16x16x32_bf16 v[16:19], v[182:185], v[206:209], v[16:19]
	v_mfma_f32_16x16x32_bf16 v[28:31], v[174:177], v[214:217], v[28:31]
	v_mfma_f32_16x16x32_bf16 v[24:27], v[182:185], v[214:217], v[24:27]
	v_mfma_f32_16x16x32_bf16 v[4:7], v[178:181], v[194:197], v[2:5]
	v_mfma_f32_16x16x32_bf16 v[128:131], v[186:189], v[194:197], v[128:131]
	v_mfma_f32_16x16x32_bf16 v[12:15], v[178:181], v[202:205], v[12:15]
	v_mfma_f32_16x16x32_bf16 v[8:11], v[186:189], v[202:205], v[8:11]
	v_mfma_f32_16x16x32_bf16 v[20:23], v[178:181], v[210:213], v[20:23]
	v_mfma_f32_16x16x32_bf16 v[16:19], v[186:189], v[210:213], v[16:19]
	v_mfma_f32_16x16x32_bf16 v[28:31], v[178:181], v[218:221], v[28:31]
	v_mfma_f32_16x16x32_bf16 v[24:27], v[186:189], v[218:221], v[24:27]
	s_setprio 0
	s_barrier
; #define PG8_STAGE(bufoff, gbase, voff) do { _Pragma("unroll") for (int _i = 0; _i < 2; ++_i) \
;         __builtin_amdgcn_global_load_lds((const unsigned*)((const char*)(gbase) + (voff)[_i]), (PG8_LAS unsigned*)(lds + (bufoff) + ldsw + _i * 8192), 16, 0, 0); } while (0)
; #define PG8_LDA(dst, b, h) do { _Pragma("unroll") for (int m = 0; m < 4; ++m) _Pragma("unroll") for (int k = 0; k < 2; ++k) dst[m][k] = *(const PG8_LAS bf16x8*)(lds + PG8_SA(b, h) + aoff + m * 2048 + k * 1024); } while (0)
; #define PG8_MMA(ai, bj, At, Bt) do { __builtin_amdgcn_s_setprio(1); _Pragma("unroll") for (int m = 0; m < 4; ++m) _Pragma("unroll") for (int n = 0; n < 2; ++n) _Pragma("unroll") for (int k = 0; k < 2; ++k) \
;         acc[ai][bj][m][n] = __builtin_amdgcn_mfma_f32_16x16x32_bf16(Bt[n][k], At[m][k], acc[ai][bj][m][n], 0, 0, 0); __builtin_amdgcn_s_setprio(0); } while (0)
; #define PG8_WAIT_V(n) asm volatile("s_waitcnt vmcnt(" #n ")" ::: "memory")
; #define PG8_WAIT_L(n) asm volatile("s_waitcnt lgkmcnt(" #n ")" ::: "memory")
; #define PG8_BAR __builtin_amdgcn_s_barrier()
; #define PG8_SCHED __builtin_amdgcn_sched_barrier(0)
; template <class Epi, class Sched, bool ALIGN_EPI = false, bool SP2 = false>
; __device__ __forceinline__ void gemm_phase(PG8_LAS unsigned char* lds, const Gemm g, const Sched& S, const Epi& E) {
;     ...
;         for (int t = 0; t < nt; t += 2) {
;             const bool last = (t == nt - 2);
;     ...
;             PG8_LDA(At, 1, 1); PG8_STAGE(PG8_SB(1, 0), b3, voffB); PG8_STAGE(PG8_SB(1, 1), b3 + hstep, voffB); PG8_STAGE(PG8_SA(1, 0), a3, voffA);
;             PG8_WAIT_V(8); PG8_WAIT_L(0); PG8_BAR; PG8_MMA(1, 0, At, B0); PG8_MMA(1, 1, At, B1); PG8_BAR; PG8_SCHED;
	s_add_i32 s44, s73, s54
	v_lshl_add_u64 v[2:3], v[222:223], 0, s[36:37]
	s_mov_b32 m0, s44
	ds_read_b128 v[190:193], v151 offset:49152
	ds_read_b128 v[194:197], v151 offset:50176
	ds_read_b128 v[198:201], v151 offset:51200
	ds_read_b128 v[202:205], v151 offset:52224
	ds_read_b128 v[206:209], v151 offset:53248
	ds_read_b128 v[210:213], v151 offset:54272
	ds_read_b128 v[214:217], v151 offset:55296
	ds_read_b128 v[218:221], v151 offset:56320
	global_load_lds_dwordx4 v[2:3], off
	v_lshl_add_u64 v[2:3], v[224:225], 0, s[36:37]
	s_add_i32 m0, s44, 0x2000
	s_add_i32 s44, s74, s54
	global_load_lds_dwordx4 v[2:3], off
	v_lshl_add_u64 v[2:3], v[226:227], 0, s[36:37]
	s_mov_b32 m0, s44
	s_nop 0
	global_load_lds_dwordx4 v[2:3], off
	v_lshl_add_u64 v[2:3], v[228:229], 0, s[36:37]
	s_add_i32 m0, s44, 0x2000
	s_nop 0
	global_load_lds_dwordx4 v[2:3], off
	v_lshl_add_u64 v[2:3], v[230:231], 0, s[36:37]
	s_mov_b32 m0, s61
	s_nop 0
	global_load_lds_dwordx4 v[2:3], off
	v_lshl_add_u64 v[2:3], v[232:233], 0, s[36:37]
	s_mov_b32 m0, s63
	s_nop 0
	global_load_lds_dwordx4 v[2:3], off
	s_waitcnt vmcnt(8)
	s_waitcnt lgkmcnt(0)
	s_barrier
	s_setprio 1
	s_waitcnt lgkmcnt(0)
	v_mfma_f32_16x16x32_bf16 v[96:99], v[158:161], v[190:193], v[96:99]
	v_mfma_f32_16x16x32_bf16 v[88:91], v[166:169], v[190:193], v[88:91]
	v_mfma_f32_16x16x32_bf16 v[116:119], v[158:161], v[198:201], v[116:119]
	v_mfma_f32_16x16x32_bf16 v[112:115], v[166:169], v[198:201], v[112:115]
	v_mfma_f32_16x16x32_bf16 v[124:127], v[158:161], v[206:209], v[124:127]
	v_mfma_f32_16x16x32_bf16 v[120:123], v[166:169], v[206:209], v[120:123]
	v_mfma_f32_16x16x32_bf16 v[108:111], v[158:161], v[214:217], v[108:111]
	v_mfma_f32_16x16x32_bf16 v[104:107], v[166:169], v[214:217], v[104:107]
	v_mfma_f32_16x16x32_bf16 v[96:99], v[162:165], v[194:197], v[96:99]
	v_mfma_f32_16x16x32_bf16 v[88:91], v[170:173], v[194:197], v[88:91]
	v_mfma_f32_16x16x32_bf16 v[116:119], v[162:165], v[202:205], v[116:119]
	v_mfma_f32_16x16x32_bf16 v[112:115], v[170:173], v[202:205], v[112:115]
	v_mfma_f32_16x16x32_bf16 v[124:127], v[162:165], v[210:213], v[124:127]
	v_mfma_f32_16x16x32_bf16 v[120:123], v[170:173], v[210:213], v[120:123]
	v_mfma_f32_16x16x32_bf16 v[108:111], v[162:165], v[218:221], v[108:111]
	v_mfma_f32_16x16x32_bf16 v[104:107], v[170:173], v[218:221], v[104:107]
	v_mfma_f32_16x16x32_bf16 v[36:39], v[174:177], v[190:193], v[36:39]
	v_mfma_f32_16x16x32_bf16 v[32:35], v[182:185], v[190:193], v[32:35]
	v_mfma_f32_16x16x32_bf16 v[52:55], v[174:177], v[198:201], v[52:55]
	v_mfma_f32_16x16x32_bf16 v[48:51], v[182:185], v[198:201], v[48:51]
	v_mfma_f32_16x16x32_bf16 v[76:79], v[174:177], v[206:209], v[76:79]
	v_mfma_f32_16x16x32_bf16 v[72:75], v[182:185], v[206:209], v[72:75]
	v_mfma_f32_16x16x32_bf16 v[100:103], v[174:177], v[214:217], v[100:103]
	v_mfma_f32_16x16x32_bf16 v[92:95], v[182:185], v[214:217], v[92:95]
	v_mfma_f32_16x16x32_bf16 v[36:39], v[178:181], v[194:197], v[36:39]
	v_mfma_f32_16x16x32_bf16 v[32:35], v[186:189], v[194:197], v[32:35]
	v_mfma_f32_16x16x32_bf16 v[52:55], v[178:181], v[202:205], v[52:55]
	v_mfma_f32_16x16x32_bf16 v[48:51], v[186:189], v[202:205], v[48:51]
	v_mfma_f32_16x16x32_bf16 v[76:79], v[178:181], v[210:213], v[76:79]
	v_mfma_f32_16x16x32_bf16 v[72:75], v[186:189], v[210:213], v[72:75]
	v_mfma_f32_16x16x32_bf16 v[100:103], v[178:181], v[218:221], v[100:103]
	v_mfma_f32_16x16x32_bf16 v[92:95], v[186:189], v[218:221], v[92:95]
	s_setprio 0
	s_barrier
	s_add_u32 s42, s42, 0x100
	s_addc_u32 s43, s43, 0
	s_add_u32 s0, s0, 0x100
	s_addc_u32 s1, s1, 0
	s_cmp_ge_i32 s72, s64
	s_mov_b32 s44, s72
	s_cbranch_scc0 .LBB0_1688

; #define PG8_STAGE(bufoff, gbase, voff) do { _Pragma("unroll") for (int _i = 0; _i < 2; ++_i) \
;         __builtin_amdgcn_global_load_lds((const unsigned*)((const char*)(gbase) + (voff)[_i]), (PG8_LAS unsigned*)(lds + (bufoff) + ldsw + _i * 8192), 16, 0, 0); } while (0)
; #define PG8_LDA(dst, b, h) do { _Pragma("unroll") for (int m = 0; m < 4; ++m) _Pragma("unroll") for (int k = 0; k < 2; ++k) dst[m][k] = *(const PG8_LAS bf16x8*)(lds + PG8_SA(b, h) + aoff + m * 2048 + k * 1024); } while (0)
; #define PG8_LDB(dst, b, h) do { _Pragma("unroll") for (int n = 0; n < 2; ++n) _Pragma("unroll") for (int k = 0; k < 2; ++k) dst[n][k] = *(const PG8_LAS bf16x8*)(lds + PG8_SB(b, h) + boff + n * 2048 + k * 1024); } while (0)
; #define PG8_MMA(ai, bj, At, Bt) do { __builtin_amdgcn_s_setprio(1); _Pragma("unroll") for (int m = 0; m < 4; ++m) _Pragma("unroll") for (int n = 0; n < 2; ++n) _Pragma("unroll") for (int k = 0; k < 2; ++k) \
;         acc[ai][bj][m][n] = __builtin_amdgcn_mfma_f32_16x16x32_bf16(Bt[n][k], At[m][k], acc[ai][bj][m][n], 0, 0, 0); __builtin_amdgcn_s_setprio(0); } while (0)
; #define PG8_WAIT_V(n) asm volatile("s_waitcnt vmcnt(" #n ")" ::: "memory")
; #define PG8_WAIT_L(n) asm volatile("s_waitcnt lgkmcnt(" #n ")" ::: "memory")
; template <class Epi, class Sched, bool ALIGN_EPI = false, bool SP2 = false>
; __device__ __forceinline__ void gemm_phase(PG8_LAS unsigned char* lds, const Gemm g, const Sched& S, const Epi& E) {
;     ...
;             const bool last = (t == nt - 2);
;             const char* a1 = cA + (size_t)(t + 1) * kstep;
;             const char* a2 = last ? nA : cA + (size_t)(t + 2) * kstep; const char* b2 = last ? nB : cB + (size_t)(t + 2) * kstep;
;             const char* a3 = a2 + kstep; const char* b3 = b2 + kstep;
;             if (last && has_next) S.a_ready(nxt);
;             if constexpr (SP2) {
;             PG8_LDB(B0, 0, 0); PG8_LDB(B1, 0, 1); PG8_SCHED; PG8_LDA(At, 0, 0); PG8_STAGE(PG8_SA(1, 1), a1 + hstep, voffA);
;             PG8_WAIT_V(8); PG8_WAIT_L(0); PG8_BAR; PG8_MMA(0, 0, At, B0); PG8_MMA(0, 1, At, B1); PG8_BAR; PG8_SCHED;
;             PG8_LDA(At, 0, 1); PG8_STAGE(PG8_SB(0, 0), b2, voffB); PG8_STAGE(PG8_SB(0, 1), b2 + hstep, voffB); PG8_STAGE(PG8_SA(0, 0), a2, voffA);
;             PG8_WAIT_V(8); PG8_WAIT_L(0); PG8_BAR; PG8_MMA(1, 0, At, B0); PG8_MMA(1, 1, At, B1); PG8_BAR; PG8_SCHED;
.LBB0_1871:
	v_add_u32_e32 v1, s70, v150
	ds_read_b128 v[158:161], v1
	ds_read_b128 v[162:165], v1 offset:1024
	ds_read_b128 v[166:169], v1 offset:2048
	ds_read_b128 v[170:173], v1 offset:3072
	v_add_u32_e32 v1, s71, v150
	ds_read_b128 v[174:177], v1
	ds_read_b128 v[178:181], v1 offset:1024
	ds_read_b128 v[182:185], v1 offset:2048
	ds_read_b128 v[186:189], v1 offset:3072
	s_add_i32 s76, s48, 2
	s_add_u32 s77, s46, 0x80
	s_addc_u32 s49, s47, 0
	s_cmp_eq_u32 s69, s48
	s_cselect_b32 s48, s10, s77
	s_cselect_b32 s49, s11, s49
	s_cselect_b32 s81, s45, s1
	s_cselect_b32 s80, s44, s0
	v_lshl_add_u64 v[2:3], s[46:47], 0, v[140:141]
	s_add_i32 m0, s61, 0xc000
	ds_read_b128 v[190:193], v151
	ds_read_b128 v[194:197], v151 offset:1024
	ds_read_b128 v[198:201], v151 offset:2048
	ds_read_b128 v[202:205], v151 offset:3072
	ds_read_b128 v[206:209], v151 offset:4096
	ds_read_b128 v[210:213], v151 offset:5120
	ds_read_b128 v[214:217], v151 offset:6144
	ds_read_b128 v[218:221], v151 offset:7168
	global_load_lds_dwordx4 v[2:3], off
	v_lshl_add_u64 v[2:3], s[46:47], 0, v[142:143]
	s_add_i32 m0, s61, 0xe000
	s_nop 0
	global_load_lds_dwordx4 v[2:3], off
	s_waitcnt vmcnt(8)
	s_waitcnt lgkmcnt(0)
	s_barrier
	s_setprio 1
	s_waitcnt lgkmcnt(0)
	v_mfma_f32_16x16x32_bf16 v[20:23], v[158:161], v[190:193], v[20:23]
	v_mfma_f32_16x16x32_bf16 v[16:19], v[166:169], v[190:193], v[16:19]
	v_mfma_f32_16x16x32_bf16 v[32:35], v[158:161], v[198:201], v[32:35]
	v_mfma_f32_16x16x32_bf16 v[36:39], v[166:169], v[198:201], v[36:39]
	v_mfma_f32_16x16x32_bf16 v[60:63], v[158:161], v[206:209], v[60:63]
	v_mfma_f32_16x16x32_bf16 v[52:55], v[166:169], v[206:209], v[52:55]
	v_mfma_f32_16x16x32_bf16 v[80:83], v[158:161], v[214:217], v[80:83]
	v_mfma_f32_16x16x32_bf16 v[84:87], v[166:169], v[214:217], v[84:87]
	v_mfma_f32_16x16x32_bf16 v[20:23], v[162:165], v[194:197], v[20:23]
	v_mfma_f32_16x16x32_bf16 v[16:19], v[170:173], v[194:197], v[16:19]
	v_mfma_f32_16x16x32_bf16 v[32:35], v[162:165], v[202:205], v[32:35]
	v_mfma_f32_16x16x32_bf16 v[36:39], v[170:173], v[202:205], v[36:39]
	v_mfma_f32_16x16x32_bf16 v[60:63], v[162:165], v[210:213], v[60:63]
	v_mfma_f32_16x16x32_bf16 v[52:55], v[170:173], v[210:213], v[52:55]
	v_mfma_f32_16x16x32_bf16 v[80:83], v[162:165], v[218:221], v[80:83]
	v_mfma_f32_16x16x32_bf16 v[84:87], v[170:173], v[218:221], v[84:87]
	v_mfma_f32_16x16x32_bf16 v[128:131], v[174:177], v[190:193], v[128:131]
	v_mfma_f32_16x16x32_bf16 v[2:5], v[182:185], v[190:193], v[4:7]
	v_mfma_f32_16x16x32_bf16 v[6:9], v[174:177], v[198:201], v[8:11]
	v_mfma_f32_16x16x32_bf16 v[12:15], v[182:185], v[198:201], v[12:15]
	v_mfma_f32_16x16x32_bf16 v[24:27], v[174:177], v[206:209], v[24:27]
	v_mfma_f32_16x16x32_bf16 v[28:31], v[182:185], v[206:209], v[28:31]
	v_mfma_f32_16x16x32_bf16 v[40:43], v[174:177], v[214:217], v[40:43]
	v_mfma_f32_16x16x32_bf16 v[44:47], v[182:185], v[214:217], v[44:47]
	v_mfma_f32_16x16x32_bf16 v[128:131], v[178:181], v[194:197], v[128:131]
	v_mfma_f32_16x16x32_bf16 v[2:5], v[186:189], v[194:197], v[2:5]
	v_mfma_f32_16x16x32_bf16 v[8:11], v[178:181], v[202:205], v[6:9]
	v_mfma_f32_16x16x32_bf16 v[12:15], v[186:189], v[202:205], v[12:15]
	v_mfma_f32_16x16x32_bf16 v[24:27], v[178:181], v[210:213], v[24:27]
	v_mfma_f32_16x16x32_bf16 v[28:31], v[186:189], v[210:213], v[28:31]
	v_mfma_f32_16x16x32_bf16 v[40:43], v[178:181], v[218:221], v[40:43]
	v_mfma_f32_16x16x32_bf16 v[44:47], v[186:189], v[218:221], v[44:47]
	s_setprio 0
	s_barrier
	s_add_i32 s77, s70, s60
	v_lshl_add_u64 v[222:223], s[80:81], 0, v[134:135]
	s_mov_b32 m0, s77
	ds_read_b128 v[190:193], v151 offset:16384
	ds_read_b128 v[194:197], v151 offset:17408
	ds_read_b128 v[198:201], v151 offset:18432
	ds_read_b128 v[202:205], v151 offset:19456
	ds_read_b128 v[206:209], v151 offset:20480
	ds_read_b128 v[210:213], v151 offset:21504
	ds_read_b128 v[214:217], v151 offset:22528
	ds_read_b128 v[218:221], v151 offset:23552
	global_load_lds_dwordx4 v[222:223], off
	s_add_i32 m0, s77, 0x2000
	v_lshl_add_u64 v[224:225], s[80:81], 0, v[138:139]
	s_add_u32 s80, s80, s26
	s_addc_u32 s81, s81, s27
	s_add_i32 s77, s71, s60
	global_load_lds_dwordx4 v[224:225], off
	v_lshl_add_u64 v[226:227], s[80:81], 0, v[134:135]
	s_mov_b32 m0, s77
	v_lshl_add_u64 v[228:229], s[80:81], 0, v[138:139]
	global_load_lds_dwordx4 v[226:227], off
	s_add_i32 m0, s77, 0x2000
	v_lshl_add_u64 v[230:231], s[48:49], 0, v[132:133]
	global_load_lds_dwordx4 v[228:229], off
	s_mov_b32 m0, s61
	v_lshl_add_u64 v[232:233], s[48:49], 0, v[136:137]
	global_load_lds_dwordx4 v[230:231], off
	s_mov_b32 m0, s62
	s_nop 0
	global_load_lds_dwordx4 v[232:233], off
	s_waitcnt vmcnt(8)
	s_waitcnt lgkmcnt(0)
	s_barrier
; #define PG8_STAGE(bufoff, gbase, voff) do { _Pragma("unroll") for (int _i = 0; _i < 2; ++_i) \
;         __builtin_amdgcn_global_load_lds((const unsigned*)((const char*)(gbase) + (voff)[_i]), (PG8_LAS unsigned*)(lds + (bufoff) + ldsw + _i * 8192), 16, 0, 0); } while (0)
; #define PG8_LDA(dst, b, h) do { _Pragma("unroll") for (int m = 0; m < 4; ++m) _Pragma("unroll") for (int k = 0; k < 2; ++k) dst[m][k] = *(const PG8_LAS bf16x8*)(lds + PG8_SA(b, h) + aoff + m * 2048 + k * 1024); } while (0)
; #define PG8_LDB(dst, b, h) do { _Pragma("unroll") for (int n = 0; n < 2; ++n) _Pragma("unroll") for (int k = 0; k < 2; ++k) dst[n][k] = *(const PG8_LAS bf16x8*)(lds + PG8_SB(b, h) + boff + n * 2048 + k * 1024); } while (0)
; #define PG8_MMA(ai, bj, At, Bt) do { __builtin_amdgcn_s_setprio(1); _Pragma("unroll") for (int m = 0; m < 4; ++m) _Pragma("unroll") for (int n = 0; n < 2; ++n) _Pragma("unroll") for (int k = 0; k < 2; ++k) \
;         acc[ai][bj][m][n] = __builtin_amdgcn_mfma_f32_16x16x32_bf16(Bt[n][k], At[m][k], acc[ai][bj][m][n], 0, 0, 0); __builtin_amdgcn_s_setprio(0); } while (0)
; #define PG8_WAIT_V(n) asm volatile("s_waitcnt vmcnt(" #n ")" ::: "memory")
; #define PG8_WAIT_L(n) asm volatile("s_waitcnt lgkmcnt(" #n ")" ::: "memory")
; #define PG8_BAR __builtin_amdgcn_s_barrier()
; #define PG8_SCHED __builtin_amdgcn_sched_barrier(0)
; template <class Epi, class Sched, bool ALIGN_EPI = false, bool SP2 = false>
; __device__ __forceinline__ void gemm_phase(PG8_LAS unsigned char* lds, const Gemm g, const Sched& S, const Epi& E) {
;     ...
;             PG8_WAIT_V(8); PG8_WAIT_L(0); PG8_BAR; PG8_MMA(1, 0, At, B0); PG8_MMA(1, 1, At, B1); PG8_BAR; PG8_SCHED;
;             PG8_LDB(B0, 1, 0); PG8_LDB(B1, 1, 1); PG8_SCHED; PG8_LDA(At, 1, 0); PG8_STAGE(PG8_SA(0, 1), a2 + hstep, voffA);
;             PG8_WAIT_V(8); PG8_WAIT_L(0); PG8_BAR; PG8_MMA(0, 0, At, B0); PG8_MMA(0, 1, At, B1); PG8_BAR; PG8_SCHED;
	s_setprio 1
	s_waitcnt lgkmcnt(0)
	v_mfma_f32_16x16x32_bf16 v[112:115], v[158:161], v[190:193], v[112:115]
	v_mfma_f32_16x16x32_bf16 v[116:119], v[166:169], v[190:193], v[116:119]
	v_mfma_f32_16x16x32_bf16 v[124:127], v[158:161], v[198:201], v[124:127]
	v_mfma_f32_16x16x32_bf16 v[120:123], v[166:169], v[198:201], v[120:123]
	v_mfma_f32_16x16x32_bf16 v[108:111], v[158:161], v[206:209], v[108:111]
	v_mfma_f32_16x16x32_bf16 v[100:103], v[166:169], v[206:209], v[100:103]
	v_mfma_f32_16x16x32_bf16 v[68:71], v[158:161], v[214:217], v[68:71]
	v_mfma_f32_16x16x32_bf16 v[64:67], v[166:169], v[214:217], v[64:67]
	v_mfma_f32_16x16x32_bf16 v[112:115], v[162:165], v[194:197], v[112:115]
	v_mfma_f32_16x16x32_bf16 v[116:119], v[170:173], v[194:197], v[116:119]
	v_mfma_f32_16x16x32_bf16 v[124:127], v[162:165], v[202:205], v[124:127]
	v_mfma_f32_16x16x32_bf16 v[120:123], v[170:173], v[202:205], v[120:123]
	v_mfma_f32_16x16x32_bf16 v[108:111], v[162:165], v[210:213], v[108:111]
	v_mfma_f32_16x16x32_bf16 v[100:103], v[170:173], v[210:213], v[100:103]
	v_mfma_f32_16x16x32_bf16 v[68:71], v[162:165], v[218:221], v[68:71]
	v_mfma_f32_16x16x32_bf16 v[64:67], v[170:173], v[218:221], v[64:67]
	v_mfma_f32_16x16x32_bf16 v[72:75], v[174:177], v[190:193], v[72:75]
	v_mfma_f32_16x16x32_bf16 v[76:79], v[182:185], v[190:193], v[76:79]
	v_mfma_f32_16x16x32_bf16 v[96:99], v[174:177], v[198:201], v[96:99]
	v_mfma_f32_16x16x32_bf16 v[104:107], v[182:185], v[198:201], v[104:107]
	v_mfma_f32_16x16x32_bf16 v[92:95], v[174:177], v[206:209], v[92:95]
	v_mfma_f32_16x16x32_bf16 v[88:91], v[182:185], v[206:209], v[88:91]
	v_mfma_f32_16x16x32_bf16 v[56:59], v[174:177], v[214:217], v[56:59]
	v_mfma_f32_16x16x32_bf16 v[48:51], v[182:185], v[214:217], v[48:51]
	v_mfma_f32_16x16x32_bf16 v[72:75], v[178:181], v[194:197], v[72:75]
	v_mfma_f32_16x16x32_bf16 v[76:79], v[186:189], v[194:197], v[76:79]
	v_mfma_f32_16x16x32_bf16 v[96:99], v[178:181], v[202:205], v[96:99]
	v_mfma_f32_16x16x32_bf16 v[104:107], v[186:189], v[202:205], v[104:107]
	v_mfma_f32_16x16x32_bf16 v[92:95], v[178:181], v[210:213], v[92:95]
	v_mfma_f32_16x16x32_bf16 v[88:91], v[186:189], v[210:213], v[88:91]
	v_mfma_f32_16x16x32_bf16 v[56:59], v[178:181], v[218:221], v[56:59]
	v_mfma_f32_16x16x32_bf16 v[48:51], v[186:189], v[218:221], v[48:51]
	s_setprio 0
	s_barrier
	s_add_i32 s77, 0, 0x18000
	v_add_u32_e32 v1, s77, v150
	s_add_i32 s79, 0, 0x1c000
	ds_read_b128 v[158:161], v1
	ds_read_b128 v[162:165], v1 offset:1024
	ds_read_b128 v[166:169], v1 offset:2048
	ds_read_b128 v[170:173], v1 offset:3072
	v_add_u32_e32 v1, s79, v150
	ds_read_b128 v[174:177], v1
	ds_read_b128 v[178:181], v1 offset:1024
	ds_read_b128 v[182:185], v1 offset:2048
	ds_read_b128 v[186:189], v1 offset:3072
	s_add_u32 s48, s48, s26
	s_addc_u32 s49, s49, s27
	s_mov_b32 m0, s63
	v_lshl_add_u64 v[6:7], s[48:49], 0, v[132:133]
	ds_read_b128 v[190:193], v151 offset:32768
	ds_read_b128 v[194:197], v151 offset:33792
	ds_read_b128 v[198:201], v151 offset:34816
	ds_read_b128 v[202:205], v151 offset:35840
	ds_read_b128 v[206:209], v151 offset:36864
	ds_read_b128 v[210:213], v151 offset:37888
	ds_read_b128 v[214:217], v151 offset:38912
	ds_read_b128 v[218:221], v151 offset:39936
	global_load_lds_dwordx4 v[6:7], off
	v_lshl_add_u64 v[6:7], s[48:49], 0, v[136:137]
	s_mov_b32 m0, s64
	s_nop 0
	global_load_lds_dwordx4 v[6:7], off
	s_waitcnt vmcnt(8)
	s_waitcnt lgkmcnt(0)
	s_barrier
	s_setprio 1
	s_waitcnt lgkmcnt(0)
	v_mfma_f32_16x16x32_bf16 v[20:23], v[158:161], v[190:193], v[20:23]
	v_mfma_f32_16x16x32_bf16 v[16:19], v[166:169], v[190:193], v[16:19]
	v_mfma_f32_16x16x32_bf16 v[32:35], v[158:161], v[198:201], v[32:35]
	v_mfma_f32_16x16x32_bf16 v[36:39], v[166:169], v[198:201], v[36:39]
	v_mfma_f32_16x16x32_bf16 v[60:63], v[158:161], v[206:209], v[60:63]
	v_mfma_f32_16x16x32_bf16 v[52:55], v[166:169], v[206:209], v[52:55]
	v_mfma_f32_16x16x32_bf16 v[80:83], v[158:161], v[214:217], v[80:83]
	v_mfma_f32_16x16x32_bf16 v[84:87], v[166:169], v[214:217], v[84:87]
	v_mfma_f32_16x16x32_bf16 v[20:23], v[162:165], v[194:197], v[20:23]
	v_mfma_f32_16x16x32_bf16 v[16:19], v[170:173], v[194:197], v[16:19]
	v_mfma_f32_16x16x32_bf16 v[32:35], v[162:165], v[202:205], v[32:35]
	v_mfma_f32_16x16x32_bf16 v[36:39], v[170:173], v[202:205], v[36:39]
	v_mfma_f32_16x16x32_bf16 v[60:63], v[162:165], v[210:213], v[60:63]
	v_mfma_f32_16x16x32_bf16 v[52:55], v[170:173], v[210:213], v[52:55]
	v_mfma_f32_16x16x32_bf16 v[80:83], v[162:165], v[218:221], v[80:83]
	v_mfma_f32_16x16x32_bf16 v[84:87], v[170:173], v[218:221], v[84:87]
	v_mfma_f32_16x16x32_bf16 v[128:131], v[174:177], v[190:193], v[128:131]
	v_mfma_f32_16x16x32_bf16 v[2:5], v[182:185], v[190:193], v[2:5]
	v_mfma_f32_16x16x32_bf16 v[8:11], v[174:177], v[198:201], v[8:11]
	v_mfma_f32_16x16x32_bf16 v[12:15], v[182:185], v[198:201], v[12:15]
	v_mfma_f32_16x16x32_bf16 v[24:27], v[174:177], v[206:209], v[24:27]
	v_mfma_f32_16x16x32_bf16 v[28:31], v[182:185], v[206:209], v[28:31]
	v_mfma_f32_16x16x32_bf16 v[40:43], v[174:177], v[214:217], v[40:43]
	v_mfma_f32_16x16x32_bf16 v[44:47], v[182:185], v[214:217], v[44:47]
	v_mfma_f32_16x16x32_bf16 v[128:131], v[178:181], v[194:197], v[128:131]
	v_mfma_f32_16x16x32_bf16 v[4:7], v[186:189], v[194:197], v[2:5]
	v_mfma_f32_16x16x32_bf16 v[8:11], v[178:181], v[202:205], v[8:11]
	v_mfma_f32_16x16x32_bf16 v[12:15], v[186:189], v[202:205], v[12:15]
	v_mfma_f32_16x16x32_bf16 v[24:27], v[178:181], v[210:213], v[24:27]
	v_mfma_f32_16x16x32_bf16 v[28:31], v[186:189], v[210:213], v[28:31]
	v_mfma_f32_16x16x32_bf16 v[40:43], v[178:181], v[218:221], v[40:43]
	v_mfma_f32_16x16x32_bf16 v[44:47], v[186:189], v[218:221], v[44:47]
	s_setprio 0
	s_barrier
; #define PG8_STAGE(bufoff, gbase, voff) do { _Pragma("unroll") for (int _i = 0; _i < 2; ++_i) \
;         __builtin_amdgcn_global_load_lds((const unsigned*)((const char*)(gbase) + (voff)[_i]), (PG8_LAS unsigned*)(lds + (bufoff) + ldsw + _i * 8192), 16, 0, 0); } while (0)
; #define PG8_LDA(dst, b, h) do { _Pragma("unroll") for (int m = 0; m < 4; ++m) _Pragma("unroll") for (int k = 0; k < 2; ++k) dst[m][k] = *(const PG8_LAS bf16x8*)(lds + PG8_SA(b, h) + aoff + m * 2048 + k * 1024); } while (0)
; #define PG8_MMA(ai, bj, At, Bt) do { __builtin_amdgcn_s_setprio(1); _Pragma("unroll") for (int m = 0; m < 4; ++m) _Pragma("unroll") for (int n = 0; n < 2; ++n) _Pragma("unroll") for (int k = 0; k < 2; ++k) \
;         acc[ai][bj][m][n] = __builtin_amdgcn_mfma_f32_16x16x32_bf16(Bt[n][k], At[m][k], acc[ai][bj][m][n], 0, 0, 0); __builtin_amdgcn_s_setprio(0); } while (0)
; #define PG8_WAIT_V(n) asm volatile("s_waitcnt vmcnt(" #n ")" ::: "memory")
; #define PG8_WAIT_L(n) asm volatile("s_waitcnt lgkmcnt(" #n ")" ::: "memory")
; #define PG8_BAR __builtin_amdgcn_s_barrier()
; #define PG8_SCHED __builtin_amdgcn_sched_barrier(0)
; template <class Epi, class Sched, bool ALIGN_EPI = false, bool SP2 = false>
; __device__ __forceinline__ void gemm_phase(PG8_LAS unsigned char* lds, const Gemm g, const Sched& S, const Epi& E) {
;     ...
;         for (int t = 0; t < nt; t += 2) {
;             const bool last = (t == nt - 2);
;     ...
;             PG8_LDA(At, 1, 1); PG8_STAGE(PG8_SB(1, 0), b3, voffB); PG8_STAGE(PG8_SB(1, 1), b3 + hstep, voffB); PG8_STAGE(PG8_SA(1, 0), a3, voffA);
;             PG8_WAIT_V(8); PG8_WAIT_L(0); PG8_BAR; PG8_MMA(1, 0, At, B0); PG8_MMA(1, 1, At, B1); PG8_BAR; PG8_SCHED;
	s_add_i32 s48, s77, s60
	v_lshl_add_u64 v[2:3], v[222:223], 0, s[40:41]
	s_mov_b32 m0, s48
	ds_read_b128 v[190:193], v151 offset:49152
	ds_read_b128 v[194:197], v151 offset:50176
	ds_read_b128 v[198:201], v151 offset:51200
	ds_read_b128 v[202:205], v151 offset:52224
	ds_read_b128 v[206:209], v151 offset:53248
	ds_read_b128 v[210:213], v151 offset:54272
	ds_read_b128 v[214:217], v151 offset:55296
	ds_read_b128 v[218:221], v151 offset:56320
	global_load_lds_dwordx4 v[2:3], off
	v_lshl_add_u64 v[2:3], v[224:225], 0, s[40:41]
	s_add_i32 m0, s48, 0x2000
	s_add_i32 s48, s79, s60
	global_load_lds_dwordx4 v[2:3], off
	v_lshl_add_u64 v[2:3], v[226:227], 0, s[40:41]
	s_mov_b32 m0, s48
	s_nop 0
	global_load_lds_dwordx4 v[2:3], off
	v_lshl_add_u64 v[2:3], v[228:229], 0, s[40:41]
	s_add_i32 m0, s48, 0x2000
	s_nop 0
	global_load_lds_dwordx4 v[2:3], off
	v_lshl_add_u64 v[2:3], v[230:231], 0, s[40:41]
	s_mov_b32 m0, s66
	s_nop 0
	global_load_lds_dwordx4 v[2:3], off
	v_lshl_add_u64 v[2:3], v[232:233], 0, s[40:41]
	s_mov_b32 m0, s67
	s_nop 0
	global_load_lds_dwordx4 v[2:3], off
	s_waitcnt vmcnt(8)
	s_waitcnt lgkmcnt(0)
	s_barrier
	s_setprio 1
	s_waitcnt lgkmcnt(0)
	v_mfma_f32_16x16x32_bf16 v[112:115], v[158:161], v[190:193], v[112:115]
	v_mfma_f32_16x16x32_bf16 v[116:119], v[166:169], v[190:193], v[116:119]
	v_mfma_f32_16x16x32_bf16 v[124:127], v[158:161], v[198:201], v[124:127]
	v_mfma_f32_16x16x32_bf16 v[120:123], v[166:169], v[198:201], v[120:123]
	v_mfma_f32_16x16x32_bf16 v[108:111], v[158:161], v[206:209], v[108:111]
	v_mfma_f32_16x16x32_bf16 v[100:103], v[166:169], v[206:209], v[100:103]
	v_mfma_f32_16x16x32_bf16 v[68:71], v[158:161], v[214:217], v[68:71]
	v_mfma_f32_16x16x32_bf16 v[64:67], v[166:169], v[214:217], v[64:67]
	v_mfma_f32_16x16x32_bf16 v[112:115], v[162:165], v[194:197], v[112:115]
	v_mfma_f32_16x16x32_bf16 v[116:119], v[170:173], v[194:197], v[116:119]
	v_mfma_f32_16x16x32_bf16 v[124:127], v[162:165], v[202:205], v[124:127]
	v_mfma_f32_16x16x32_bf16 v[120:123], v[170:173], v[202:205], v[120:123]
	v_mfma_f32_16x16x32_bf16 v[108:111], v[162:165], v[210:213], v[108:111]
	v_mfma_f32_16x16x32_bf16 v[100:103], v[170:173], v[210:213], v[100:103]
	v_mfma_f32_16x16x32_bf16 v[68:71], v[162:165], v[218:221], v[68:71]
	v_mfma_f32_16x16x32_bf16 v[64:67], v[170:173], v[218:221], v[64:67]
	v_mfma_f32_16x16x32_bf16 v[72:75], v[174:177], v[190:193], v[72:75]
	v_mfma_f32_16x16x32_bf16 v[76:79], v[182:185], v[190:193], v[76:79]
	v_mfma_f32_16x16x32_bf16 v[96:99], v[174:177], v[198:201], v[96:99]
	v_mfma_f32_16x16x32_bf16 v[104:107], v[182:185], v[198:201], v[104:107]
	v_mfma_f32_16x16x32_bf16 v[92:95], v[174:177], v[206:209], v[92:95]
	v_mfma_f32_16x16x32_bf16 v[88:91], v[182:185], v[206:209], v[88:91]
	v_mfma_f32_16x16x32_bf16 v[56:59], v[174:177], v[214:217], v[56:59]
	v_mfma_f32_16x16x32_bf16 v[48:51], v[182:185], v[214:217], v[48:51]
	v_mfma_f32_16x16x32_bf16 v[72:75], v[178:181], v[194:197], v[72:75]
	v_mfma_f32_16x16x32_bf16 v[76:79], v[186:189], v[194:197], v[76:79]
	v_mfma_f32_16x16x32_bf16 v[96:99], v[178:181], v[202:205], v[96:99]
	v_mfma_f32_16x16x32_bf16 v[104:107], v[186:189], v[202:205], v[104:107]
	v_mfma_f32_16x16x32_bf16 v[92:95], v[178:181], v[210:213], v[92:95]
	v_mfma_f32_16x16x32_bf16 v[88:91], v[186:189], v[210:213], v[88:91]
	v_mfma_f32_16x16x32_bf16 v[56:59], v[178:181], v[218:221], v[56:59]
	v_mfma_f32_16x16x32_bf16 v[48:51], v[186:189], v[218:221], v[48:51]
	s_setprio 0
	s_barrier
	s_add_u32 s46, s46, 0x100
	s_addc_u32 s47, s47, 0
	s_add_u32 s0, s0, 0x100
	s_addc_u32 s1, s1, 0
	s_cmp_ge_i32 s76, s68
	s_mov_b32 s48, s76
	s_cbranch_scc0 .LBB0_1871
